# baseline (speedup 1.0000x reference)
.Llate_p1_done:
.LBB0_89:
	ds_read_b128 v[128:131], v222
	ds_read_b128 v[132:135], v222 offset:2048
	ds_read_b128 v[136:139], v223
	ds_read_b128 v[140:143], v223 offset:2048
	s_mov_b32 m0, s74
	ds_read_b128 v[144:147], v224
	ds_read_b128 v[148:151], v224 offset:2048
	ds_read_b128 v[152:155], v225
	ds_read_b128 v[156:159], v225 offset:2048
	ds_read_b128 v[160:163], v224 offset:4096
	ds_read_b128 v[164:167], v224 offset:6144
	ds_read_b128 v[168:171], v225 offset:4096
	ds_read_b128 v[172:175], v225 offset:6144
	s_add_u32 s82, s38, 0x80080
	s_addc_u32 s83, s39, 0x0
	s_nop 0
	global_load_lds_dwordx4 v212, s[82:83]
	s_mov_b32 m0, s75
	s_nop 0
	s_add_u32 s82, s38, 0xc0080
	s_addc_u32 s83, s39, 0x0
	s_nop 0
	global_load_lds_dwordx4 v212, s[82:83]
	s_waitcnt lgkmcnt(8)
	s_barrier
	s_waitcnt lgkmcnt(0)
	v_mfma_f32_16x16x32_bf16 v[124:127], v[128:131], v[144:147], v[124:127]
	v_mfma_f32_16x16x32_bf16 v[120:123], v[132:135], v[144:147], v[120:123]
	v_mfma_f32_16x16x32_bf16 v[116:119], v[128:131], v[148:151], v[116:119]
	v_mfma_f32_16x16x32_bf16 v[112:115], v[132:135], v[148:151], v[112:115]
	v_mfma_f32_16x16x32_bf16 v[108:111], v[128:131], v[160:163], v[108:111]
	v_mfma_f32_16x16x32_bf16 v[104:107], v[132:135], v[160:163], v[104:107]
	v_mfma_f32_16x16x32_bf16 v[100:103], v[128:131], v[164:167], v[100:103]
	v_mfma_f32_16x16x32_bf16 v[96:99], v[132:135], v[164:167], v[96:99]
	v_mfma_f32_16x16x32_bf16 v[124:127], v[136:139], v[152:155], v[124:127]
	v_mfma_f32_16x16x32_bf16 v[120:123], v[140:143], v[152:155], v[120:123]
	v_mfma_f32_16x16x32_bf16 v[116:119], v[136:139], v[156:159], v[116:119]
	v_mfma_f32_16x16x32_bf16 v[112:115], v[140:143], v[156:159], v[112:115]
	v_mfma_f32_16x16x32_bf16 v[108:111], v[136:139], v[168:171], v[108:111]
	v_mfma_f32_16x16x32_bf16 v[104:107], v[140:143], v[168:171], v[104:107]
	v_mfma_f32_16x16x32_bf16 v[100:103], v[136:139], v[172:175], v[100:103]
	v_mfma_f32_16x16x32_bf16 v[96:99], v[140:143], v[172:175], v[96:99]
	s_barrier
	s_mov_b32 m0, s30
	ds_read_b128 v[176:179], v226
	ds_read_b128 v[180:183], v226 offset:2048
	ds_read_b128 v[184:187], v227
	ds_read_b128 v[188:191], v227 offset:2048
	s_add_u32 s82, s40, s24
	s_addc_u32 s83, s41, s25
	s_nop 0
	global_load_lds_dwordx4 v212, s[82:83]
	s_mov_b32 m0, s31
	s_nop 0
	s_add_u32 s82, s40, s26
	s_addc_u32 s83, s41, s27
	s_nop 0
	global_load_lds_dwordx4 v212, s[82:83]
	s_waitcnt lgkmcnt(0)
	s_barrier
	v_mfma_f32_16x16x32_bf16 v[92:95], v[176:179], v[144:147], v[92:95]
	v_mfma_f32_16x16x32_bf16 v[88:91], v[180:183], v[144:147], v[88:91]
	v_mfma_f32_16x16x32_bf16 v[84:87], v[176:179], v[148:151], v[84:87]
	v_mfma_f32_16x16x32_bf16 v[80:83], v[180:183], v[148:151], v[80:83]
	v_mfma_f32_16x16x32_bf16 v[76:79], v[176:179], v[160:163], v[76:79]
	v_mfma_f32_16x16x32_bf16 v[72:75], v[180:183], v[160:163], v[72:75]
	v_mfma_f32_16x16x32_bf16 v[68:71], v[176:179], v[164:167], v[68:71]
	v_mfma_f32_16x16x32_bf16 v[56:59], v[180:183], v[164:167], v[56:59]
	v_mfma_f32_16x16x32_bf16 v[92:95], v[184:187], v[152:155], v[92:95]
	v_mfma_f32_16x16x32_bf16 v[88:91], v[188:191], v[152:155], v[88:91]
	v_mfma_f32_16x16x32_bf16 v[84:87], v[184:187], v[156:159], v[84:87]
	v_mfma_f32_16x16x32_bf16 v[80:83], v[188:191], v[156:159], v[80:83]
	v_mfma_f32_16x16x32_bf16 v[76:79], v[184:187], v[168:171], v[76:79]
	v_mfma_f32_16x16x32_bf16 v[72:75], v[188:191], v[168:171], v[72:75]
	v_mfma_f32_16x16x32_bf16 v[68:71], v[184:187], v[172:175], v[68:71]
	v_mfma_f32_16x16x32_bf16 v[56:59], v[188:191], v[172:175], v[56:59]
	s_barrier
	s_mov_b32 m0, s22
	ds_read_b128 v[144:147], v224 offset:16384
	ds_read_b128 v[148:151], v224 offset:18432
	ds_read_b128 v[152:155], v225 offset:16384
	ds_read_b128 v[156:159], v225 offset:18432
	ds_read_b128 v[160:163], v224 offset:20480
	ds_read_b128 v[164:167], v224 offset:22528
	ds_read_b128 v[168:171], v225 offset:20480
	ds_read_b128 v[172:175], v225 offset:22528
	s_add_u32 s82, s38, s24
	s_addc_u32 s83, s39, s25
	s_nop 0
	global_load_lds_dwordx4 v212, s[82:83]
	s_mov_b32 m0, s33
	s_nop 0
	s_add_u32 s82, s38, s26
	s_addc_u32 s83, s39, s27
	s_nop 0
	global_load_lds_dwordx4 v212, s[82:83]
	s_barrier
	s_waitcnt lgkmcnt(0)
	v_mfma_f32_16x16x32_bf16 v[28:31], v[128:131], v[144:147], v[28:31]
	v_mfma_f32_16x16x32_bf16 v[24:27], v[132:135], v[144:147], v[24:27]
	v_mfma_f32_16x16x32_bf16 v[20:23], v[128:131], v[148:151], v[20:23]
	v_mfma_f32_16x16x32_bf16 v[16:19], v[132:135], v[148:151], v[16:19]
	v_mfma_f32_16x16x32_bf16 v[12:15], v[128:131], v[160:163], v[12:15]
	v_mfma_f32_16x16x32_bf16 v[8:11], v[132:135], v[160:163], v[8:11]
	v_mfma_f32_16x16x32_bf16 v[4:7], v[128:131], v[164:167], v[4:7]
	v_mfma_f32_16x16x32_bf16 v[0:3], v[132:135], v[164:167], v[0:3]
	v_mfma_f32_16x16x32_bf16 v[28:31], v[136:139], v[152:155], v[28:31]
	v_mfma_f32_16x16x32_bf16 v[24:27], v[140:143], v[152:155], v[24:27]
	v_mfma_f32_16x16x32_bf16 v[20:23], v[136:139], v[156:159], v[20:23]
	v_mfma_f32_16x16x32_bf16 v[16:19], v[140:143], v[156:159], v[16:19]
	v_mfma_f32_16x16x32_bf16 v[12:15], v[136:139], v[168:171], v[12:15]
	v_mfma_f32_16x16x32_bf16 v[8:11], v[140:143], v[168:171], v[8:11]
	v_mfma_f32_16x16x32_bf16 v[4:7], v[136:139], v[172:175], v[4:7]
	v_mfma_f32_16x16x32_bf16 v[0:3], v[140:143], v[172:175], v[0:3]
	s_barrier
	s_mov_b32 m0, s34
	s_add_u32 s82, s4, s24
	s_addc_u32 s83, s5, s25
	s_nop 0
	global_load_lds_dwordx4 v212, s[82:83]
	s_mov_b32 m0, s35
	s_nop 0
	s_add_u32 s82, s4, s26
	s_addc_u32 s83, s5, s27
	s_nop 0
	global_load_lds_dwordx4 v212, s[82:83]
	s_waitcnt vmcnt(6)
	s_barrier
	v_mfma_f32_16x16x32_bf16 v[32:35], v[176:179], v[144:147], v[32:35]
	v_mfma_f32_16x16x32_bf16 v[36:39], v[180:183], v[144:147], v[36:39]
	v_mfma_f32_16x16x32_bf16 v[40:43], v[176:179], v[148:151], v[40:43]
	v_mfma_f32_16x16x32_bf16 v[44:47], v[180:183], v[148:151], v[44:47]
	v_mfma_f32_16x16x32_bf16 v[48:51], v[176:179], v[160:163], v[48:51]
	v_mfma_f32_16x16x32_bf16 v[52:55], v[180:183], v[160:163], v[52:55]
	v_mfma_f32_16x16x32_bf16 v[60:63], v[176:179], v[164:167], v[60:63]
	v_mfma_f32_16x16x32_bf16 v[64:67], v[180:183], v[164:167], v[64:67]
	v_mfma_f32_16x16x32_bf16 v[32:35], v[184:187], v[152:155], v[32:35]
	v_mfma_f32_16x16x32_bf16 v[36:39], v[188:191], v[152:155], v[36:39]
	v_mfma_f32_16x16x32_bf16 v[40:43], v[184:187], v[156:159], v[40:43]
	v_mfma_f32_16x16x32_bf16 v[44:47], v[188:191], v[156:159], v[44:47]
	v_mfma_f32_16x16x32_bf16 v[48:51], v[184:187], v[168:171], v[48:51]
	v_mfma_f32_16x16x32_bf16 v[52:55], v[188:191], v[168:171], v[52:55]
	v_mfma_f32_16x16x32_bf16 v[60:63], v[184:187], v[172:175], v[60:63]
	v_mfma_f32_16x16x32_bf16 v[64:67], v[188:191], v[172:175], v[64:67]
	s_barrier
	ds_read_b128 v[128:131], v228
	ds_read_b128 v[132:135], v228 offset:2048
	ds_read_b128 v[136:139], v229
	ds_read_b128 v[140:143], v229 offset:2048
	s_mov_b32 m0, s42
	ds_read_b128 v[144:147], v224 offset:32768
	ds_read_b128 v[148:151], v224 offset:34816
	ds_read_b128 v[152:155], v225 offset:32768
	ds_read_b128 v[156:159], v225 offset:34816
	ds_read_b128 v[160:163], v224 offset:36864
	ds_read_b128 v[164:167], v224 offset:38912
	ds_read_b128 v[168:171], v225 offset:36864
	ds_read_b128 v[172:175], v225 offset:38912
	s_add_u32 s82, s38, 0x80100
	s_addc_u32 s83, s39, 0x0
	s_nop 0
	global_load_lds_dwordx4 v212, s[82:83]
	s_mov_b32 m0, s43
	s_nop 0
	s_add_u32 s82, s38, 0xc0100
	s_addc_u32 s83, s39, 0x0
	s_nop 0
	global_load_lds_dwordx4 v212, s[82:83]
	s_waitcnt lgkmcnt(8)
	s_barrier
	s_waitcnt lgkmcnt(0)
	v_mfma_f32_16x16x32_bf16 v[124:127], v[128:131], v[144:147], v[124:127]
	v_mfma_f32_16x16x32_bf16 v[120:123], v[132:135], v[144:147], v[120:123]
	v_mfma_f32_16x16x32_bf16 v[116:119], v[128:131], v[148:151], v[116:119]
	v_mfma_f32_16x16x32_bf16 v[112:115], v[132:135], v[148:151], v[112:115]
	v_mfma_f32_16x16x32_bf16 v[108:111], v[128:131], v[160:163], v[108:111]
	v_mfma_f32_16x16x32_bf16 v[104:107], v[132:135], v[160:163], v[104:107]
	v_mfma_f32_16x16x32_bf16 v[100:103], v[128:131], v[164:167], v[100:103]
	v_mfma_f32_16x16x32_bf16 v[96:99], v[132:135], v[164:167], v[96:99]
	v_mfma_f32_16x16x32_bf16 v[124:127], v[136:139], v[152:155], v[124:127]
	v_mfma_f32_16x16x32_bf16 v[120:123], v[140:143], v[152:155], v[120:123]
	v_mfma_f32_16x16x32_bf16 v[116:119], v[136:139], v[156:159], v[116:119]
	v_mfma_f32_16x16x32_bf16 v[112:115], v[140:143], v[156:159], v[112:115]
	v_mfma_f32_16x16x32_bf16 v[108:111], v[136:139], v[168:171], v[108:111]
	v_mfma_f32_16x16x32_bf16 v[104:107], v[140:143], v[168:171], v[104:107]
	v_mfma_f32_16x16x32_bf16 v[100:103], v[136:139], v[172:175], v[100:103]
	v_mfma_f32_16x16x32_bf16 v[96:99], v[140:143], v[172:175], v[96:99]
	s_barrier
	s_mov_b32 m0, s44
	ds_read_b128 v[176:179], v232
	ds_read_b128 v[180:183], v232 offset:2048
	ds_read_b128 v[184:187], v233
	ds_read_b128 v[188:191], v233 offset:2048
	s_add_u32 s82, s40, s28
	s_addc_u32 s83, s41, s29
	s_nop 0
	global_load_lds_dwordx4 v212, s[82:83]
	s_mov_b32 m0, s45
	s_nop 0
	s_add_u32 s82, s40, s36
	s_addc_u32 s83, s41, s37
	s_nop 0
	global_load_lds_dwordx4 v212, s[82:83]
	s_waitcnt lgkmcnt(0)
	s_barrier
	v_mfma_f32_16x16x32_bf16 v[92:95], v[176:179], v[144:147], v[92:95]
	v_mfma_f32_16x16x32_bf16 v[88:91], v[180:183], v[144:147], v[88:91]
	v_mfma_f32_16x16x32_bf16 v[84:87], v[176:179], v[148:151], v[84:87]
	v_mfma_f32_16x16x32_bf16 v[80:83], v[180:183], v[148:151], v[80:83]
	v_mfma_f32_16x16x32_bf16 v[76:79], v[176:179], v[160:163], v[76:79]
	v_mfma_f32_16x16x32_bf16 v[72:75], v[180:183], v[160:163], v[72:75]
	v_mfma_f32_16x16x32_bf16 v[68:71], v[176:179], v[164:167], v[68:71]
	v_mfma_f32_16x16x32_bf16 v[56:59], v[180:183], v[164:167], v[56:59]
	v_mfma_f32_16x16x32_bf16 v[92:95], v[184:187], v[152:155], v[92:95]
	v_mfma_f32_16x16x32_bf16 v[88:91], v[188:191], v[152:155], v[88:91]
	v_mfma_f32_16x16x32_bf16 v[84:87], v[184:187], v[156:159], v[84:87]
	v_mfma_f32_16x16x32_bf16 v[80:83], v[188:191], v[156:159], v[80:83]
	v_mfma_f32_16x16x32_bf16 v[76:79], v[184:187], v[168:171], v[76:79]
	v_mfma_f32_16x16x32_bf16 v[72:75], v[188:191], v[168:171], v[72:75]
	v_mfma_f32_16x16x32_bf16 v[68:71], v[184:187], v[172:175], v[68:71]
	v_mfma_f32_16x16x32_bf16 v[56:59], v[188:191], v[172:175], v[56:59]
	s_barrier
	s_mov_b32 m0, s46
	ds_read_b128 v[144:147], v224 offset:49152
	ds_read_b128 v[148:151], v224 offset:51200
	ds_read_b128 v[152:155], v225 offset:49152
	ds_read_b128 v[156:159], v225 offset:51200
	ds_read_b128 v[160:163], v224 offset:53248
	ds_read_b128 v[164:167], v224 offset:55296
	ds_read_b128 v[168:171], v225 offset:53248
	ds_read_b128 v[172:175], v225 offset:55296
	s_add_u32 s82, s38, s28
	s_addc_u32 s83, s39, s29
	s_nop 0
	global_load_lds_dwordx4 v212, s[82:83]
	s_mov_b32 m0, s47
	s_nop 0
	s_add_u32 s82, s38, s36
	s_addc_u32 s83, s39, s37
	s_nop 0
	global_load_lds_dwordx4 v212, s[82:83]
	s_barrier
; template <int K, int EPI, bool MIX = false>
; __device__ __forceinline__ void gemm_phase(const Params& p, const u16* __restrict__ A, const u16* __restrict__ Bt,
;                            const float* __restrict__ rs_in, float* __restrict__ ssq_out, float alpha, bool rev = false) {
;     ...
;       for (int t = 0; t < nt - 2; t += 2) KBODY(t);
	s_waitcnt lgkmcnt(0)
	v_mfma_f32_16x16x32_bf16 v[28:31], v[128:131], v[144:147], v[28:31]
	v_mfma_f32_16x16x32_bf16 v[24:27], v[132:135], v[144:147], v[24:27]
	v_mfma_f32_16x16x32_bf16 v[20:23], v[128:131], v[148:151], v[20:23]
	v_mfma_f32_16x16x32_bf16 v[16:19], v[132:135], v[148:151], v[16:19]
	v_mfma_f32_16x16x32_bf16 v[12:15], v[128:131], v[160:163], v[12:15]
	v_mfma_f32_16x16x32_bf16 v[8:11], v[132:135], v[160:163], v[8:11]
	v_mfma_f32_16x16x32_bf16 v[4:7], v[128:131], v[164:167], v[4:7]
	v_mfma_f32_16x16x32_bf16 v[0:3], v[132:135], v[164:167], v[0:3]
	v_mfma_f32_16x16x32_bf16 v[28:31], v[136:139], v[152:155], v[28:31]
	v_mfma_f32_16x16x32_bf16 v[24:27], v[140:143], v[152:155], v[24:27]
	v_mfma_f32_16x16x32_bf16 v[20:23], v[136:139], v[156:159], v[20:23]
	v_mfma_f32_16x16x32_bf16 v[16:19], v[140:143], v[156:159], v[16:19]
	v_mfma_f32_16x16x32_bf16 v[12:15], v[136:139], v[168:171], v[12:15]
	v_mfma_f32_16x16x32_bf16 v[8:11], v[140:143], v[168:171], v[8:11]
	v_mfma_f32_16x16x32_bf16 v[4:7], v[136:139], v[172:175], v[4:7]
	v_mfma_f32_16x16x32_bf16 v[0:3], v[140:143], v[172:175], v[0:3]
	s_barrier
	s_mov_b32 m0, s48
	s_add_u32 s82, s4, s28
	s_addc_u32 s83, s5, s29
	s_nop 0
	global_load_lds_dwordx4 v212, s[82:83]
	s_mov_b32 m0, s49
	s_nop 0
	s_add_u32 s82, s4, s36
	s_addc_u32 s83, s5, s37
	s_nop 0
	global_load_lds_dwordx4 v212, s[82:83]
	s_waitcnt vmcnt(6)
	s_barrier
	v_mfma_f32_16x16x32_bf16 v[32:35], v[176:179], v[144:147], v[32:35]
	v_mfma_f32_16x16x32_bf16 v[36:39], v[180:183], v[144:147], v[36:39]
	v_mfma_f32_16x16x32_bf16 v[40:43], v[176:179], v[148:151], v[40:43]
	v_mfma_f32_16x16x32_bf16 v[44:47], v[180:183], v[148:151], v[44:47]
	v_mfma_f32_16x16x32_bf16 v[48:51], v[176:179], v[160:163], v[48:51]
	v_mfma_f32_16x16x32_bf16 v[52:55], v[180:183], v[160:163], v[52:55]
	v_mfma_f32_16x16x32_bf16 v[60:63], v[176:179], v[164:167], v[60:63]
	v_mfma_f32_16x16x32_bf16 v[64:67], v[180:183], v[164:167], v[64:67]
	v_mfma_f32_16x16x32_bf16 v[32:35], v[184:187], v[152:155], v[32:35]
	v_mfma_f32_16x16x32_bf16 v[36:39], v[188:191], v[152:155], v[36:39]
	v_mfma_f32_16x16x32_bf16 v[40:43], v[184:187], v[156:159], v[40:43]
	v_mfma_f32_16x16x32_bf16 v[44:47], v[188:191], v[156:159], v[44:47]
	v_mfma_f32_16x16x32_bf16 v[48:51], v[184:187], v[168:171], v[48:51]
	v_mfma_f32_16x16x32_bf16 v[52:55], v[188:191], v[168:171], v[52:55]
	v_mfma_f32_16x16x32_bf16 v[60:63], v[184:187], v[172:175], v[60:63]
	v_mfma_f32_16x16x32_bf16 v[64:67], v[188:191], v[172:175], v[64:67]
	s_barrier
	s_add_i32 s81, s81, 2
	s_add_u32 s40, s40, 0x100
	s_addc_u32 s41, s41, 0
	s_add_u32 s38, s38, 0x100
	s_addc_u32 s39, s39, 0
	s_add_u32 s4, s4, 0x100
	s_addc_u32 s5, s5, 0
	s_cmp_lt_u32 s81, 28
	s_cbranch_scc1 .LBB0_89
; #define LDA(dst,b,h) _Pragma("unroll") for(int m=0;m<4;++m) _Pragma("unroll") for(int k=0;k<2;++k) \
;     dst[m][k]=*reinterpret_cast<const bf16x8*>(SA(b,h)+(wr*64+m*16)*128+koff[k])
; #define LDB(dst,b,h) _Pragma("unroll") for(int n=0;n<2;++n) _Pragma("unroll") for(int k=0;k<2;++k) \
;     dst[n][k]=*reinterpret_cast<const bf16x8*>(SB(b,h)+(wc*32+n*16)*128+koff[k])
; #define MMA(ai,bj,Af,Bf) do{__builtin_amdgcn_s_setprio(1); \
;     _Pragma("unroll") for(int m=0;m<4;++m) _Pragma("unroll") for(int n=0;n<2;++n) _Pragma("unroll") for(int k=0;k<2;++k) \
;       acc[ai][bj][m][n]=__builtin_amdgcn_mfma_f32_16x16x32_bf16(Bf[n][k],Af[m][k],acc[ai][bj][m][n],0,0,0); \
;     __builtin_amdgcn_s_setprio(0);}while(0)
; #define WAIT_V(n) asm volatile("s_waitcnt vmcnt(" #n ")":::"memory")
; #define WAIT_L(n) asm volatile("s_waitcnt lgkmcnt(" #n ")":::"memory")
; #define BAR __builtin_amdgcn_s_barrier()
; template <int K, int EPI, bool MIX = false>
; __device__ __forceinline__ void gemm_phase(const Params& p, const u16* __restrict__ A, const u16* __restrict__ Bt,
;                            const float* __restrict__ rs_in, float* __restrict__ ssq_out, float alpha, bool rev = false) {
;     ...
;     if constexpr (EPI == EPI_SWIGLU || EPI == EPI_Z || MIX) {
;       const float* rsrc = MIX ? p.ssqb : rs_in;
;       int fr_p = fr;
;       asm volatile("" : "+v"(fr_p));
; #pragma unroll
;       for (int ai = 0; ai < 2; ++ai)
; #pragma unroll
;         for (int m = 0; m < 4; ++m) rsq[ai][m] = rsrc[cpm * 256 + ai * 128 + wr * 64 + m * 16 + fr_p];
;     }
;     ++it;
;     id = item_id(it);
;     const bool more = id < ntiles;
;     if (rev) id = ntiles - 1 - id;
;     {
;       LDB(B0,0,0); SCHED; LDA(At,0,0); STAGE_A(1,1,nt-1);
;       WAIT_L(8); BAR; WAIT_L(0); MMA(0,0,At,B0); BAR; SCHED;
;       if (more) SETUP_TILE();
;       LDB(B1,0,1); if (more) STAGE_B(0,0,0);
;       BAR; WAIT_L(0); MMA(0,1,At,B1); BAR;
;       LDA(At,0,1); if (more) STAGE_A(0,0,0);
;       BAR; WAIT_L(0); MMA(1,0,At,B0); BAR; SCHED;
;       if (more) { STAGE_B(0,1,0); WAIT_V(6); } else { WAIT_V(0); }
;       BAR; MMA(1,1,At,B1); BAR;
;       LDB(B0,1,0); SCHED; LDA(At,1,0); if (more) STAGE_A(0,1,0);
;       WAIT_L(8); BAR; WAIT_L(0); MMA(0,0,At,B0); BAR; SCHED;
;       LDB(B1,1,1); if (more) STAGE_B(1,0,1);
;       BAR; WAIT_L(0); MMA(0,1,At,B1); BAR;
;       LDA(At,1,1); if (more) STAGE_A(1,0,1);
	v_mov_b32_e32 v128, v221
	s_lshl_b32 s41, s23, 8
	s_add_i32 s41, s41, s50
	v_add_u32_e32 v128, s41, v128
	v_readlane_b32 s52, v254, 32
	v_ashrrev_i32_e32 v129, 31, v128
	v_readlane_b32 s62, v254, 42
	v_readlane_b32 s63, v254, 43
	s_add_i32 s79, s79, 1
	s_mul_i32 s4, s79, s76
	v_lshl_add_u64 v[128:129], v[128:129], 2, s[62:63]
	global_load_dword v210, v[128:129], off
	global_load_dword v241, v[128:129], off offset:64
	global_load_dword v240, v[128:129], off offset:128
	global_load_dword v239, v[128:129], off offset:192
	global_load_dword v238, v[128:129], off offset:512
	global_load_dword v237, v[128:129], off offset:576
	global_load_dword v236, v[128:129], off offset:640
	global_load_dword v235, v[128:129], off offset:704
	ds_read_b128 v[144:147], v222
	ds_read_b128 v[148:151], v222 offset:2048
	ds_read_b128 v[156:159], v223
	ds_read_b128 v[152:155], v223 offset:2048
	s_add_i32 s4, s4, s77
	v_readlane_b32 s53, v254, 33
	v_readlane_b32 s54, v254, 34
	v_readlane_b32 s55, v254, 35
	v_readlane_b32 s56, v254, 36
	v_readlane_b32 s57, v254, 37
	v_readlane_b32 s58, v254, 38
	v_readlane_b32 s59, v254, 39
	v_readlane_b32 s60, v254, 40
	v_readlane_b32 s61, v254, 41
	v_readlane_b32 s64, v254, 44
	v_readlane_b32 s65, v254, 45
	v_readlane_b32 s66, v254, 46
	v_readlane_b32 s67, v254, 47
	v_lshl_add_u64 v[128:129], s[0:1], 0, v[208:209]
	s_mov_b64 s[38:39], 0x80f80
	s_mov_b32 m0, s74
	v_lshl_add_u64 v[130:131], v[128:129], 0, s[38:39]
	s_mov_b64 s[38:39], 0xc0f80
	ds_read_b128 v[160:163], v224
	ds_read_b128 v[164:167], v224 offset:2048
	ds_read_b128 v[188:191], v225
	ds_read_b128 v[180:183], v225 offset:2048
	ds_read_b128 v[168:171], v224 offset:4096
	ds_read_b128 v[172:175], v224 offset:6144
	ds_read_b128 v[184:187], v225 offset:4096
	ds_read_b128 v[176:179], v225 offset:6144
	global_load_lds_dwordx4 v[130:131], off
	v_lshl_add_u64 v[128:129], v[128:129], 0, s[38:39]
	s_mov_b32 m0, s75
	s_nop 0
	global_load_lds_dwordx4 v[128:129], off
	s_waitcnt lgkmcnt(8)
	s_barrier
	s_waitcnt lgkmcnt(0)
	v_mfma_f32_16x16x32_bf16 v[124:127], v[144:147], v[160:163], v[124:127]
	s_cmpk_lt_i32 s4, 0x2100
	s_cselect_b64 s[38:39], -1, 0
	s_cmpk_gt_i32 s4, 0x20ff
	v_mfma_f32_16x16x32_bf16 v[120:123], v[148:151], v[160:163], v[120:123]
	v_mfma_f32_16x16x32_bf16 v[116:119], v[144:147], v[164:167], v[116:119]
	v_mfma_f32_16x16x32_bf16 v[112:115], v[148:151], v[164:167], v[112:115]
	v_mfma_f32_16x16x32_bf16 v[108:111], v[144:147], v[168:171], v[108:111]
	v_mfma_f32_16x16x32_bf16 v[104:107], v[148:151], v[168:171], v[104:107]
	v_mfma_f32_16x16x32_bf16 v[100:103], v[144:147], v[172:175], v[100:103]
	v_mfma_f32_16x16x32_bf16 v[96:99], v[148:151], v[172:175], v[96:99]
	v_mfma_f32_16x16x32_bf16 v[124:127], v[156:159], v[188:191], v[124:127]
	v_mfma_f32_16x16x32_bf16 v[128:131], v[152:155], v[188:191], v[120:123]
	v_mfma_f32_16x16x32_bf16 v[116:119], v[156:159], v[180:183], v[116:119]
	v_mfma_f32_16x16x32_bf16 v[132:135], v[152:155], v[180:183], v[112:115]
	v_mfma_f32_16x16x32_bf16 v[108:111], v[156:159], v[184:187], v[108:111]
	v_mfma_f32_16x16x32_bf16 v[136:139], v[152:155], v[184:187], v[104:107]
	v_mfma_f32_16x16x32_bf16 v[100:103], v[156:159], v[176:179], v[100:103]
	v_mfma_f32_16x16x32_bf16 v[140:143], v[152:155], v[176:179], v[96:99]
	s_barrier
	s_mov_b32 s40, s80
	s_cbranch_scc1 .LBB0_92
	s_mul_hi_i32 s0, s4, 0x2e8ba2e9
	s_lshr_b32 s1, s0, 31
	s_ashr_i32 s0, s0, 6
	s_add_i32 s0, s0, s1
	s_lshl_b32 s1, s0, 3
	s_mulk_i32 s0, 0xfea0
	s_add_i32 s0, s0, s4
	s_and_b32 s4, s4, 7
	s_or_b32 s23, s1, s4
	s_ashr_i32 s40, s0, 3
	s_lshl_b32 s0, s23, 8
	s_ashr_i32 s1, s0, 31
	s_lshl_b64 s[0:1], s[0:1], 12
	s_add_u32 s0, s90, s0
	s_addc_u32 s1, s91, s1
	s_lshl_b32 s4, s40, 7
	s_ashr_i32 s5, s4, 31
	v_readlane_b32 s52, v254, 16
	s_lshl_b64 s[4:5], s[4:5], 12
	v_readlane_b32 s62, v254, 26
	v_readlane_b32 s63, v254, 27
	s_add_u32 s6, s62, s4
	s_addc_u32 s7, s63, s5
	s_add_u32 s8, s6, 0x1600000
	v_readlane_b32 s76, v255, 6
	s_addc_u32 s9, s7, 0
	v_readlane_b32 s53, v254, 17
	v_readlane_b32 s54, v254, 18
	v_readlane_b32 s55, v254, 19
	v_readlane_b32 s56, v254, 20
	v_readlane_b32 s57, v254, 21
	v_readlane_b32 s58, v254, 22
	v_readlane_b32 s59, v254, 23
	v_readlane_b32 s60, v254, 24
	v_readlane_b32 s61, v254, 25
	v_readlane_b32 s64, v254, 28
	v_readlane_b32 s65, v254, 29
	v_readlane_b32 s66, v254, 30
	v_readlane_b32 s67, v254, 31

.Llate_p2_done:
.LBB0_128:
	ds_read_b128 v[128:131], v219
	ds_read_b128 v[132:135], v219 offset:2048
	ds_read_b128 v[136:139], v220
	ds_read_b128 v[140:143], v220 offset:2048
	s_mov_b32 m0, s74
	ds_read_b128 v[144:147], v221
	ds_read_b128 v[148:151], v221 offset:2048
	ds_read_b128 v[152:155], v222
	ds_read_b128 v[156:159], v222 offset:2048
	ds_read_b128 v[160:163], v221 offset:4096
	ds_read_b128 v[164:167], v221 offset:6144
	ds_read_b128 v[168:171], v222 offset:4096
	ds_read_b128 v[172:175], v222 offset:6144
	s_add_u32 s96, s46, s18
	s_addc_u32 s97, s47, s19
	s_nop 0
	global_load_lds_dwordx4 v210, s[96:97]
	s_mov_b32 m0, s75
	s_nop 0
	s_add_u32 s96, s46, s20
	s_addc_u32 s97, s47, s21
	s_nop 0
	global_load_lds_dwordx4 v210, s[96:97]
	s_waitcnt lgkmcnt(8)
	s_barrier
	s_waitcnt lgkmcnt(0)
	v_mfma_f32_16x16x32_bf16 v[124:127], v[128:131], v[144:147], v[124:127]
	v_mfma_f32_16x16x32_bf16 v[120:123], v[132:135], v[144:147], v[120:123]
	v_mfma_f32_16x16x32_bf16 v[116:119], v[128:131], v[148:151], v[116:119]
	v_mfma_f32_16x16x32_bf16 v[112:115], v[132:135], v[148:151], v[112:115]
	v_mfma_f32_16x16x32_bf16 v[108:111], v[128:131], v[160:163], v[108:111]
	v_mfma_f32_16x16x32_bf16 v[104:107], v[132:135], v[160:163], v[104:107]
	v_mfma_f32_16x16x32_bf16 v[100:103], v[128:131], v[164:167], v[100:103]
	v_mfma_f32_16x16x32_bf16 v[96:99], v[132:135], v[164:167], v[96:99]
	v_mfma_f32_16x16x32_bf16 v[124:127], v[136:139], v[152:155], v[124:127]
	v_mfma_f32_16x16x32_bf16 v[120:123], v[140:143], v[152:155], v[120:123]
	v_mfma_f32_16x16x32_bf16 v[116:119], v[136:139], v[156:159], v[116:119]
	v_mfma_f32_16x16x32_bf16 v[112:115], v[140:143], v[156:159], v[112:115]
	v_mfma_f32_16x16x32_bf16 v[108:111], v[136:139], v[168:171], v[108:111]
	v_mfma_f32_16x16x32_bf16 v[104:107], v[140:143], v[168:171], v[104:107]
	v_mfma_f32_16x16x32_bf16 v[100:103], v[136:139], v[172:175], v[100:103]
	v_mfma_f32_16x16x32_bf16 v[96:99], v[140:143], v[172:175], v[96:99]
	s_barrier
	s_mov_b32 m0, s23
	ds_read_b128 v[176:179], v223
	ds_read_b128 v[180:183], v223 offset:2048
	ds_read_b128 v[184:187], v224
	ds_read_b128 v[188:191], v224 offset:2048
	s_add_u32 s96, s62, s28
	s_addc_u32 s97, s63, s29
	s_nop 0
	global_load_lds_dwordx4 v210, s[96:97]
	s_mov_b32 m0, s30
	s_nop 0
	s_add_u32 s96, s62, s36
	s_addc_u32 s97, s63, s37
	s_nop 0
	global_load_lds_dwordx4 v210, s[96:97]
	s_waitcnt lgkmcnt(0)
	s_barrier
	v_mfma_f32_16x16x32_bf16 v[92:95], v[176:179], v[144:147], v[92:95]
	v_mfma_f32_16x16x32_bf16 v[88:91], v[180:183], v[144:147], v[88:91]
	v_mfma_f32_16x16x32_bf16 v[84:87], v[176:179], v[148:151], v[84:87]
	v_mfma_f32_16x16x32_bf16 v[80:83], v[180:183], v[148:151], v[80:83]
	v_mfma_f32_16x16x32_bf16 v[76:79], v[176:179], v[160:163], v[76:79]
	v_mfma_f32_16x16x32_bf16 v[72:75], v[180:183], v[160:163], v[72:75]
	v_mfma_f32_16x16x32_bf16 v[68:71], v[176:179], v[164:167], v[68:71]
	v_mfma_f32_16x16x32_bf16 v[64:67], v[180:183], v[164:167], v[64:67]
	v_mfma_f32_16x16x32_bf16 v[92:95], v[184:187], v[152:155], v[92:95]
	v_mfma_f32_16x16x32_bf16 v[88:91], v[188:191], v[152:155], v[88:91]
	v_mfma_f32_16x16x32_bf16 v[84:87], v[184:187], v[156:159], v[84:87]
	v_mfma_f32_16x16x32_bf16 v[80:83], v[188:191], v[156:159], v[80:83]
	v_mfma_f32_16x16x32_bf16 v[76:79], v[184:187], v[168:171], v[76:79]
	v_mfma_f32_16x16x32_bf16 v[72:75], v[188:191], v[168:171], v[72:75]
	v_mfma_f32_16x16x32_bf16 v[68:71], v[184:187], v[172:175], v[68:71]
	v_mfma_f32_16x16x32_bf16 v[64:67], v[188:191], v[172:175], v[64:67]
	s_barrier
	s_mov_b32 m0, s22
	ds_read_b128 v[144:147], v221 offset:16384
	ds_read_b128 v[148:151], v221 offset:18432
	ds_read_b128 v[152:155], v222 offset:16384
	ds_read_b128 v[156:159], v222 offset:18432
	ds_read_b128 v[160:163], v221 offset:20480
	ds_read_b128 v[164:167], v221 offset:22528
	ds_read_b128 v[168:171], v222 offset:20480
	ds_read_b128 v[172:175], v222 offset:22528
	s_add_u32 s96, s46, s28
	s_addc_u32 s97, s47, s29
	s_nop 0
	global_load_lds_dwordx4 v210, s[96:97]
	s_mov_b32 m0, s31
	s_nop 0
	s_add_u32 s96, s46, s36
	s_addc_u32 s97, s47, s37
	s_nop 0
	global_load_lds_dwordx4 v210, s[96:97]
	s_barrier
	s_waitcnt lgkmcnt(0)
	v_mfma_f32_16x16x32_bf16 v[60:63], v[128:131], v[144:147], v[60:63]
	v_mfma_f32_16x16x32_bf16 v[56:59], v[132:135], v[144:147], v[56:59]
	v_mfma_f32_16x16x32_bf16 v[52:55], v[128:131], v[148:151], v[52:55]
	v_mfma_f32_16x16x32_bf16 v[48:51], v[132:135], v[148:151], v[48:51]
	v_mfma_f32_16x16x32_bf16 v[44:47], v[128:131], v[160:163], v[44:47]
	v_mfma_f32_16x16x32_bf16 v[40:43], v[132:135], v[160:163], v[40:43]
	v_mfma_f32_16x16x32_bf16 v[36:39], v[128:131], v[164:167], v[36:39]
	v_mfma_f32_16x16x32_bf16 v[32:35], v[132:135], v[164:167], v[32:35]
	v_mfma_f32_16x16x32_bf16 v[60:63], v[136:139], v[152:155], v[60:63]
	v_mfma_f32_16x16x32_bf16 v[56:59], v[140:143], v[152:155], v[56:59]
	v_mfma_f32_16x16x32_bf16 v[52:55], v[136:139], v[156:159], v[52:55]
	v_mfma_f32_16x16x32_bf16 v[48:51], v[140:143], v[156:159], v[48:51]
	v_mfma_f32_16x16x32_bf16 v[44:47], v[136:139], v[168:171], v[44:47]
	v_mfma_f32_16x16x32_bf16 v[40:43], v[140:143], v[168:171], v[40:43]
	v_mfma_f32_16x16x32_bf16 v[36:39], v[136:139], v[172:175], v[36:39]
	v_mfma_f32_16x16x32_bf16 v[32:35], v[140:143], v[172:175], v[32:35]
	s_barrier
	s_mov_b32 m0, s33
	s_add_u32 s96, s4, s28
	s_addc_u32 s97, s5, s29
	s_nop 0
	global_load_lds_dwordx4 v210, s[96:97]
	s_mov_b32 m0, s34
	s_nop 0
	s_add_u32 s96, s4, s36
	s_addc_u32 s97, s5, s37
	s_nop 0
	global_load_lds_dwordx4 v210, s[96:97]
	s_waitcnt vmcnt(6)
	s_barrier
	v_mfma_f32_16x16x32_bf16 v[28:31], v[176:179], v[144:147], v[28:31]
	v_mfma_f32_16x16x32_bf16 v[24:27], v[180:183], v[144:147], v[24:27]
	v_mfma_f32_16x16x32_bf16 v[20:23], v[176:179], v[148:151], v[20:23]
	v_mfma_f32_16x16x32_bf16 v[16:19], v[180:183], v[148:151], v[16:19]
	v_mfma_f32_16x16x32_bf16 v[12:15], v[176:179], v[160:163], v[12:15]
	v_mfma_f32_16x16x32_bf16 v[8:11], v[180:183], v[160:163], v[8:11]
	v_mfma_f32_16x16x32_bf16 v[4:7], v[176:179], v[164:167], v[4:7]
	v_mfma_f32_16x16x32_bf16 v[0:3], v[180:183], v[164:167], v[0:3]
	v_mfma_f32_16x16x32_bf16 v[28:31], v[184:187], v[152:155], v[28:31]
	v_mfma_f32_16x16x32_bf16 v[24:27], v[188:191], v[152:155], v[24:27]
	v_mfma_f32_16x16x32_bf16 v[20:23], v[184:187], v[156:159], v[20:23]
	v_mfma_f32_16x16x32_bf16 v[16:19], v[188:191], v[156:159], v[16:19]
	v_mfma_f32_16x16x32_bf16 v[12:15], v[184:187], v[168:171], v[12:15]
	v_mfma_f32_16x16x32_bf16 v[8:11], v[188:191], v[168:171], v[8:11]
	v_mfma_f32_16x16x32_bf16 v[4:7], v[184:187], v[172:175], v[4:7]
	v_mfma_f32_16x16x32_bf16 v[0:3], v[188:191], v[172:175], v[0:3]
	s_barrier
	ds_read_b128 v[128:131], v225
	ds_read_b128 v[132:135], v225 offset:2048
	ds_read_b128 v[136:139], v226
	ds_read_b128 v[140:143], v226 offset:2048
	s_mov_b32 m0, s35
	ds_read_b128 v[144:147], v221 offset:32768
	ds_read_b128 v[148:151], v221 offset:34816
	ds_read_b128 v[152:155], v222 offset:32768
	ds_read_b128 v[156:159], v222 offset:34816
	ds_read_b128 v[160:163], v221 offset:36864
	ds_read_b128 v[164:167], v221 offset:38912
	ds_read_b128 v[168:171], v222 offset:36864
	ds_read_b128 v[172:175], v222 offset:38912
	s_add_u32 s96, s46, 0x168000
	s_addc_u32 s97, s47, 0x0
	s_nop 0
	global_load_lds_dwordx4 v210, s[96:97]
	s_mov_b32 m0, s42
	s_nop 0
	s_add_u32 s96, s46, 0x16a000
	s_addc_u32 s97, s47, 0x0
	s_nop 0
	global_load_lds_dwordx4 v210, s[96:97]
	s_waitcnt lgkmcnt(8)
	s_barrier
	s_waitcnt lgkmcnt(0)
	v_mfma_f32_16x16x32_bf16 v[124:127], v[128:131], v[144:147], v[124:127]
	v_mfma_f32_16x16x32_bf16 v[120:123], v[132:135], v[144:147], v[120:123]
	v_mfma_f32_16x16x32_bf16 v[116:119], v[128:131], v[148:151], v[116:119]
	v_mfma_f32_16x16x32_bf16 v[112:115], v[132:135], v[148:151], v[112:115]
	v_mfma_f32_16x16x32_bf16 v[108:111], v[128:131], v[160:163], v[108:111]
	v_mfma_f32_16x16x32_bf16 v[104:107], v[132:135], v[160:163], v[104:107]
	v_mfma_f32_16x16x32_bf16 v[100:103], v[128:131], v[164:167], v[100:103]
	v_mfma_f32_16x16x32_bf16 v[96:99], v[132:135], v[164:167], v[96:99]
	v_mfma_f32_16x16x32_bf16 v[124:127], v[136:139], v[152:155], v[124:127]
	v_mfma_f32_16x16x32_bf16 v[120:123], v[140:143], v[152:155], v[120:123]
	v_mfma_f32_16x16x32_bf16 v[116:119], v[136:139], v[156:159], v[116:119]
	v_mfma_f32_16x16x32_bf16 v[112:115], v[140:143], v[156:159], v[112:115]
	v_mfma_f32_16x16x32_bf16 v[108:111], v[136:139], v[168:171], v[108:111]
	v_mfma_f32_16x16x32_bf16 v[104:107], v[140:143], v[168:171], v[104:107]
	v_mfma_f32_16x16x32_bf16 v[100:103], v[136:139], v[172:175], v[100:103]
	v_mfma_f32_16x16x32_bf16 v[96:99], v[140:143], v[172:175], v[96:99]
	s_barrier
	s_mov_b32 m0, s43
	ds_read_b128 v[176:179], v227
	ds_read_b128 v[180:183], v227 offset:2048
	ds_read_b128 v[184:187], v228
	ds_read_b128 v[188:191], v228 offset:2048
	s_add_u32 s96, s62, s38
	s_addc_u32 s97, s63, s39
	s_nop 0
	global_load_lds_dwordx4 v210, s[96:97]
	s_mov_b32 m0, s44
	s_nop 0
	s_add_u32 s96, s62, s40
	s_addc_u32 s97, s63, s41
	s_nop 0
	global_load_lds_dwordx4 v210, s[96:97]
	s_waitcnt lgkmcnt(0)
	s_barrier
	v_mfma_f32_16x16x32_bf16 v[92:95], v[176:179], v[144:147], v[92:95]
	v_mfma_f32_16x16x32_bf16 v[88:91], v[180:183], v[144:147], v[88:91]
	v_mfma_f32_16x16x32_bf16 v[84:87], v[176:179], v[148:151], v[84:87]
	v_mfma_f32_16x16x32_bf16 v[80:83], v[180:183], v[148:151], v[80:83]
	v_mfma_f32_16x16x32_bf16 v[76:79], v[176:179], v[160:163], v[76:79]
	v_mfma_f32_16x16x32_bf16 v[72:75], v[180:183], v[160:163], v[72:75]
	v_mfma_f32_16x16x32_bf16 v[68:71], v[176:179], v[164:167], v[68:71]
	v_mfma_f32_16x16x32_bf16 v[64:67], v[180:183], v[164:167], v[64:67]
	v_mfma_f32_16x16x32_bf16 v[92:95], v[184:187], v[152:155], v[92:95]
	v_mfma_f32_16x16x32_bf16 v[88:91], v[188:191], v[152:155], v[88:91]
	v_mfma_f32_16x16x32_bf16 v[84:87], v[184:187], v[156:159], v[84:87]
	v_mfma_f32_16x16x32_bf16 v[80:83], v[188:191], v[156:159], v[80:83]
	v_mfma_f32_16x16x32_bf16 v[76:79], v[184:187], v[168:171], v[76:79]
	v_mfma_f32_16x16x32_bf16 v[72:75], v[188:191], v[168:171], v[72:75]
	v_mfma_f32_16x16x32_bf16 v[68:71], v[184:187], v[172:175], v[68:71]
	v_mfma_f32_16x16x32_bf16 v[64:67], v[188:191], v[172:175], v[64:67]
	s_barrier
	s_mov_b32 m0, s45
	ds_read_b128 v[144:147], v221 offset:49152
	ds_read_b128 v[148:151], v221 offset:51200
	ds_read_b128 v[152:155], v222 offset:49152
	ds_read_b128 v[156:159], v222 offset:51200
	ds_read_b128 v[160:163], v221 offset:53248
	ds_read_b128 v[164:167], v221 offset:55296
	ds_read_b128 v[168:171], v222 offset:53248
	ds_read_b128 v[172:175], v222 offset:55296
	s_add_u32 s96, s46, s38
	s_addc_u32 s97, s47, s39
	s_nop 0
	global_load_lds_dwordx4 v210, s[96:97]
	s_mov_b32 m0, s48
	s_nop 0
	s_add_u32 s96, s46, s40
	s_addc_u32 s97, s47, s41
	s_nop 0
	global_load_lds_dwordx4 v210, s[96:97]
	s_barrier
; #define LDA(dst,b,h) _Pragma("unroll") for(int m=0;m<4;++m) _Pragma("unroll") for(int k=0;k<2;++k) \
;     dst[m][k]=*reinterpret_cast<const bf16x8*>(SA(b,h)+(wr*64+m*16)*128+koff[k])
; #define LDB(dst,b,h) _Pragma("unroll") for(int n=0;n<2;++n) _Pragma("unroll") for(int k=0;k<2;++k) \
;     dst[n][k]=*reinterpret_cast<const bf16x8*>(SB(b,h)+(wc*32+n*16)*128+koff[k])
; #define MMA(ai,bj,Af,Bf) do{__builtin_amdgcn_s_setprio(1); \
;     _Pragma("unroll") for(int m=0;m<4;++m) _Pragma("unroll") for(int n=0;n<2;++n) _Pragma("unroll") for(int k=0;k<2;++k) \
;       acc[ai][bj][m][n]=__builtin_amdgcn_mfma_f32_16x16x32_bf16(Bf[n][k],Af[m][k],acc[ai][bj][m][n],0,0,0); \
;     __builtin_amdgcn_s_setprio(0);}while(0)
; #define WAIT_V(n) asm volatile("s_waitcnt vmcnt(" #n ")":::"memory")
; #define WAIT_L(n) asm volatile("s_waitcnt lgkmcnt(" #n ")":::"memory")
; #define BAR __builtin_amdgcn_s_barrier()
; #define SCHED __builtin_amdgcn_sched_barrier(0)
; template <int K, int EPI, bool MIX = false>
; __device__ __forceinline__ void gemm_phase(const Params& p, const u16* __restrict__ A, const u16* __restrict__ Bt,
;                            const float* __restrict__ rs_in, float* __restrict__ ssq_out, float alpha, bool rev = false) {
;     ...
;     ++it;
;     id = item_id(it);
;     const bool more = id < ntiles;
;     if (rev) id = ntiles - 1 - id;
;     {
;       LDB(B0,0,0); SCHED; LDA(At,0,0); STAGE_A(1,1,nt-1);
;       WAIT_L(8); BAR; WAIT_L(0); MMA(0,0,At,B0); BAR; SCHED;
;       if (more) SETUP_TILE();
;       LDB(B1,0,1); if (more) STAGE_B(0,0,0);
;       BAR; WAIT_L(0); MMA(0,1,At,B1); BAR;
;       LDA(At,0,1); if (more) STAGE_A(0,0,0);
;       BAR; WAIT_L(0); MMA(1,0,At,B0); BAR; SCHED;
;       if (more) { STAGE_B(0,1,0); WAIT_V(6); } else { WAIT_V(0); }
;       BAR; MMA(1,1,At,B1); BAR;
;       LDB(B0,1,0); SCHED; LDA(At,1,0); if (more) STAGE_A(0,1,0);
;       WAIT_L(8); BAR; WAIT_L(0); MMA(0,0,At,B0); BAR; SCHED;
;       LDB(B1,1,1); if (more) STAGE_B(1,0,1);
;       BAR; WAIT_L(0); MMA(0,1,At,B1); BAR;
;       LDA(At,1,1); if (more) STAGE_A(1,0,1);
	s_waitcnt lgkmcnt(0)
	v_mfma_f32_16x16x32_bf16 v[60:63], v[128:131], v[144:147], v[60:63]
	v_mfma_f32_16x16x32_bf16 v[56:59], v[132:135], v[144:147], v[56:59]
	v_mfma_f32_16x16x32_bf16 v[52:55], v[128:131], v[148:151], v[52:55]
	v_mfma_f32_16x16x32_bf16 v[48:51], v[132:135], v[148:151], v[48:51]
	v_mfma_f32_16x16x32_bf16 v[44:47], v[128:131], v[160:163], v[44:47]
	v_mfma_f32_16x16x32_bf16 v[40:43], v[132:135], v[160:163], v[40:43]
	v_mfma_f32_16x16x32_bf16 v[36:39], v[128:131], v[164:167], v[36:39]
	v_mfma_f32_16x16x32_bf16 v[32:35], v[132:135], v[164:167], v[32:35]
	v_mfma_f32_16x16x32_bf16 v[60:63], v[136:139], v[152:155], v[60:63]
	v_mfma_f32_16x16x32_bf16 v[56:59], v[140:143], v[152:155], v[56:59]
	v_mfma_f32_16x16x32_bf16 v[52:55], v[136:139], v[156:159], v[52:55]
	v_mfma_f32_16x16x32_bf16 v[48:51], v[140:143], v[156:159], v[48:51]
	v_mfma_f32_16x16x32_bf16 v[44:47], v[136:139], v[168:171], v[44:47]
	v_mfma_f32_16x16x32_bf16 v[40:43], v[140:143], v[168:171], v[40:43]
	v_mfma_f32_16x16x32_bf16 v[36:39], v[136:139], v[172:175], v[36:39]
	v_mfma_f32_16x16x32_bf16 v[32:35], v[140:143], v[172:175], v[32:35]
	s_barrier
	s_mov_b32 m0, s49
	s_add_u32 s96, s4, s38
	s_addc_u32 s97, s5, s39
	s_nop 0
	global_load_lds_dwordx4 v210, s[96:97]
	s_mov_b32 m0, s50
	s_nop 0
	s_add_u32 s96, s4, s40
	s_addc_u32 s97, s5, s41
	s_nop 0
	global_load_lds_dwordx4 v210, s[96:97]
	s_waitcnt vmcnt(6)
	s_barrier
	v_mfma_f32_16x16x32_bf16 v[28:31], v[176:179], v[144:147], v[28:31]
	v_mfma_f32_16x16x32_bf16 v[24:27], v[180:183], v[144:147], v[24:27]
	v_mfma_f32_16x16x32_bf16 v[20:23], v[176:179], v[148:151], v[20:23]
	v_mfma_f32_16x16x32_bf16 v[16:19], v[180:183], v[148:151], v[16:19]
	v_mfma_f32_16x16x32_bf16 v[12:15], v[176:179], v[160:163], v[12:15]
	v_mfma_f32_16x16x32_bf16 v[8:11], v[180:183], v[160:163], v[8:11]
	v_mfma_f32_16x16x32_bf16 v[4:7], v[176:179], v[164:167], v[4:7]
	v_mfma_f32_16x16x32_bf16 v[0:3], v[180:183], v[164:167], v[0:3]
	v_mfma_f32_16x16x32_bf16 v[28:31], v[184:187], v[152:155], v[28:31]
	v_mfma_f32_16x16x32_bf16 v[24:27], v[188:191], v[152:155], v[24:27]
	v_mfma_f32_16x16x32_bf16 v[20:23], v[184:187], v[156:159], v[20:23]
	v_mfma_f32_16x16x32_bf16 v[16:19], v[188:191], v[156:159], v[16:19]
	v_mfma_f32_16x16x32_bf16 v[12:15], v[184:187], v[168:171], v[12:15]
	v_mfma_f32_16x16x32_bf16 v[8:11], v[188:191], v[168:171], v[8:11]
	v_mfma_f32_16x16x32_bf16 v[4:7], v[184:187], v[172:175], v[4:7]
	v_mfma_f32_16x16x32_bf16 v[0:3], v[188:191], v[172:175], v[0:3]
	s_barrier
	s_add_i32 s79, s79, 2
	s_add_u32 s62, s62, 0x8000
	s_addc_u32 s63, s63, 0
	s_add_u32 s46, s46, 0x8000
	s_addc_u32 s47, s47, 0
	s_add_u32 s4, s4, 0x8000
	s_addc_u32 s5, s5, 0
	s_cmpk_lt_u32 s79, 0x54
	s_cbranch_scc1 .LBB0_128
	ds_read_b128 v[136:139], v219
	ds_read_b128 v[140:143], v219 offset:2048
	ds_read_b128 v[148:151], v220
	ds_read_b128 v[144:147], v220 offset:2048
	s_add_i32 s78, s78, 1
	s_mul_i32 s4, s78, s76
	s_add_i32 s4, s4, s77
	s_cmpk_lt_i32 s4, 0x600
	s_cselect_b64 s[46:47], -1, 0
	s_cmpk_gt_i32 s4, 0x5ff
	v_lshl_add_u64 v[128:129], s[2:3], 0, v[208:209]
	s_mov_b64 s[62:63], 0x2bc000
	s_mov_b32 m0, s74
	v_lshl_add_u64 v[130:131], v[128:129], 0, s[62:63]
	s_mov_b64 s[62:63], 0x2be000
	ds_read_b128 v[156:159], v221
	ds_read_b128 v[160:163], v221 offset:2048
	ds_read_b128 v[184:187], v222
	ds_read_b128 v[176:179], v222 offset:2048
	ds_read_b128 v[164:167], v221 offset:4096
	ds_read_b128 v[168:171], v221 offset:6144
	ds_read_b128 v[180:183], v222 offset:4096
	ds_read_b128 v[172:175], v222 offset:6144
	global_load_lds_dwordx4 v[130:131], off
	v_lshl_add_u64 v[128:129], v[128:129], 0, s[62:63]
	s_mov_b32 m0, s75
	s_nop 0
	global_load_lds_dwordx4 v[128:129], off
	s_waitcnt lgkmcnt(8)
	s_barrier
	s_waitcnt lgkmcnt(0)
	v_mfma_f32_16x16x32_bf16 v[124:127], v[136:139], v[156:159], v[124:127]
	v_mfma_f32_16x16x32_bf16 v[120:123], v[140:143], v[156:159], v[120:123]
	v_mfma_f32_16x16x32_bf16 v[116:119], v[136:139], v[160:163], v[116:119]
	v_mfma_f32_16x16x32_bf16 v[112:115], v[140:143], v[160:163], v[112:115]
	v_mfma_f32_16x16x32_bf16 v[108:111], v[136:139], v[164:167], v[108:111]
	v_mfma_f32_16x16x32_bf16 v[104:107], v[140:143], v[164:167], v[104:107]
	v_mfma_f32_16x16x32_bf16 v[100:103], v[136:139], v[168:171], v[100:103]
	v_mfma_f32_16x16x32_bf16 v[96:99], v[140:143], v[168:171], v[96:99]
	v_mfma_f32_16x16x32_bf16 v[124:127], v[148:151], v[184:187], v[124:127]
	v_mfma_f32_16x16x32_bf16 v[120:123], v[144:147], v[184:187], v[120:123]
	v_mfma_f32_16x16x32_bf16 v[116:119], v[148:151], v[176:179], v[116:119]
	v_mfma_f32_16x16x32_bf16 v[112:115], v[144:147], v[176:179], v[112:115]
	v_mfma_f32_16x16x32_bf16 v[128:131], v[148:151], v[180:183], v[108:111]
	v_mfma_f32_16x16x32_bf16 v[132:135], v[144:147], v[180:183], v[104:107]
	v_mfma_f32_16x16x32_bf16 v[100:103], v[148:151], v[172:175], v[100:103]
	v_mfma_f32_16x16x32_bf16 v[96:99], v[144:147], v[172:175], v[96:99]
	s_barrier
	s_mov_b32 s79, s81
	s_mov_b32 s80, s82
	s_cbranch_scc1 .LBB0_131
	s_sub_i32 s2, 0x5ff, s4
	s_lshr_b32 s3, s2, 3
	s_and_b32 s3, s3, 0x1ffffff8
	s_lshl_b32 s4, s3, 3
	s_sub_i32 s4, s2, s4
	s_and_b32 s2, s2, 7
	s_or_b32 s80, s3, s2
	s_ashr_i32 s79, s4, 3
	s_lshl_b32 s2, s80, 1
	s_mul_i32 s3, s80, 0x2c0000
	v_readlane_b32 s52, v254, 16
	s_mul_hi_u32 s4, s2, 0x160000
	s_add_u32 s2, s92, s3
	v_readlane_b32 s60, v254, 24
	v_readlane_b32 s61, v254, 25
	v_readlane_b32 s62, v254, 26
	v_readlane_b32 s63, v254, 27
	v_readlane_b32 s64, v254, 28
	v_readlane_b32 s65, v254, 29
	s_addc_u32 s3, s93, s4
	s_lshl_b32 s4, s79, 1
	s_mul_i32 s5, s79, 0x2c0000
	v_readlane_b32 s66, v254, 30
	v_readlane_b32 s67, v254, 31
	s_mov_b64 s[60:61], s[64:65]
	s_mul_hi_i32 s4, s4, 0x160000
	s_add_u32 s8, s60, s5
	s_addc_u32 s9, s61, s4
	s_add_u32 s10, s8, 0x160000
	v_readlane_b32 s76, v255, 6
	s_addc_u32 s11, s9, 0
	v_readlane_b32 s53, v254, 17
	v_readlane_b32 s54, v254, 18
	v_readlane_b32 s55, v254, 19
	v_readlane_b32 s56, v254, 20
	v_readlane_b32 s57, v254, 21
	v_readlane_b32 s58, v254, 22
	v_readlane_b32 s59, v254, 23
	s_mov_b64 s[62:63], s[66:67]

.Llate_p3_done:
.LBB0_183:
	ds_read_b128 v[128:131], v220
	s_waitcnt lgkmcnt(0)
	ds_read_b128 v[132:135], v220 offset:2048
	ds_read_b128 v[136:139], v221
	ds_read_b128 v[140:143], v221 offset:2048
	s_mov_b32 m0, s28
	ds_read_b128 v[144:147], v222
	ds_read_b128 v[148:151], v222 offset:2048
	ds_read_b128 v[152:155], v223
	ds_read_b128 v[156:159], v223 offset:2048
	ds_read_b128 v[160:163], v222 offset:4096
	ds_read_b128 v[164:167], v222 offset:6144
	ds_read_b128 v[168:171], v223 offset:4096
	ds_read_b128 v[172:175], v223 offset:6144
	s_add_u32 s10, s6, s72
	s_addc_u32 s11, s7, s73
	s_nop 0
	global_load_lds_dwordx4 v210, s[10:11]
	s_mov_b32 m0, s22
	s_nop 0
	s_add_u32 s10, s6, s70
	s_addc_u32 s11, s7, s71
	s_nop 0
	global_load_lds_dwordx4 v210, s[10:11]
	s_waitcnt lgkmcnt(8)
	s_barrier
	s_waitcnt lgkmcnt(0)
	v_mfma_f32_16x16x32_bf16 v[124:127], v[128:131], v[144:147], v[124:127]
	v_mfma_f32_16x16x32_bf16 v[120:123], v[132:135], v[144:147], v[120:123]
	v_mfma_f32_16x16x32_bf16 v[116:119], v[128:131], v[148:151], v[116:119]
	v_mfma_f32_16x16x32_bf16 v[112:115], v[132:135], v[148:151], v[112:115]
	v_mfma_f32_16x16x32_bf16 v[108:111], v[128:131], v[160:163], v[108:111]
	v_mfma_f32_16x16x32_bf16 v[104:107], v[132:135], v[160:163], v[104:107]
	v_mfma_f32_16x16x32_bf16 v[100:103], v[128:131], v[164:167], v[100:103]
	v_mfma_f32_16x16x32_bf16 v[96:99], v[132:135], v[164:167], v[96:99]
	v_mfma_f32_16x16x32_bf16 v[124:127], v[136:139], v[152:155], v[124:127]
	v_mfma_f32_16x16x32_bf16 v[120:123], v[140:143], v[152:155], v[120:123]
	v_mfma_f32_16x16x32_bf16 v[116:119], v[136:139], v[156:159], v[116:119]
	v_mfma_f32_16x16x32_bf16 v[112:115], v[140:143], v[156:159], v[112:115]
	v_mfma_f32_16x16x32_bf16 v[108:111], v[136:139], v[168:171], v[108:111]
	v_mfma_f32_16x16x32_bf16 v[104:107], v[140:143], v[168:171], v[104:107]
	v_mfma_f32_16x16x32_bf16 v[100:103], v[136:139], v[172:175], v[100:103]
	v_mfma_f32_16x16x32_bf16 v[96:99], v[140:143], v[172:175], v[96:99]
	s_barrier
	s_mov_b32 m0, s37
	ds_read_b128 v[176:179], v224
	ds_read_b128 v[180:183], v224 offset:2048
	ds_read_b128 v[184:187], v225
	ds_read_b128 v[188:191], v225 offset:2048
	s_add_u32 s10, s8, s78
	s_addc_u32 s11, s9, s79
	s_nop 0
	global_load_lds_dwordx4 v210, s[10:11]
	s_mov_b32 m0, s39
	s_nop 0
	s_add_u32 s10, s8, s80
	s_addc_u32 s11, s9, s81
	s_nop 0
	global_load_lds_dwordx4 v210, s[10:11]
	s_waitcnt lgkmcnt(0)
	s_barrier
	v_mfma_f32_16x16x32_bf16 v[56:59], v[176:179], v[144:147], v[56:59]
	v_mfma_f32_16x16x32_bf16 v[64:67], v[180:183], v[144:147], v[64:67]
	v_mfma_f32_16x16x32_bf16 v[72:75], v[176:179], v[148:151], v[72:75]
	v_mfma_f32_16x16x32_bf16 v[76:79], v[180:183], v[148:151], v[76:79]
	v_mfma_f32_16x16x32_bf16 v[80:83], v[176:179], v[160:163], v[80:83]
	v_mfma_f32_16x16x32_bf16 v[84:87], v[180:183], v[160:163], v[84:87]
	v_mfma_f32_16x16x32_bf16 v[88:91], v[176:179], v[164:167], v[88:91]
	v_mfma_f32_16x16x32_bf16 v[92:95], v[180:183], v[164:167], v[92:95]
	v_mfma_f32_16x16x32_bf16 v[56:59], v[184:187], v[152:155], v[56:59]
	v_mfma_f32_16x16x32_bf16 v[64:67], v[188:191], v[152:155], v[64:67]
	v_mfma_f32_16x16x32_bf16 v[72:75], v[184:187], v[156:159], v[72:75]
	v_mfma_f32_16x16x32_bf16 v[76:79], v[188:191], v[156:159], v[76:79]
	v_mfma_f32_16x16x32_bf16 v[80:83], v[184:187], v[168:171], v[80:83]
	v_mfma_f32_16x16x32_bf16 v[84:87], v[188:191], v[168:171], v[84:87]
	v_mfma_f32_16x16x32_bf16 v[88:91], v[184:187], v[172:175], v[88:91]
	v_mfma_f32_16x16x32_bf16 v[92:95], v[188:191], v[172:175], v[92:95]
	s_barrier
	s_mov_b32 m0, s76
	ds_read_b128 v[144:147], v222 offset:16384
	ds_read_b128 v[148:151], v222 offset:18432
	ds_read_b128 v[152:155], v223 offset:16384
	ds_read_b128 v[156:159], v223 offset:18432
	ds_read_b128 v[160:163], v222 offset:20480
	ds_read_b128 v[164:167], v222 offset:22528
	ds_read_b128 v[168:171], v223 offset:20480
	ds_read_b128 v[172:175], v223 offset:22528
	s_add_u32 s10, s6, s78
	s_addc_u32 s11, s7, s79
	s_nop 0
	global_load_lds_dwordx4 v210, s[10:11]
	s_mov_b32 m0, s77
	s_nop 0
	s_add_u32 s10, s6, s80
	s_addc_u32 s11, s7, s81
	s_nop 0
	global_load_lds_dwordx4 v210, s[10:11]
	s_barrier
	s_waitcnt lgkmcnt(0)
	v_mfma_f32_16x16x32_bf16 v[32:35], v[128:131], v[144:147], v[32:35]
	v_mfma_f32_16x16x32_bf16 v[36:39], v[132:135], v[144:147], v[36:39]
	v_mfma_f32_16x16x32_bf16 v[40:43], v[128:131], v[148:151], v[40:43]
	v_mfma_f32_16x16x32_bf16 v[44:47], v[132:135], v[148:151], v[44:47]
	v_mfma_f32_16x16x32_bf16 v[48:51], v[128:131], v[160:163], v[48:51]
	v_mfma_f32_16x16x32_bf16 v[52:55], v[132:135], v[160:163], v[52:55]
	v_mfma_f32_16x16x32_bf16 v[60:63], v[128:131], v[164:167], v[60:63]
	v_mfma_f32_16x16x32_bf16 v[68:71], v[132:135], v[164:167], v[68:71]
	v_mfma_f32_16x16x32_bf16 v[32:35], v[136:139], v[152:155], v[32:35]
	v_mfma_f32_16x16x32_bf16 v[36:39], v[140:143], v[152:155], v[36:39]
	v_mfma_f32_16x16x32_bf16 v[40:43], v[136:139], v[156:159], v[40:43]
	v_mfma_f32_16x16x32_bf16 v[44:47], v[140:143], v[156:159], v[44:47]
	v_mfma_f32_16x16x32_bf16 v[48:51], v[136:139], v[168:171], v[48:51]
	v_mfma_f32_16x16x32_bf16 v[52:55], v[140:143], v[168:171], v[52:55]
	v_mfma_f32_16x16x32_bf16 v[60:63], v[136:139], v[172:175], v[60:63]
	v_mfma_f32_16x16x32_bf16 v[68:71], v[140:143], v[172:175], v[68:71]
	s_barrier
	s_mov_b32 m0, s23
	s_add_u32 s10, s4, s78
	s_addc_u32 s11, s5, s79
	s_nop 0
	global_load_lds_dwordx4 v210, s[10:11]
	s_mov_b32 m0, s33
	s_nop 0
	s_add_u32 s10, s4, s80
	s_addc_u32 s11, s5, s81
	s_nop 0
	global_load_lds_dwordx4 v210, s[10:11]
	s_waitcnt vmcnt(6)
	s_barrier
	v_mfma_f32_16x16x32_bf16 v[0:3], v[176:179], v[144:147], v[0:3]
	v_mfma_f32_16x16x32_bf16 v[4:7], v[180:183], v[144:147], v[4:7]
	v_mfma_f32_16x16x32_bf16 v[8:11], v[176:179], v[148:151], v[8:11]
	v_mfma_f32_16x16x32_bf16 v[12:15], v[180:183], v[148:151], v[12:15]
	v_mfma_f32_16x16x32_bf16 v[16:19], v[176:179], v[160:163], v[16:19]
	v_mfma_f32_16x16x32_bf16 v[20:23], v[180:183], v[160:163], v[20:23]
	v_mfma_f32_16x16x32_bf16 v[24:27], v[176:179], v[164:167], v[24:27]
	v_mfma_f32_16x16x32_bf16 v[28:31], v[180:183], v[164:167], v[28:31]
	v_mfma_f32_16x16x32_bf16 v[0:3], v[184:187], v[152:155], v[0:3]
	v_mfma_f32_16x16x32_bf16 v[4:7], v[188:191], v[152:155], v[4:7]
	v_mfma_f32_16x16x32_bf16 v[8:11], v[184:187], v[156:159], v[8:11]
	v_mfma_f32_16x16x32_bf16 v[12:15], v[188:191], v[156:159], v[12:15]
	v_mfma_f32_16x16x32_bf16 v[16:19], v[184:187], v[168:171], v[16:19]
	v_mfma_f32_16x16x32_bf16 v[20:23], v[188:191], v[168:171], v[20:23]
	v_mfma_f32_16x16x32_bf16 v[24:27], v[184:187], v[172:175], v[24:27]
	v_mfma_f32_16x16x32_bf16 v[28:31], v[188:191], v[172:175], v[28:31]
	s_barrier
	ds_read_b128 v[128:131], v226
	ds_read_b128 v[132:135], v226 offset:2048
	ds_read_b128 v[136:139], v227
	ds_read_b128 v[140:143], v227 offset:2048
	s_mov_b32 m0, s26
	ds_read_b128 v[144:147], v222 offset:32768
	ds_read_b128 v[148:151], v222 offset:34816
	ds_read_b128 v[152:155], v223 offset:32768
	ds_read_b128 v[156:159], v223 offset:34816
	ds_read_b128 v[160:163], v222 offset:36864
	ds_read_b128 v[164:167], v222 offset:38912
	ds_read_b128 v[168:171], v223 offset:36864
	ds_read_b128 v[172:175], v223 offset:38912
	s_add_u32 s10, s6, 0x80100
	s_addc_u32 s11, s7, 0x0
	s_nop 0
	global_load_lds_dwordx4 v210, s[10:11]
	s_mov_b32 m0, s35
	s_nop 0
	s_add_u32 s10, s6, 0xc0100
	s_addc_u32 s11, s7, 0x0
	s_nop 0
	global_load_lds_dwordx4 v210, s[10:11]
	s_waitcnt lgkmcnt(8)
	s_barrier
	s_waitcnt lgkmcnt(0)
	v_mfma_f32_16x16x32_bf16 v[124:127], v[128:131], v[144:147], v[124:127]
	v_mfma_f32_16x16x32_bf16 v[120:123], v[132:135], v[144:147], v[120:123]
	v_mfma_f32_16x16x32_bf16 v[116:119], v[128:131], v[148:151], v[116:119]
	v_mfma_f32_16x16x32_bf16 v[112:115], v[132:135], v[148:151], v[112:115]
	v_mfma_f32_16x16x32_bf16 v[108:111], v[128:131], v[160:163], v[108:111]
	v_mfma_f32_16x16x32_bf16 v[104:107], v[132:135], v[160:163], v[104:107]
	v_mfma_f32_16x16x32_bf16 v[100:103], v[128:131], v[164:167], v[100:103]
	v_mfma_f32_16x16x32_bf16 v[96:99], v[132:135], v[164:167], v[96:99]
	v_mfma_f32_16x16x32_bf16 v[124:127], v[136:139], v[152:155], v[124:127]
	v_mfma_f32_16x16x32_bf16 v[120:123], v[140:143], v[152:155], v[120:123]
	v_mfma_f32_16x16x32_bf16 v[116:119], v[136:139], v[156:159], v[116:119]
	v_mfma_f32_16x16x32_bf16 v[112:115], v[140:143], v[156:159], v[112:115]
	v_mfma_f32_16x16x32_bf16 v[108:111], v[136:139], v[168:171], v[108:111]
	v_mfma_f32_16x16x32_bf16 v[104:107], v[140:143], v[168:171], v[104:107]
	v_mfma_f32_16x16x32_bf16 v[100:103], v[136:139], v[172:175], v[100:103]
	v_mfma_f32_16x16x32_bf16 v[96:99], v[140:143], v[172:175], v[96:99]
	s_barrier
	s_mov_b32 m0, s27
	ds_read_b128 v[176:179], v228
	ds_read_b128 v[180:183], v228 offset:2048
	ds_read_b128 v[184:187], v229
	ds_read_b128 v[188:191], v229 offset:2048
	s_add_u32 s10, s8, s82
	s_addc_u32 s11, s9, s83
	s_nop 0
	global_load_lds_dwordx4 v210, s[10:11]
	s_mov_b32 m0, s31
	s_nop 0
	s_add_u32 s10, s8, s96
	s_addc_u32 s11, s9, s97
	s_nop 0
	global_load_lds_dwordx4 v210, s[10:11]
	s_waitcnt lgkmcnt(0)
	s_barrier
	v_mfma_f32_16x16x32_bf16 v[56:59], v[176:179], v[144:147], v[56:59]
	v_mfma_f32_16x16x32_bf16 v[64:67], v[180:183], v[144:147], v[64:67]
	v_mfma_f32_16x16x32_bf16 v[72:75], v[176:179], v[148:151], v[72:75]
	v_mfma_f32_16x16x32_bf16 v[76:79], v[180:183], v[148:151], v[76:79]
	v_mfma_f32_16x16x32_bf16 v[80:83], v[176:179], v[160:163], v[80:83]
	v_mfma_f32_16x16x32_bf16 v[84:87], v[180:183], v[160:163], v[84:87]
	v_mfma_f32_16x16x32_bf16 v[88:91], v[176:179], v[164:167], v[88:91]
	v_mfma_f32_16x16x32_bf16 v[92:95], v[180:183], v[164:167], v[92:95]
	v_mfma_f32_16x16x32_bf16 v[56:59], v[184:187], v[152:155], v[56:59]
	v_mfma_f32_16x16x32_bf16 v[64:67], v[188:191], v[152:155], v[64:67]
	v_mfma_f32_16x16x32_bf16 v[72:75], v[184:187], v[156:159], v[72:75]
	v_mfma_f32_16x16x32_bf16 v[76:79], v[188:191], v[156:159], v[76:79]
	v_mfma_f32_16x16x32_bf16 v[80:83], v[184:187], v[168:171], v[80:83]
	v_mfma_f32_16x16x32_bf16 v[84:87], v[188:191], v[168:171], v[84:87]
	v_mfma_f32_16x16x32_bf16 v[88:91], v[184:187], v[172:175], v[88:91]
	v_mfma_f32_16x16x32_bf16 v[92:95], v[188:191], v[172:175], v[92:95]
	s_barrier
	s_mov_b32 m0, s1
	ds_read_b128 v[144:147], v222 offset:49152
	ds_read_b128 v[148:151], v222 offset:51200
	ds_read_b128 v[152:155], v223 offset:49152
	ds_read_b128 v[156:159], v223 offset:51200
	ds_read_b128 v[160:163], v222 offset:53248
	ds_read_b128 v[164:167], v222 offset:55296
	ds_read_b128 v[168:171], v223 offset:53248
	ds_read_b128 v[172:175], v223 offset:55296
	s_add_u32 s10, s6, s82
	s_addc_u32 s11, s7, s83
	s_nop 0
	global_load_lds_dwordx4 v210, s[10:11]
	s_mov_b32 m0, s34
	s_nop 0
	s_add_u32 s10, s6, s96
	s_addc_u32 s11, s7, s97
	s_nop 0
	global_load_lds_dwordx4 v210, s[10:11]
	s_barrier
; template <int K, int EPI, bool MIX = false>
; __device__ __forceinline__ void gemm_phase(const Params& p, const u16* __restrict__ A, const u16* __restrict__ Bt,
;                            const float* __restrict__ rs_in, float* __restrict__ ssq_out, float alpha, bool rev = false) {
;     ...
;       for (int t = 0; t < nt - 2; t += 2) KBODY(t);
	s_waitcnt lgkmcnt(0)
	v_mfma_f32_16x16x32_bf16 v[32:35], v[128:131], v[144:147], v[32:35]
	v_mfma_f32_16x16x32_bf16 v[36:39], v[132:135], v[144:147], v[36:39]
	v_mfma_f32_16x16x32_bf16 v[40:43], v[128:131], v[148:151], v[40:43]
	v_mfma_f32_16x16x32_bf16 v[44:47], v[132:135], v[148:151], v[44:47]
	v_mfma_f32_16x16x32_bf16 v[48:51], v[128:131], v[160:163], v[48:51]
	v_mfma_f32_16x16x32_bf16 v[52:55], v[132:135], v[160:163], v[52:55]
	v_mfma_f32_16x16x32_bf16 v[60:63], v[128:131], v[164:167], v[60:63]
	v_mfma_f32_16x16x32_bf16 v[68:71], v[132:135], v[164:167], v[68:71]
	v_mfma_f32_16x16x32_bf16 v[32:35], v[136:139], v[152:155], v[32:35]
	v_mfma_f32_16x16x32_bf16 v[36:39], v[140:143], v[152:155], v[36:39]
	v_mfma_f32_16x16x32_bf16 v[40:43], v[136:139], v[156:159], v[40:43]
	v_mfma_f32_16x16x32_bf16 v[44:47], v[140:143], v[156:159], v[44:47]
	v_mfma_f32_16x16x32_bf16 v[48:51], v[136:139], v[168:171], v[48:51]
	v_mfma_f32_16x16x32_bf16 v[52:55], v[140:143], v[168:171], v[52:55]
	v_mfma_f32_16x16x32_bf16 v[60:63], v[136:139], v[172:175], v[60:63]
	v_mfma_f32_16x16x32_bf16 v[68:71], v[140:143], v[172:175], v[68:71]
	s_barrier
	s_mov_b32 m0, s19
	s_add_u32 s10, s4, s82
	s_addc_u32 s11, s5, s83
	s_nop 0
	global_load_lds_dwordx4 v210, s[10:11]
	s_mov_b32 m0, s18
	s_nop 0
	s_add_u32 s10, s4, s96
	s_addc_u32 s11, s5, s97
	s_nop 0
	global_load_lds_dwordx4 v210, s[10:11]
	s_waitcnt vmcnt(6)
	s_barrier
	v_mfma_f32_16x16x32_bf16 v[0:3], v[176:179], v[144:147], v[0:3]
	v_mfma_f32_16x16x32_bf16 v[4:7], v[180:183], v[144:147], v[4:7]
	v_mfma_f32_16x16x32_bf16 v[8:11], v[176:179], v[148:151], v[8:11]
	v_mfma_f32_16x16x32_bf16 v[12:15], v[180:183], v[148:151], v[12:15]
	v_mfma_f32_16x16x32_bf16 v[16:19], v[176:179], v[160:163], v[16:19]
	v_mfma_f32_16x16x32_bf16 v[20:23], v[180:183], v[160:163], v[20:23]
	v_mfma_f32_16x16x32_bf16 v[24:27], v[176:179], v[164:167], v[24:27]
	v_mfma_f32_16x16x32_bf16 v[28:31], v[180:183], v[164:167], v[28:31]
	v_mfma_f32_16x16x32_bf16 v[0:3], v[184:187], v[152:155], v[0:3]
	v_mfma_f32_16x16x32_bf16 v[4:7], v[188:191], v[152:155], v[4:7]
	v_mfma_f32_16x16x32_bf16 v[8:11], v[184:187], v[156:159], v[8:11]
	v_mfma_f32_16x16x32_bf16 v[12:15], v[188:191], v[156:159], v[12:15]
	v_mfma_f32_16x16x32_bf16 v[16:19], v[184:187], v[168:171], v[16:19]
	v_mfma_f32_16x16x32_bf16 v[20:23], v[188:191], v[168:171], v[20:23]
	v_mfma_f32_16x16x32_bf16 v[24:27], v[184:187], v[172:175], v[24:27]
	v_mfma_f32_16x16x32_bf16 v[28:31], v[188:191], v[172:175], v[28:31]
	s_barrier
	s_add_i32 s2, s2, 2
	s_add_u32 s8, s8, 0x100
	s_addc_u32 s9, s9, 0
	s_add_u32 s6, s6, 0x100
	s_addc_u32 s7, s7, 0
	s_add_u32 s4, s4, 0x100
	s_addc_u32 s5, s5, 0
	s_cmp_lt_u32 s2, 28
	s_cbranch_scc1 .LBB0_183
; #define LDA(dst,b,h) _Pragma("unroll") for(int m=0;m<4;++m) _Pragma("unroll") for(int k=0;k<2;++k) \
;     dst[m][k]=*reinterpret_cast<const bf16x8*>(SA(b,h)+(wr*64+m*16)*128+koff[k])
; #define LDB(dst,b,h) _Pragma("unroll") for(int n=0;n<2;++n) _Pragma("unroll") for(int k=0;k<2;++k) \
;     dst[n][k]=*reinterpret_cast<const bf16x8*>(SB(b,h)+(wc*32+n*16)*128+koff[k])
; #define MMA(ai,bj,Af,Bf) do{__builtin_amdgcn_s_setprio(1); \
;     _Pragma("unroll") for(int m=0;m<4;++m) _Pragma("unroll") for(int n=0;n<2;++n) _Pragma("unroll") for(int k=0;k<2;++k) \
;       acc[ai][bj][m][n]=__builtin_amdgcn_mfma_f32_16x16x32_bf16(Bf[n][k],Af[m][k],acc[ai][bj][m][n],0,0,0); \
;     __builtin_amdgcn_s_setprio(0);}while(0)
; #define WAIT_V(n) asm volatile("s_waitcnt vmcnt(" #n ")":::"memory")
; #define WAIT_L(n) asm volatile("s_waitcnt lgkmcnt(" #n ")":::"memory")
; #define BAR __builtin_amdgcn_s_barrier()
; template <int K, int EPI, bool MIX = false>
; __device__ __forceinline__ void gemm_phase(const Params& p, const u16* __restrict__ A, const u16* __restrict__ Bt,
;                            const float* __restrict__ rs_in, float* __restrict__ ssq_out, float alpha, bool rev = false) {
;     ...
;     if constexpr (EPI == EPI_SWIGLU || EPI == EPI_Z || MIX) {
;       const float* rsrc = MIX ? p.ssqb : rs_in;
;       int fr_p = fr;
;       asm volatile("" : "+v"(fr_p));
; #pragma unroll
;       for (int ai = 0; ai < 2; ++ai)
; #pragma unroll
;         for (int m = 0; m < 4; ++m) rsq[ai][m] = rsrc[cpm * 256 + ai * 128 + wr * 64 + m * 16 + fr_p];
;     }
;     ++it;
;     id = item_id(it);
;     const bool more = id < ntiles;
;     if (rev) id = ntiles - 1 - id;
;     {
;       LDB(B0,0,0); SCHED; LDA(At,0,0); STAGE_A(1,1,nt-1);
;       WAIT_L(8); BAR; WAIT_L(0); MMA(0,0,At,B0); BAR; SCHED;
;       if (more) SETUP_TILE();
;       LDB(B1,0,1); if (more) STAGE_B(0,0,0);
;       BAR; WAIT_L(0); MMA(0,1,At,B1); BAR;
;       LDA(At,0,1); if (more) STAGE_A(0,0,0);
;       BAR; WAIT_L(0); MMA(1,0,At,B0); BAR; SCHED;
;       if (more) { STAGE_B(0,1,0); WAIT_V(6); } else { WAIT_V(0); }
;       BAR; MMA(1,1,At,B1); BAR;
;       LDB(B0,1,0); SCHED; LDA(At,1,0); if (more) STAGE_A(0,1,0);
;       WAIT_L(8); BAR; WAIT_L(0); MMA(0,0,At,B0); BAR; SCHED;
;       LDB(B1,1,1); if (more) STAGE_B(1,0,1);
;       BAR; WAIT_L(0); MMA(0,1,At,B1); BAR;
;       LDA(At,1,1); if (more) STAGE_A(1,0,1);
	v_mov_b32_e32 v128, v219
	s_lshl_b32 s15, s12, 8
	s_add_i32 s15, s15, s13
	v_add_u32_e32 v128, s15, v128
	v_readlane_b32 s52, v254, 32
	v_ashrrev_i32_e32 v129, 31, v128
	v_readlane_b32 s64, v254, 44
	v_readlane_b32 s65, v254, 45
	s_add_i32 s74, s74, 1
	v_readlane_b32 s2, v255, 6
	v_lshl_add_u64 v[128:129], v[128:129], 2, s[64:65]
	global_load_dword v242, v[128:129], off
	global_load_dword v241, v[128:129], off offset:64
	global_load_dword v240, v[128:129], off offset:128
	global_load_dword v239, v[128:129], off offset:192
	global_load_dword v238, v[128:129], off offset:512
	global_load_dword v237, v[128:129], off offset:576
	global_load_dword v236, v[128:129], off offset:640
	global_load_dword v235, v[128:129], off offset:704
	ds_read_b128 v[136:139], v220
	ds_read_b128 v[140:143], v220 offset:2048
	ds_read_b128 v[148:151], v221
	ds_read_b128 v[144:147], v221 offset:2048
	s_mul_i32 s2, s74, s2
	v_readlane_b32 s4, v255, 17
	s_add_i32 s2, s2, s4
	v_readlane_b32 s53, v254, 33
	v_readlane_b32 s54, v254, 34
	v_readlane_b32 s55, v254, 35
	v_readlane_b32 s56, v254, 36
	v_readlane_b32 s57, v254, 37
	v_readlane_b32 s58, v254, 38
	v_readlane_b32 s59, v254, 39
	v_readlane_b32 s60, v254, 40
	v_readlane_b32 s61, v254, 41
	v_readlane_b32 s62, v254, 42
	v_readlane_b32 s63, v254, 43
	v_readlane_b32 s66, v254, 46
	v_readlane_b32 s67, v254, 47
	v_lshl_add_u64 v[128:129], s[16:17], 0, v[208:209]
	s_mov_b64 s[4:5], 0x80f80
	s_mov_b32 m0, s28
	v_lshl_add_u64 v[130:131], v[128:129], 0, s[4:5]
	s_mov_b64 s[4:5], 0xc0f80
	ds_read_b128 v[152:155], v222
	ds_read_b128 v[156:159], v222 offset:2048
	ds_read_b128 v[180:183], v223
	ds_read_b128 v[164:167], v223 offset:2048
	ds_read_b128 v[160:163], v222 offset:4096
	ds_read_b128 v[168:171], v222 offset:6144
	ds_read_b128 v[176:179], v223 offset:4096
	ds_read_b128 v[172:175], v223 offset:6144
	global_load_lds_dwordx4 v[130:131], off
	v_lshl_add_u64 v[128:129], v[128:129], 0, s[4:5]
	s_mov_b32 m0, s22
	s_nop 0
	global_load_lds_dwordx4 v[128:129], off
	s_waitcnt lgkmcnt(8)
	s_barrier
	s_waitcnt lgkmcnt(0)
	v_mfma_f32_16x16x32_bf16 v[124:127], v[136:139], v[152:155], v[124:127]
	s_cmpk_lt_i32 s2, 0xf00
	s_cselect_b64 s[4:5], -1, 0
	s_cmpk_gt_i32 s2, 0xeff
	v_mfma_f32_16x16x32_bf16 v[120:123], v[140:143], v[152:155], v[120:123]
	v_mfma_f32_16x16x32_bf16 v[116:119], v[136:139], v[156:159], v[116:119]
	v_mfma_f32_16x16x32_bf16 v[112:115], v[140:143], v[156:159], v[112:115]
	v_mfma_f32_16x16x32_bf16 v[108:111], v[136:139], v[160:163], v[108:111]
	v_mfma_f32_16x16x32_bf16 v[104:107], v[140:143], v[160:163], v[104:107]
	v_mfma_f32_16x16x32_bf16 v[100:103], v[136:139], v[168:171], v[100:103]
	v_mfma_f32_16x16x32_bf16 v[96:99], v[140:143], v[168:171], v[96:99]
	v_mfma_f32_16x16x32_bf16 v[124:127], v[148:151], v[180:183], v[124:127]
	v_mfma_f32_16x16x32_bf16 v[120:123], v[144:147], v[180:183], v[120:123]
	v_mfma_f32_16x16x32_bf16 v[116:119], v[148:151], v[164:167], v[116:119]
	v_mfma_f32_16x16x32_bf16 v[112:115], v[144:147], v[164:167], v[112:115]
	v_mfma_f32_16x16x32_bf16 v[108:111], v[148:151], v[176:179], v[108:111]
	v_mfma_f32_16x16x32_bf16 v[104:107], v[144:147], v[176:179], v[104:107]
	v_mfma_f32_16x16x32_bf16 v[128:131], v[148:151], v[172:175], v[100:103]
	v_mfma_f32_16x16x32_bf16 v[132:135], v[144:147], v[172:175], v[96:99]
	s_barrier
	s_mov_b32 s75, s25
	s_cbranch_scc1 .LBB0_186
	s_mul_hi_i32 s6, s2, 0x66666667
	s_lshr_b32 s7, s6, 31
	s_ashr_i32 s6, s6, 6
	s_add_i32 s6, s6, s7
	s_lshl_b32 s7, s6, 3
	s_mulk_i32 s6, 0xff60
	s_add_i32 s6, s6, s2
	s_and_b32 s2, s2, 7
	s_or_b32 s12, s7, s2
	s_ashr_i32 s75, s6, 3
	s_lshl_b32 s6, s12, 8
	s_ashr_i32 s7, s6, 31
	s_lshl_b64 s[6:7], s[6:7], 12
	s_add_u32 s16, s90, s6
	s_addc_u32 s17, s91, s7
	s_lshl_b32 s6, s75, 8
	s_ashr_i32 s7, s6, 31
	v_readlane_b32 s52, v254, 16
	s_lshl_b64 s[6:7], s[6:7], 12
	v_readlane_b32 s66, v254, 30
	v_readlane_b32 s67, v254, 31
	s_add_u32 s20, s66, s6
	s_addc_u32 s21, s67, s7
	s_add_u32 s44, s20, 0x80000
	s_addc_u32 s45, s21, 0
	v_readlane_b32 s53, v254, 17
	v_readlane_b32 s54, v254, 18
	v_readlane_b32 s55, v254, 19
	v_readlane_b32 s56, v254, 20
	v_readlane_b32 s57, v254, 21
	v_readlane_b32 s58, v254, 22
	v_readlane_b32 s59, v254, 23
	v_readlane_b32 s60, v254, 24
	v_readlane_b32 s61, v254, 25
	v_readlane_b32 s62, v254, 26
	v_readlane_b32 s63, v254, 27
	v_readlane_b32 s64, v254, 28
	v_readlane_b32 s65, v254, 29

; template <int K, int EPI, bool MIX = false>
; __device__ __forceinline__ void gemm_phase(const Params& p, const u16* __restrict__ A, const u16* __restrict__ Bt,
;                            const float* __restrict__ rs_in, float* __restrict__ ssq_out, float alpha, bool rev = false) {
;     ...
;       const int bcol = cpn * 256;
;       if (cpn < 8) {
;         const float* gn = (cpn < 4) ? p.q_norm : p.k_norm;
;         const float sc = (cpn < 4) ? 0.125f : 1.f;
;         float4 g[2][2];
; #pragma unroll
;         for (int bj = 0; bj < 2; ++bj)
; #pragma unroll
;           for (int n = 0; n < 2; ++n) g[bj][n] = *(const float4*)(gn + (bj * 2 + n) * 16 + pq4);
; #pragma unroll
;         for (int ai = 0; ai < 2; ++ai)
; #pragma unroll
;           for (int m = 0; m < 4; ++m) {
;             int row = brow + ai * 128 + wr * 64 + m * 16 + fr_e;
;             const float rin = rsqrtf(rsq[ai][m] * (1.f / DM) + 1e-6f);
.LBB0_204:
	v_mov_b32_e32 v147, v218
	s_lshl_b32 s2, s25, 8
	v_lshrrev_b32_e32 v128, 1, v147
	v_ashrrev_i32_e32 v145, 5, v147
	v_and_b32_e32 v146, 8, v128
	s_waitcnt vmcnt(6)
	v_fmamk_f32 v142, v242, 0x3a000000, v232
	v_and_b32_e32 v144, 15, v147
	v_lshl_or_b32 v128, v145, 4, v146
	s_mov_b64 s[4:5], -1
	s_cmp_gt_i32 s25, 7
	v_cmp_gt_f32_e32 vcc, s29, v142
	v_mul_f32_e32 v143, 0x4b800000, v142
	s_cbranch_scc1 .LBB0_207
	s_and_b64 vcc, exec, s[4:5]
	s_cbranch_vccnz .LBB0_304

.Llate_p5_done:
.LBB0_365:
	ds_read_b128 v[112:115], v234
	ds_read_b128 v[116:119], v234 offset:2048
	ds_read_b128 v[136:139], v235
	ds_read_b128 v[140:143], v235 offset:2048
	s_mov_b32 m0, s74
	ds_read_b128 v[144:147], v236
	ds_read_b128 v[148:151], v236 offset:2048
	ds_read_b128 v[152:155], v237
	ds_read_b128 v[156:159], v237 offset:2048
	ds_read_b128 v[160:163], v236 offset:4096
	ds_read_b128 v[164:167], v236 offset:6144
	ds_read_b128 v[168:171], v237 offset:4096
	ds_read_b128 v[172:175], v237 offset:6144
	s_add_u32 s80, s6, s22
	s_addc_u32 s81, s7, s23
	s_nop 0
	global_load_lds_dwordx4 v222, s[80:81]
	s_mov_b32 m0, s75
	s_nop 0
	s_add_u32 s80, s6, s24
	s_addc_u32 s81, s7, s25
	s_nop 0
	global_load_lds_dwordx4 v222, s[80:81]
	s_waitcnt lgkmcnt(8)
	s_barrier
	s_waitcnt lgkmcnt(0)
	v_mfma_f32_16x16x32_bf16 v[28:31], v[112:115], v[144:147], v[28:31]
	v_mfma_f32_16x16x32_bf16 v[24:27], v[116:119], v[144:147], v[24:27]
	v_mfma_f32_16x16x32_bf16 v[44:47], v[112:115], v[148:151], v[44:47]
	v_mfma_f32_16x16x32_bf16 v[40:43], v[116:119], v[148:151], v[40:43]
	v_mfma_f32_16x16x32_bf16 v[68:71], v[112:115], v[160:163], v[68:71]
	v_mfma_f32_16x16x32_bf16 v[64:67], v[116:119], v[160:163], v[64:67]
	v_mfma_f32_16x16x32_bf16 v[100:103], v[112:115], v[164:167], v[100:103]
	v_mfma_f32_16x16x32_bf16 v[96:99], v[116:119], v[164:167], v[96:99]
	v_mfma_f32_16x16x32_bf16 v[28:31], v[136:139], v[152:155], v[28:31]
	v_mfma_f32_16x16x32_bf16 v[24:27], v[140:143], v[152:155], v[24:27]
	v_mfma_f32_16x16x32_bf16 v[44:47], v[136:139], v[156:159], v[44:47]
	v_mfma_f32_16x16x32_bf16 v[40:43], v[140:143], v[156:159], v[40:43]
	v_mfma_f32_16x16x32_bf16 v[68:71], v[136:139], v[168:171], v[68:71]
	v_mfma_f32_16x16x32_bf16 v[64:67], v[140:143], v[168:171], v[64:67]
	v_mfma_f32_16x16x32_bf16 v[100:103], v[136:139], v[172:175], v[100:103]
	v_mfma_f32_16x16x32_bf16 v[96:99], v[140:143], v[172:175], v[96:99]
	s_barrier
	s_mov_b32 m0, s42
	ds_read_b128 v[176:179], v238
	ds_read_b128 v[180:183], v238 offset:2048
	ds_read_b128 v[184:187], v239
	ds_read_b128 v[188:191], v239 offset:2048
	s_add_u32 s80, s60, s30
	s_addc_u32 s81, s61, s31
	s_nop 0
	global_load_lds_dwordx4 v222, s[80:81]
	s_mov_b32 m0, s43
	s_nop 0
	s_add_u32 s80, s60, s36
	s_addc_u32 s81, s61, s37
	s_nop 0
	global_load_lds_dwordx4 v222, s[80:81]
	s_waitcnt lgkmcnt(0)
	s_barrier
	v_mfma_f32_16x16x32_bf16 v[20:23], v[176:179], v[144:147], v[20:23]
	v_mfma_f32_16x16x32_bf16 v[16:19], v[180:183], v[144:147], v[16:19]
	v_mfma_f32_16x16x32_bf16 v[36:39], v[176:179], v[148:151], v[36:39]
	v_mfma_f32_16x16x32_bf16 v[32:35], v[180:183], v[148:151], v[32:35]
	v_mfma_f32_16x16x32_bf16 v[52:55], v[176:179], v[160:163], v[52:55]
	v_mfma_f32_16x16x32_bf16 v[48:51], v[180:183], v[160:163], v[48:51]
	v_mfma_f32_16x16x32_bf16 v[76:79], v[176:179], v[164:167], v[76:79]
	v_mfma_f32_16x16x32_bf16 v[72:75], v[180:183], v[164:167], v[72:75]
	v_mfma_f32_16x16x32_bf16 v[20:23], v[184:187], v[152:155], v[20:23]
	v_mfma_f32_16x16x32_bf16 v[16:19], v[188:191], v[152:155], v[16:19]
	v_mfma_f32_16x16x32_bf16 v[36:39], v[184:187], v[156:159], v[36:39]
	v_mfma_f32_16x16x32_bf16 v[32:35], v[188:191], v[156:159], v[32:35]
	v_mfma_f32_16x16x32_bf16 v[52:55], v[184:187], v[168:171], v[52:55]
	v_mfma_f32_16x16x32_bf16 v[48:51], v[188:191], v[168:171], v[48:51]
	v_mfma_f32_16x16x32_bf16 v[76:79], v[184:187], v[172:175], v[76:79]
	v_mfma_f32_16x16x32_bf16 v[72:75], v[188:191], v[172:175], v[72:75]
	s_barrier
	s_mov_b32 m0, s34
	ds_read_b128 v[144:147], v236 offset:16384
	ds_read_b128 v[148:151], v236 offset:18432
	ds_read_b128 v[152:155], v237 offset:16384
	ds_read_b128 v[156:159], v237 offset:18432
	ds_read_b128 v[160:163], v236 offset:20480
	ds_read_b128 v[164:167], v236 offset:22528
	ds_read_b128 v[168:171], v237 offset:20480
	ds_read_b128 v[172:175], v237 offset:22528
	s_add_u32 s80, s6, s30
	s_addc_u32 s81, s7, s31
	s_nop 0
	global_load_lds_dwordx4 v222, s[80:81]
	s_mov_b32 m0, s44
	s_nop 0
	s_add_u32 s80, s6, s36
	s_addc_u32 s81, s7, s37
	s_nop 0
	global_load_lds_dwordx4 v222, s[80:81]
	s_barrier
	s_waitcnt lgkmcnt(0)
	v_mfma_f32_16x16x32_bf16 v[84:87], v[112:115], v[144:147], v[84:87]
	v_mfma_f32_16x16x32_bf16 v[80:83], v[116:119], v[144:147], v[80:83]
	v_mfma_f32_16x16x32_bf16 v[108:111], v[112:115], v[148:151], v[108:111]
	v_mfma_f32_16x16x32_bf16 v[104:107], v[116:119], v[148:151], v[104:107]
	v_mfma_f32_16x16x32_bf16 v[60:63], v[112:115], v[160:163], v[60:63]
	v_mfma_f32_16x16x32_bf16 v[56:59], v[116:119], v[160:163], v[56:59]
	v_mfma_f32_16x16x32_bf16 v[4:7], v[112:115], v[164:167], v[4:7]
	v_mfma_f32_16x16x32_bf16 v[0:3], v[116:119], v[164:167], v[0:3]
	v_mfma_f32_16x16x32_bf16 v[84:87], v[136:139], v[152:155], v[84:87]
	v_mfma_f32_16x16x32_bf16 v[80:83], v[140:143], v[152:155], v[80:83]
	v_mfma_f32_16x16x32_bf16 v[108:111], v[136:139], v[156:159], v[108:111]
	v_mfma_f32_16x16x32_bf16 v[104:107], v[140:143], v[156:159], v[104:107]
	v_mfma_f32_16x16x32_bf16 v[60:63], v[136:139], v[168:171], v[60:63]
	v_mfma_f32_16x16x32_bf16 v[56:59], v[140:143], v[168:171], v[56:59]
	v_mfma_f32_16x16x32_bf16 v[4:7], v[136:139], v[172:175], v[4:7]
	v_mfma_f32_16x16x32_bf16 v[0:3], v[140:143], v[172:175], v[0:3]
	s_barrier
	s_mov_b32 m0, s45
	s_add_u32 s80, s4, s30
	s_addc_u32 s81, s5, s31
	s_nop 0
	global_load_lds_dwordx4 v222, s[80:81]
	s_mov_b32 m0, s62
	s_nop 0
	s_add_u32 s80, s4, s36
	s_addc_u32 s81, s5, s37
	s_nop 0
	global_load_lds_dwordx4 v222, s[80:81]
	s_waitcnt vmcnt(6)
	s_barrier
	v_mfma_f32_16x16x32_bf16 v[120:123], v[176:179], v[148:151], v[120:123]
	v_mfma_f32_16x16x32_bf16 v[124:127], v[180:183], v[148:151], v[124:127]
	v_mfma_f32_16x16x32_bf16 v[88:91], v[176:179], v[160:163], v[88:91]
	v_mfma_f32_16x16x32_bf16 v[92:95], v[180:183], v[160:163], v[92:95]
	v_mfma_f32_16x16x32_bf16 v[12:15], v[176:179], v[164:167], v[12:15]
	v_mfma_f32_16x16x32_bf16 v[8:11], v[180:183], v[164:167], v[8:11]
	v_mfma_f32_16x16x32_bf16 v[112:115], v[176:179], v[144:147], v[128:131]
	v_mfma_f32_16x16x32_bf16 v[116:119], v[180:183], v[144:147], v[132:135]
	v_mfma_f32_16x16x32_bf16 v[120:123], v[184:187], v[156:159], v[120:123]
	v_mfma_f32_16x16x32_bf16 v[124:127], v[188:191], v[156:159], v[124:127]
	v_mfma_f32_16x16x32_bf16 v[88:91], v[184:187], v[168:171], v[88:91]
	v_mfma_f32_16x16x32_bf16 v[92:95], v[188:191], v[168:171], v[92:95]
	v_mfma_f32_16x16x32_bf16 v[12:15], v[184:187], v[172:175], v[12:15]
	v_mfma_f32_16x16x32_bf16 v[8:11], v[188:191], v[172:175], v[8:11]
	v_mfma_f32_16x16x32_bf16 v[112:115], v[184:187], v[152:155], v[112:115]
	v_mfma_f32_16x16x32_bf16 v[116:119], v[188:191], v[152:155], v[116:119]
	s_barrier
	ds_read_b128 v[128:131], v240
	ds_read_b128 v[132:135], v240 offset:2048
	ds_read_b128 v[136:139], v241
	ds_read_b128 v[140:143], v241 offset:2048
	s_mov_b32 m0, s63
	ds_read_b128 v[144:147], v236 offset:32768
	ds_read_b128 v[148:151], v236 offset:34816
	ds_read_b128 v[152:155], v237 offset:32768
	ds_read_b128 v[156:159], v237 offset:34816
	ds_read_b128 v[160:163], v236 offset:36864
	ds_read_b128 v[164:167], v236 offset:38912
	ds_read_b128 v[168:171], v237 offset:36864
	ds_read_b128 v[172:175], v237 offset:38912
	s_add_u32 s80, s6, 0x80100
	s_addc_u32 s81, s7, 0x0
	s_nop 0
	global_load_lds_dwordx4 v222, s[80:81]
	s_mov_b32 m0, s64
	s_nop 0
	s_add_u32 s80, s6, 0xc0100
	s_addc_u32 s81, s7, 0x0
	s_nop 0
	global_load_lds_dwordx4 v222, s[80:81]
	s_waitcnt lgkmcnt(8)
	s_barrier
	s_waitcnt lgkmcnt(0)
	v_mfma_f32_16x16x32_bf16 v[28:31], v[128:131], v[144:147], v[28:31]
	v_mfma_f32_16x16x32_bf16 v[24:27], v[132:135], v[144:147], v[24:27]
	v_mfma_f32_16x16x32_bf16 v[44:47], v[128:131], v[148:151], v[44:47]
	v_mfma_f32_16x16x32_bf16 v[40:43], v[132:135], v[148:151], v[40:43]
	v_mfma_f32_16x16x32_bf16 v[68:71], v[128:131], v[160:163], v[68:71]
	v_mfma_f32_16x16x32_bf16 v[64:67], v[132:135], v[160:163], v[64:67]
	v_mfma_f32_16x16x32_bf16 v[100:103], v[128:131], v[164:167], v[100:103]
	v_mfma_f32_16x16x32_bf16 v[96:99], v[132:135], v[164:167], v[96:99]
	v_mfma_f32_16x16x32_bf16 v[28:31], v[136:139], v[152:155], v[28:31]
	v_mfma_f32_16x16x32_bf16 v[24:27], v[140:143], v[152:155], v[24:27]
	v_mfma_f32_16x16x32_bf16 v[44:47], v[136:139], v[156:159], v[44:47]
	v_mfma_f32_16x16x32_bf16 v[40:43], v[140:143], v[156:159], v[40:43]
	v_mfma_f32_16x16x32_bf16 v[68:71], v[136:139], v[168:171], v[68:71]
	v_mfma_f32_16x16x32_bf16 v[64:67], v[140:143], v[168:171], v[64:67]
	v_mfma_f32_16x16x32_bf16 v[100:103], v[136:139], v[172:175], v[100:103]
	v_mfma_f32_16x16x32_bf16 v[96:99], v[140:143], v[172:175], v[96:99]
	s_barrier
	s_mov_b32 m0, s65
	ds_read_b128 v[176:179], v242
	ds_read_b128 v[180:183], v242 offset:2048
	ds_read_b128 v[184:187], v243
	ds_read_b128 v[188:191], v243 offset:2048
	s_add_u32 s80, s60, s38
	s_addc_u32 s81, s61, s39
	s_nop 0
	global_load_lds_dwordx4 v222, s[80:81]
	s_mov_b32 m0, s68
	s_nop 0
	s_add_u32 s80, s60, s40
	s_addc_u32 s81, s61, s41
	s_nop 0
	global_load_lds_dwordx4 v222, s[80:81]
	s_waitcnt lgkmcnt(0)
	s_barrier
	v_mfma_f32_16x16x32_bf16 v[20:23], v[176:179], v[144:147], v[20:23]
	v_mfma_f32_16x16x32_bf16 v[16:19], v[180:183], v[144:147], v[16:19]
	v_mfma_f32_16x16x32_bf16 v[36:39], v[176:179], v[148:151], v[36:39]
	v_mfma_f32_16x16x32_bf16 v[32:35], v[180:183], v[148:151], v[32:35]
	v_mfma_f32_16x16x32_bf16 v[52:55], v[176:179], v[160:163], v[52:55]
	v_mfma_f32_16x16x32_bf16 v[48:51], v[180:183], v[160:163], v[48:51]
	v_mfma_f32_16x16x32_bf16 v[76:79], v[176:179], v[164:167], v[76:79]
	v_mfma_f32_16x16x32_bf16 v[72:75], v[180:183], v[164:167], v[72:75]
	v_mfma_f32_16x16x32_bf16 v[20:23], v[184:187], v[152:155], v[20:23]
	v_mfma_f32_16x16x32_bf16 v[16:19], v[188:191], v[152:155], v[16:19]
	v_mfma_f32_16x16x32_bf16 v[36:39], v[184:187], v[156:159], v[36:39]
	v_mfma_f32_16x16x32_bf16 v[32:35], v[188:191], v[156:159], v[32:35]
	v_mfma_f32_16x16x32_bf16 v[52:55], v[184:187], v[168:171], v[52:55]
	v_mfma_f32_16x16x32_bf16 v[48:51], v[188:191], v[168:171], v[48:51]
	v_mfma_f32_16x16x32_bf16 v[76:79], v[184:187], v[172:175], v[76:79]
	v_mfma_f32_16x16x32_bf16 v[72:75], v[188:191], v[172:175], v[72:75]
	s_barrier
	s_mov_b32 m0, s69
	ds_read_b128 v[144:147], v236 offset:49152
	ds_read_b128 v[148:151], v236 offset:51200
	ds_read_b128 v[152:155], v237 offset:49152
	ds_read_b128 v[156:159], v237 offset:51200
	ds_read_b128 v[160:163], v236 offset:53248
	ds_read_b128 v[164:167], v236 offset:55296
	ds_read_b128 v[168:171], v237 offset:53248
	ds_read_b128 v[172:175], v237 offset:55296
	s_add_u32 s80, s6, s38
	s_addc_u32 s81, s7, s39
	s_nop 0
	global_load_lds_dwordx4 v222, s[80:81]
	s_mov_b32 m0, s70
	s_nop 0
	s_add_u32 s80, s6, s40
	s_addc_u32 s81, s7, s41
	s_nop 0
	global_load_lds_dwordx4 v222, s[80:81]
	s_barrier
; template <int K, int EPI, bool MIX = false>
; __device__ __forceinline__ void gemm_phase(const Params& p, const u16* __restrict__ A, const u16* __restrict__ Bt,
;                            const float* __restrict__ rs_in, float* __restrict__ ssq_out, float alpha, bool rev = false) {
;     ...
;     if constexpr (MIX) {
;       for (int t = 0; t < nt / 2; t += 2) KBODY(t);
;       {
;           int fr_m = fr;
;           asm volatile("" : "+v"(fr_m));
; #pragma unroll
;           for (int ai = 0; ai < 2; ++ai)
; #pragma unroll
;             for (int m = 0; m < 4; ++m) {
;               const int row = pm * 256 + ai * 128 + wr * 64 + m * 16 + fr_m;
;               const float ra = rsqrtf(p.ssqa[row] * (1.f / 1024.f) + 1e-6f);
;               const float rb = rsqrtf(p.ssqb[row] * (1.f / 1024.f) + 1e-6f);
;               const float f = ra * __builtin_amdgcn_rcpf(rb);
; #pragma unroll
;               for (int bj = 0; bj < 2; ++bj)
; #pragma unroll
;                 for (int n = 0; n < 2; ++n) acc[ai][bj][m][n] *= f;
;             }
	s_waitcnt lgkmcnt(0)
	v_mfma_f32_16x16x32_bf16 v[84:87], v[128:131], v[144:147], v[84:87]
	v_mfma_f32_16x16x32_bf16 v[80:83], v[132:135], v[144:147], v[80:83]
	v_mfma_f32_16x16x32_bf16 v[108:111], v[128:131], v[148:151], v[108:111]
	v_mfma_f32_16x16x32_bf16 v[104:107], v[132:135], v[148:151], v[104:107]
	v_mfma_f32_16x16x32_bf16 v[60:63], v[128:131], v[160:163], v[60:63]
	v_mfma_f32_16x16x32_bf16 v[56:59], v[132:135], v[160:163], v[56:59]
	v_mfma_f32_16x16x32_bf16 v[4:7], v[128:131], v[164:167], v[4:7]
	v_mfma_f32_16x16x32_bf16 v[0:3], v[132:135], v[164:167], v[0:3]
	v_mfma_f32_16x16x32_bf16 v[84:87], v[136:139], v[152:155], v[84:87]
	v_mfma_f32_16x16x32_bf16 v[80:83], v[140:143], v[152:155], v[80:83]
	v_mfma_f32_16x16x32_bf16 v[108:111], v[136:139], v[156:159], v[108:111]
	v_mfma_f32_16x16x32_bf16 v[104:107], v[140:143], v[156:159], v[104:107]
	v_mfma_f32_16x16x32_bf16 v[60:63], v[136:139], v[168:171], v[60:63]
	v_mfma_f32_16x16x32_bf16 v[56:59], v[140:143], v[168:171], v[56:59]
	v_mfma_f32_16x16x32_bf16 v[4:7], v[136:139], v[172:175], v[4:7]
	v_mfma_f32_16x16x32_bf16 v[0:3], v[140:143], v[172:175], v[0:3]
	s_barrier
	s_mov_b32 m0, s71
	s_add_u32 s80, s4, s38
	s_addc_u32 s81, s5, s39
	s_nop 0
	global_load_lds_dwordx4 v222, s[80:81]
	s_mov_b32 m0, s72
	s_nop 0
	s_add_u32 s80, s4, s40
	s_addc_u32 s81, s5, s41
	s_nop 0
	global_load_lds_dwordx4 v222, s[80:81]
	s_waitcnt vmcnt(6)
	s_barrier
	v_mfma_f32_16x16x32_bf16 v[112:115], v[176:179], v[144:147], v[112:115]
	v_mfma_f32_16x16x32_bf16 v[128:131], v[184:187], v[152:155], v[112:115]
	v_mfma_f32_16x16x32_bf16 v[112:115], v[180:183], v[144:147], v[116:119]
	v_mfma_f32_16x16x32_bf16 v[132:135], v[188:191], v[152:155], v[112:115]
	v_mfma_f32_16x16x32_bf16 v[112:115], v[176:179], v[148:151], v[120:123]
	v_mfma_f32_16x16x32_bf16 v[120:123], v[184:187], v[156:159], v[112:115]
	v_mfma_f32_16x16x32_bf16 v[112:115], v[180:183], v[148:151], v[124:127]
	v_mfma_f32_16x16x32_bf16 v[88:91], v[176:179], v[160:163], v[88:91]
	v_mfma_f32_16x16x32_bf16 v[92:95], v[180:183], v[160:163], v[92:95]
	v_mfma_f32_16x16x32_bf16 v[12:15], v[176:179], v[164:167], v[12:15]
	v_mfma_f32_16x16x32_bf16 v[8:11], v[180:183], v[164:167], v[8:11]
	v_mfma_f32_16x16x32_bf16 v[124:127], v[188:191], v[156:159], v[112:115]
	v_mfma_f32_16x16x32_bf16 v[88:91], v[184:187], v[168:171], v[88:91]
	v_mfma_f32_16x16x32_bf16 v[92:95], v[188:191], v[168:171], v[92:95]
	v_mfma_f32_16x16x32_bf16 v[12:15], v[184:187], v[172:175], v[12:15]
	v_mfma_f32_16x16x32_bf16 v[8:11], v[188:191], v[172:175], v[8:11]
	s_barrier
	s_add_i32 s33, s33, 2
	s_add_u32 s60, s60, 0x100
	s_addc_u32 s61, s61, 0
	s_add_u32 s6, s6, 0x100
	s_addc_u32 s7, s7, 0
	s_add_u32 s4, s4, 0x100
	s_addc_u32 s5, s5, 0
	s_cmp_lt_u32 s33, 14
	s_cbranch_scc1 .LBB0_365
	v_mov_b32_e32 v112, v233
	s_lshl_b32 s79, s35, 8
	s_add_i32 s79, s79, s73
	v_add_u32_e32 v112, s79, v112
	v_ashrrev_i32_e32 v113, 31, v112
	v_lshlrev_b64 v[112:113], 2, v[112:113]
	v_lshl_add_u64 v[138:139], s[86:87], 0, v[112:113]
	global_load_dword v114, v[138:139], off
	v_lshl_add_u64 v[136:137], s[88:89], 0, v[112:113]
	global_load_dword v112, v[136:137], off
	s_mov_b32 s33, 14
	s_mov_b64 s[4:5], s[16:17]
	s_mov_b64 s[6:7], s[8:9]
	s_mov_b64 s[60:61], s[12:13]
	s_waitcnt vmcnt(0)
	v_fmamk_f32 v114, v114, 0x3a800000, v244
	v_cmp_gt_f32_e32 vcc, s76, v114
	v_mul_f32_e32 v115, 0x4b800000, v114
	v_fmamk_f32 v112, v112, 0x3a800000, v244
	v_cndmask_b32_e32 v114, v114, v115, vcc
	v_rsq_f32_e32 v114, v114
	v_mul_f32_e32 v113, 0x4b800000, v112
	v_mul_f32_e32 v115, 0x45800000, v114
	v_cndmask_b32_e32 v114, v114, v115, vcc
	v_cmp_gt_f32_e32 vcc, s76, v112
	s_nop 1
	v_cndmask_b32_e32 v112, v112, v113, vcc
	v_rsq_f32_e32 v112, v112
	s_nop 0
	v_mul_f32_e32 v113, 0x45800000, v112
	v_cndmask_b32_e32 v112, v112, v113, vcc
	v_rcp_f32_e32 v112, v112
	s_nop 0
	v_mul_f32_e32 v112, v114, v112
	v_pk_mul_f32 v[30:31], v[30:31], v[112:113] op_sel_hi:[1,0]
	v_pk_mul_f32 v[28:29], v[28:29], v[112:113] op_sel_hi:[1,0]
	v_pk_mul_f32 v[26:27], v[26:27], v[112:113] op_sel_hi:[1,0]
	v_pk_mul_f32 v[24:25], v[24:25], v[112:113] op_sel_hi:[1,0]
	v_pk_mul_f32 v[22:23], v[22:23], v[112:113] op_sel_hi:[1,0]
	v_pk_mul_f32 v[20:21], v[20:21], v[112:113] op_sel_hi:[1,0]
	v_pk_mul_f32 v[18:19], v[18:19], v[112:113] op_sel_hi:[1,0]
	v_pk_mul_f32 v[16:17], v[16:17], v[112:113] op_sel_hi:[1,0]
	global_load_dword v112, v[138:139], off offset:64
	s_waitcnt vmcnt(0)
	v_fmamk_f32 v112, v112, 0x3a800000, v244
	v_cmp_gt_f32_e32 vcc, s76, v112
	v_mul_f32_e32 v113, 0x4b800000, v112
	s_nop 0
	v_cndmask_b32_e32 v112, v112, v113, vcc
	v_rsq_f32_e32 v112, v112
	s_nop 0
	v_mul_f32_e32 v113, 0x45800000, v112
	v_cndmask_b32_e32 v112, v112, v113, vcc
	global_load_dword v113, v[136:137], off offset:64
	s_waitcnt vmcnt(0)
	v_fmamk_f32 v113, v113, 0x3a800000, v244
	v_cmp_gt_f32_e32 vcc, s76, v113
	v_mul_f32_e32 v114, 0x4b800000, v113
	s_nop 0
	v_cndmask_b32_e32 v113, v113, v114, vcc
	v_rsq_f32_e32 v113, v113
	s_nop 0
	v_mul_f32_e32 v114, 0x45800000, v113
	v_cndmask_b32_e32 v113, v113, v114, vcc
	v_rcp_f32_e32 v113, v113
	s_nop 0
	v_mul_f32_e32 v112, v112, v113
	v_pk_mul_f32 v[46:47], v[46:47], v[112:113] op_sel_hi:[1,0]
	v_pk_mul_f32 v[44:45], v[44:45], v[112:113] op_sel_hi:[1,0]
	v_pk_mul_f32 v[42:43], v[42:43], v[112:113] op_sel_hi:[1,0]
	v_pk_mul_f32 v[40:41], v[40:41], v[112:113] op_sel_hi:[1,0]
	v_pk_mul_f32 v[38:39], v[38:39], v[112:113] op_sel_hi:[1,0]
	v_pk_mul_f32 v[36:37], v[36:37], v[112:113] op_sel_hi:[1,0]
	v_pk_mul_f32 v[34:35], v[34:35], v[112:113] op_sel_hi:[1,0]
	v_pk_mul_f32 v[32:33], v[32:33], v[112:113] op_sel_hi:[1,0]
	global_load_dword v112, v[138:139], off offset:128
	s_waitcnt vmcnt(0)
; template <int K, int EPI, bool MIX = false>
; __device__ __forceinline__ void gemm_phase(const Params& p, const u16* __restrict__ A, const u16* __restrict__ Bt,
;                            const float* __restrict__ rs_in, float* __restrict__ ssq_out, float alpha, bool rev = false) {
;     ...
;           for (int ai = 0; ai < 2; ++ai)
; #pragma unroll
;             for (int m = 0; m < 4; ++m) {
;               const int row = pm * 256 + ai * 128 + wr * 64 + m * 16 + fr_m;
;               const float ra = rsqrtf(p.ssqa[row] * (1.f / 1024.f) + 1e-6f);
;               const float rb = rsqrtf(p.ssqb[row] * (1.f / 1024.f) + 1e-6f);
;               const float f = ra * __builtin_amdgcn_rcpf(rb);
; #pragma unroll
;               for (int bj = 0; bj < 2; ++bj)
; #pragma unroll
;                 for (int n = 0; n < 2; ++n) acc[ai][bj][m][n] *= f;
;             }
	v_fmamk_f32 v112, v112, 0x3a800000, v244
	v_cmp_gt_f32_e32 vcc, s76, v112
	v_mul_f32_e32 v113, 0x4b800000, v112
	s_nop 0
	v_cndmask_b32_e32 v112, v112, v113, vcc
	v_rsq_f32_e32 v112, v112
	s_nop 0
	v_mul_f32_e32 v113, 0x45800000, v112
	v_cndmask_b32_e32 v112, v112, v113, vcc
	global_load_dword v113, v[136:137], off offset:128
	s_waitcnt vmcnt(0)
	v_fmamk_f32 v113, v113, 0x3a800000, v244
	v_cmp_gt_f32_e32 vcc, s76, v113
	v_mul_f32_e32 v114, 0x4b800000, v113
	s_nop 0
	v_cndmask_b32_e32 v113, v113, v114, vcc
	v_rsq_f32_e32 v113, v113
	s_nop 0
	v_mul_f32_e32 v114, 0x45800000, v113
	v_cndmask_b32_e32 v113, v113, v114, vcc
	v_rcp_f32_e32 v113, v113
	s_nop 0
	v_mul_f32_e32 v112, v112, v113
	v_pk_mul_f32 v[70:71], v[70:71], v[112:113] op_sel_hi:[1,0]
	v_pk_mul_f32 v[68:69], v[68:69], v[112:113] op_sel_hi:[1,0]
	v_pk_mul_f32 v[66:67], v[66:67], v[112:113] op_sel_hi:[1,0]
	v_pk_mul_f32 v[64:65], v[64:65], v[112:113] op_sel_hi:[1,0]
	v_pk_mul_f32 v[54:55], v[54:55], v[112:113] op_sel_hi:[1,0]
	v_pk_mul_f32 v[52:53], v[52:53], v[112:113] op_sel_hi:[1,0]
	v_pk_mul_f32 v[50:51], v[50:51], v[112:113] op_sel_hi:[1,0]
	v_pk_mul_f32 v[48:49], v[48:49], v[112:113] op_sel_hi:[1,0]
	global_load_dword v112, v[138:139], off offset:192
	s_waitcnt vmcnt(0)
	v_fmamk_f32 v112, v112, 0x3a800000, v244
	v_cmp_gt_f32_e32 vcc, s76, v112
	v_mul_f32_e32 v113, 0x4b800000, v112
	s_nop 0
	v_cndmask_b32_e32 v112, v112, v113, vcc
	v_rsq_f32_e32 v112, v112
	s_nop 0
	v_mul_f32_e32 v113, 0x45800000, v112
	v_cndmask_b32_e32 v112, v112, v113, vcc
	global_load_dword v113, v[136:137], off offset:192
	s_waitcnt vmcnt(0)
	v_fmamk_f32 v113, v113, 0x3a800000, v244
	v_cmp_gt_f32_e32 vcc, s76, v113
	v_mul_f32_e32 v114, 0x4b800000, v113
	s_nop 0
	v_cndmask_b32_e32 v113, v113, v114, vcc
	v_rsq_f32_e32 v113, v113
	s_nop 0
	v_mul_f32_e32 v114, 0x45800000, v113
	v_cndmask_b32_e32 v113, v113, v114, vcc
	v_rcp_f32_e32 v113, v113
	s_nop 0
	v_mul_f32_e32 v140, v112, v113
	v_pk_mul_f32 v[112:113], v[96:97], v[140:141] op_sel_hi:[1,0]
	global_load_dword v96, v[138:139], off offset:512
	v_pk_mul_f32 v[114:115], v[98:99], v[140:141] op_sel_hi:[1,0]
	v_pk_mul_f32 v[118:119], v[102:103], v[140:141] op_sel_hi:[1,0]
	v_pk_mul_f32 v[116:117], v[100:101], v[140:141] op_sel_hi:[1,0]
	v_pk_mul_f32 v[78:79], v[78:79], v[140:141] op_sel_hi:[1,0]
	v_pk_mul_f32 v[76:77], v[76:77], v[140:141] op_sel_hi:[1,0]
	v_pk_mul_f32 v[74:75], v[74:75], v[140:141] op_sel_hi:[1,0]
	v_pk_mul_f32 v[72:73], v[72:73], v[140:141] op_sel_hi:[1,0]
	s_waitcnt vmcnt(0)
	v_fmamk_f32 v96, v96, 0x3a800000, v244
	v_cmp_gt_f32_e32 vcc, s76, v96
	v_mul_f32_e32 v97, 0x4b800000, v96
	s_nop 0
	v_cndmask_b32_e32 v96, v96, v97, vcc
	v_rsq_f32_e32 v96, v96
	s_nop 0
	v_mul_f32_e32 v97, 0x45800000, v96
	v_cndmask_b32_e32 v96, v96, v97, vcc
	global_load_dword v97, v[136:137], off offset:512
	s_waitcnt vmcnt(0)
	v_fmamk_f32 v97, v97, 0x3a800000, v244
	v_cmp_gt_f32_e32 vcc, s76, v97
	v_mul_f32_e32 v98, 0x4b800000, v97
	s_nop 0
	v_cndmask_b32_e32 v97, v97, v98, vcc
	v_rsq_f32_e32 v97, v97
	s_nop 0
	v_mul_f32_e32 v98, 0x45800000, v97
	v_cndmask_b32_e32 v97, v97, v98, vcc
	v_rcp_f32_e32 v97, v97
	s_nop 0
	v_mul_f32_e32 v140, v96, v97
	v_pk_mul_f32 v[96:97], v[80:81], v[140:141] op_sel_hi:[1,0]
	v_pk_mul_f32 v[80:81], v[128:129], v[140:141] op_sel_hi:[1,0]
	global_load_dword v128, v[138:139], off offset:576
	v_pk_mul_f32 v[98:99], v[82:83], v[140:141] op_sel_hi:[1,0]
	v_pk_mul_f32 v[82:83], v[130:131], v[140:141] op_sel_hi:[1,0]
	v_pk_mul_f32 v[102:103], v[86:87], v[140:141] op_sel_hi:[1,0]
	v_pk_mul_f32 v[100:101], v[84:85], v[140:141] op_sel_hi:[1,0]
	v_pk_mul_f32 v[86:87], v[134:135], v[140:141] op_sel_hi:[1,0]
	v_pk_mul_f32 v[84:85], v[132:133], v[140:141] op_sel_hi:[1,0]
	s_waitcnt vmcnt(0)
	v_fmamk_f32 v128, v128, 0x3a800000, v244
	v_cmp_gt_f32_e32 vcc, s76, v128
	v_mul_f32_e32 v129, 0x4b800000, v128
	s_nop 0
	v_cndmask_b32_e32 v128, v128, v129, vcc
	v_rsq_f32_e32 v128, v128
	s_nop 0
	v_mul_f32_e32 v129, 0x45800000, v128
	v_cndmask_b32_e32 v128, v128, v129, vcc
	global_load_dword v129, v[136:137], off offset:576
	s_waitcnt vmcnt(0)
	v_fmamk_f32 v129, v129, 0x3a800000, v244
	v_cmp_gt_f32_e32 vcc, s76, v129
	v_mul_f32_e32 v130, 0x4b800000, v129
	s_nop 0
	v_cndmask_b32_e32 v129, v129, v130, vcc
	v_rsq_f32_e32 v129, v129
	s_nop 0
	v_mul_f32_e32 v130, 0x45800000, v129
	v_cndmask_b32_e32 v129, v129, v130, vcc
	v_rcp_f32_e32 v129, v129
	s_nop 0
	v_mul_f32_e32 v140, v128, v129
	v_pk_mul_f32 v[128:129], v[104:105], v[140:141] op_sel_hi:[1,0]
	v_pk_mul_f32 v[104:105], v[120:121], v[140:141] op_sel_hi:[1,0]
	global_load_dword v120, v[138:139], off offset:640
	v_pk_mul_f32 v[130:131], v[106:107], v[140:141] op_sel_hi:[1,0]
	v_pk_mul_f32 v[106:107], v[122:123], v[140:141] op_sel_hi:[1,0]
	v_pk_mul_f32 v[134:135], v[110:111], v[140:141] op_sel_hi:[1,0]
	v_pk_mul_f32 v[132:133], v[108:109], v[140:141] op_sel_hi:[1,0]
	v_pk_mul_f32 v[110:111], v[126:127], v[140:141] op_sel_hi:[1,0]
	v_pk_mul_f32 v[108:109], v[124:125], v[140:141] op_sel_hi:[1,0]
	s_waitcnt vmcnt(0)
	v_fmamk_f32 v120, v120, 0x3a800000, v244
	v_cmp_gt_f32_e32 vcc, s76, v120
	v_mul_f32_e32 v121, 0x4b800000, v120
	s_nop 0
	v_cndmask_b32_e32 v120, v120, v121, vcc
	v_rsq_f32_e32 v120, v120
	s_nop 0
	v_mul_f32_e32 v121, 0x45800000, v120
	v_cndmask_b32_e32 v120, v120, v121, vcc
	global_load_dword v121, v[136:137], off offset:640
	s_waitcnt vmcnt(0)
; template <int K, int EPI, bool MIX = false>
; __device__ __forceinline__ void gemm_phase(const Params& p, const u16* __restrict__ A, const u16* __restrict__ Bt,
;                            const float* __restrict__ rs_in, float* __restrict__ ssq_out, float alpha, bool rev = false) {
;     ...
;           for (int ai = 0; ai < 2; ++ai)
; #pragma unroll
;             for (int m = 0; m < 4; ++m) {
;               const int row = pm * 256 + ai * 128 + wr * 64 + m * 16 + fr_m;
;               const float ra = rsqrtf(p.ssqa[row] * (1.f / 1024.f) + 1e-6f);
;               const float rb = rsqrtf(p.ssqb[row] * (1.f / 1024.f) + 1e-6f);
;               const float f = ra * __builtin_amdgcn_rcpf(rb);
; #pragma unroll
;               for (int bj = 0; bj < 2; ++bj)
; #pragma unroll
;                 for (int n = 0; n < 2; ++n) acc[ai][bj][m][n] *= f;
;             }
	v_fmamk_f32 v121, v121, 0x3a800000, v244
	v_cmp_gt_f32_e32 vcc, s76, v121
	v_mul_f32_e32 v122, 0x4b800000, v121
	s_nop 0
	v_cndmask_b32_e32 v121, v121, v122, vcc
	v_rsq_f32_e32 v121, v121
	s_nop 0
	v_mul_f32_e32 v122, 0x45800000, v121
	v_cndmask_b32_e32 v121, v121, v122, vcc
	v_rcp_f32_e32 v121, v121
	s_nop 0
	v_mul_f32_e32 v140, v120, v121
	v_pk_mul_f32 v[120:121], v[56:57], v[140:141] op_sel_hi:[1,0]
	v_pk_mul_f32 v[56:57], v[88:89], v[140:141] op_sel_hi:[1,0]
	global_load_dword v88, v[138:139], off offset:704
	v_pk_mul_f32 v[122:123], v[58:59], v[140:141] op_sel_hi:[1,0]
	v_pk_mul_f32 v[58:59], v[90:91], v[140:141] op_sel_hi:[1,0]
	v_pk_mul_f32 v[126:127], v[62:63], v[140:141] op_sel_hi:[1,0]
	v_pk_mul_f32 v[124:125], v[60:61], v[140:141] op_sel_hi:[1,0]
	v_pk_mul_f32 v[62:63], v[94:95], v[140:141] op_sel_hi:[1,0]
	v_pk_mul_f32 v[60:61], v[92:93], v[140:141] op_sel_hi:[1,0]
	s_waitcnt vmcnt(0)
	v_fmamk_f32 v88, v88, 0x3a800000, v244
	v_cmp_gt_f32_e32 vcc, s76, v88
	v_mul_f32_e32 v89, 0x4b800000, v88
	s_nop 0
	v_cndmask_b32_e32 v88, v88, v89, vcc
	v_rsq_f32_e32 v88, v88
	s_nop 0
	v_mul_f32_e32 v89, 0x45800000, v88
	v_cndmask_b32_e32 v88, v88, v89, vcc
	global_load_dword v89, v[136:137], off offset:704
	s_waitcnt vmcnt(0)
	v_fmamk_f32 v89, v89, 0x3a800000, v244
	v_cmp_gt_f32_e32 vcc, s76, v89
	v_mul_f32_e32 v90, 0x4b800000, v89
	s_nop 0
	v_cndmask_b32_e32 v89, v89, v90, vcc
	v_rsq_f32_e32 v89, v89
	s_nop 0
	v_mul_f32_e32 v90, 0x45800000, v89
	v_cndmask_b32_e32 v89, v89, v90, vcc
	v_rcp_f32_e32 v89, v89
	s_nop 0
	v_mul_f32_e32 v136, v88, v89
	v_pk_mul_f32 v[90:91], v[6:7], v[136:137] op_sel_hi:[1,0]
	v_pk_mul_f32 v[88:89], v[4:5], v[136:137] op_sel_hi:[1,0]
	v_pk_mul_f32 v[94:95], v[2:3], v[136:137] op_sel_hi:[1,0]
	v_pk_mul_f32 v[92:93], v[0:1], v[136:137] op_sel_hi:[1,0]
	v_pk_mul_f32 v[2:3], v[14:15], v[136:137] op_sel_hi:[1,0]
	v_pk_mul_f32 v[0:1], v[12:13], v[136:137] op_sel_hi:[1,0]
	v_pk_mul_f32 v[6:7], v[10:11], v[136:137] op_sel_hi:[1,0]
	v_pk_mul_f32 v[4:5], v[8:9], v[136:137] op_sel_hi:[1,0]
.LBB0_367:
	ds_read_b128 v[8:11], v234
	ds_read_b128 v[12:15], v234 offset:2048
	ds_read_b128 v[136:139], v235
	ds_read_b128 v[140:143], v235 offset:2048
	s_mov_b32 m0, s74
	ds_read_b128 v[144:147], v236
	ds_read_b128 v[148:151], v236 offset:2048
	ds_read_b128 v[152:155], v237
	ds_read_b128 v[156:159], v237 offset:2048
	ds_read_b128 v[160:163], v236 offset:4096
	ds_read_b128 v[164:167], v236 offset:6144
	ds_read_b128 v[168:171], v237 offset:4096
	ds_read_b128 v[172:175], v237 offset:6144
	s_add_u32 s80, s6, 0x80880
	s_addc_u32 s81, s7, 0x0
	s_nop 0
	global_load_lds_dwordx4 v222, s[80:81]
	s_mov_b32 m0, s75
	s_nop 0
	s_add_u32 s80, s6, 0xc0880
	s_addc_u32 s81, s7, 0x0
	s_nop 0
	global_load_lds_dwordx4 v222, s[80:81]
	s_waitcnt lgkmcnt(8)
	s_barrier
	s_waitcnt lgkmcnt(0)
	v_mfma_f32_16x16x32_bf16 v[28:31], v[8:11], v[144:147], v[28:31]
	v_mfma_f32_16x16x32_bf16 v[24:27], v[12:15], v[144:147], v[24:27]
	v_mfma_f32_16x16x32_bf16 v[44:47], v[8:11], v[148:151], v[44:47]
	v_mfma_f32_16x16x32_bf16 v[40:43], v[12:15], v[148:151], v[40:43]
	v_mfma_f32_16x16x32_bf16 v[68:71], v[8:11], v[160:163], v[68:71]
	v_mfma_f32_16x16x32_bf16 v[64:67], v[12:15], v[160:163], v[64:67]
	v_mfma_f32_16x16x32_bf16 v[116:119], v[8:11], v[164:167], v[116:119]
	v_mfma_f32_16x16x32_bf16 v[112:115], v[12:15], v[164:167], v[112:115]
	v_mfma_f32_16x16x32_bf16 v[28:31], v[136:139], v[152:155], v[28:31]
	v_mfma_f32_16x16x32_bf16 v[24:27], v[140:143], v[152:155], v[24:27]
	v_mfma_f32_16x16x32_bf16 v[44:47], v[136:139], v[156:159], v[44:47]
	v_mfma_f32_16x16x32_bf16 v[40:43], v[140:143], v[156:159], v[40:43]
	v_mfma_f32_16x16x32_bf16 v[68:71], v[136:139], v[168:171], v[68:71]
	v_mfma_f32_16x16x32_bf16 v[64:67], v[140:143], v[168:171], v[64:67]
	v_mfma_f32_16x16x32_bf16 v[116:119], v[136:139], v[172:175], v[116:119]
	v_mfma_f32_16x16x32_bf16 v[112:115], v[140:143], v[172:175], v[112:115]
	s_barrier
	s_mov_b32 m0, s42
	ds_read_b128 v[176:179], v238
	ds_read_b128 v[180:183], v238 offset:2048
	ds_read_b128 v[184:187], v239
	ds_read_b128 v[188:191], v239 offset:2048
	s_add_u32 s80, s60, s46
	s_addc_u32 s81, s61, s47
	s_nop 0
	global_load_lds_dwordx4 v222, s[80:81]
	s_mov_b32 m0, s43
	s_nop 0
	s_add_u32 s80, s60, s48
	s_addc_u32 s81, s61, s49
	s_nop 0
	global_load_lds_dwordx4 v222, s[80:81]
	s_waitcnt lgkmcnt(0)
	s_barrier
	v_mfma_f32_16x16x32_bf16 v[20:23], v[176:179], v[144:147], v[20:23]
	v_mfma_f32_16x16x32_bf16 v[16:19], v[180:183], v[144:147], v[16:19]
	v_mfma_f32_16x16x32_bf16 v[36:39], v[176:179], v[148:151], v[36:39]
	v_mfma_f32_16x16x32_bf16 v[32:35], v[180:183], v[148:151], v[32:35]
	v_mfma_f32_16x16x32_bf16 v[52:55], v[176:179], v[160:163], v[52:55]
	v_mfma_f32_16x16x32_bf16 v[48:51], v[180:183], v[160:163], v[48:51]
	v_mfma_f32_16x16x32_bf16 v[76:79], v[176:179], v[164:167], v[76:79]
	v_mfma_f32_16x16x32_bf16 v[72:75], v[180:183], v[164:167], v[72:75]
	v_mfma_f32_16x16x32_bf16 v[20:23], v[184:187], v[152:155], v[20:23]
	v_mfma_f32_16x16x32_bf16 v[16:19], v[188:191], v[152:155], v[16:19]
	v_mfma_f32_16x16x32_bf16 v[36:39], v[184:187], v[156:159], v[36:39]
	v_mfma_f32_16x16x32_bf16 v[32:35], v[188:191], v[156:159], v[32:35]
	v_mfma_f32_16x16x32_bf16 v[52:55], v[184:187], v[168:171], v[52:55]
	v_mfma_f32_16x16x32_bf16 v[48:51], v[188:191], v[168:171], v[48:51]
	v_mfma_f32_16x16x32_bf16 v[76:79], v[184:187], v[172:175], v[76:79]
	v_mfma_f32_16x16x32_bf16 v[72:75], v[188:191], v[172:175], v[72:75]
	s_barrier
	s_mov_b32 m0, s34
	ds_read_b128 v[144:147], v236 offset:16384
	ds_read_b128 v[148:151], v236 offset:18432
	ds_read_b128 v[152:155], v237 offset:16384
	ds_read_b128 v[156:159], v237 offset:18432
	ds_read_b128 v[160:163], v236 offset:20480
	ds_read_b128 v[164:167], v236 offset:22528
	ds_read_b128 v[168:171], v237 offset:20480
	ds_read_b128 v[172:175], v237 offset:22528
	s_add_u32 s80, s6, s46
	s_addc_u32 s81, s7, s47
	s_nop 0
	global_load_lds_dwordx4 v222, s[80:81]
	s_mov_b32 m0, s44
	s_nop 0
	s_add_u32 s80, s6, s48
	s_addc_u32 s81, s7, s49
	s_nop 0
	global_load_lds_dwordx4 v222, s[80:81]
	s_barrier
	s_waitcnt lgkmcnt(0)
	v_mfma_f32_16x16x32_bf16 v[100:103], v[8:11], v[144:147], v[100:103]
	v_mfma_f32_16x16x32_bf16 v[96:99], v[12:15], v[144:147], v[96:99]
	v_mfma_f32_16x16x32_bf16 v[132:135], v[8:11], v[148:151], v[132:135]
	v_mfma_f32_16x16x32_bf16 v[128:131], v[12:15], v[148:151], v[128:131]
	v_mfma_f32_16x16x32_bf16 v[124:127], v[8:11], v[160:163], v[124:127]
	v_mfma_f32_16x16x32_bf16 v[120:123], v[12:15], v[160:163], v[120:123]
	v_mfma_f32_16x16x32_bf16 v[100:103], v[136:139], v[152:155], v[100:103]
	v_mfma_f32_16x16x32_bf16 v[96:99], v[140:143], v[152:155], v[96:99]
	v_mfma_f32_16x16x32_bf16 v[132:135], v[136:139], v[156:159], v[132:135]
	v_mfma_f32_16x16x32_bf16 v[128:131], v[140:143], v[156:159], v[128:131]
	v_mfma_f32_16x16x32_bf16 v[124:127], v[136:139], v[168:171], v[124:127]
	v_mfma_f32_16x16x32_bf16 v[120:123], v[140:143], v[168:171], v[120:123]
	v_mfma_f32_16x16x32_bf16 v[8:11], v[8:11], v[164:167], v[88:91]
	v_mfma_f32_16x16x32_bf16 v[12:15], v[12:15], v[164:167], v[92:95]
	v_mfma_f32_16x16x32_bf16 v[8:11], v[136:139], v[172:175], v[8:11]
	v_mfma_f32_16x16x32_bf16 v[12:15], v[140:143], v[172:175], v[12:15]
	s_barrier
	s_mov_b32 m0, s45
	s_add_u32 s80, s4, s46
	s_addc_u32 s81, s5, s47
	s_nop 0
	global_load_lds_dwordx4 v222, s[80:81]
	s_mov_b32 m0, s62
	s_nop 0
	s_add_u32 s80, s4, s48
	s_addc_u32 s81, s5, s49
	s_nop 0
	global_load_lds_dwordx4 v222, s[80:81]
	s_waitcnt vmcnt(6)
	s_barrier
	v_mfma_f32_16x16x32_bf16 v[88:91], v[176:179], v[148:151], v[104:107]
	v_mfma_f32_16x16x32_bf16 v[80:83], v[176:179], v[144:147], v[80:83]
	v_mfma_f32_16x16x32_bf16 v[84:87], v[180:183], v[144:147], v[84:87]
	v_mfma_f32_16x16x32_bf16 v[104:107], v[184:187], v[156:159], v[88:91]
	v_mfma_f32_16x16x32_bf16 v[88:91], v[180:183], v[148:151], v[108:111]
	v_mfma_f32_16x16x32_bf16 v[56:59], v[176:179], v[160:163], v[56:59]
	v_mfma_f32_16x16x32_bf16 v[60:63], v[180:183], v[160:163], v[60:63]
	v_mfma_f32_16x16x32_bf16 v[0:3], v[176:179], v[164:167], v[0:3]
	v_mfma_f32_16x16x32_bf16 v[4:7], v[180:183], v[164:167], v[4:7]
	v_mfma_f32_16x16x32_bf16 v[80:83], v[184:187], v[152:155], v[80:83]
	v_mfma_f32_16x16x32_bf16 v[84:87], v[188:191], v[152:155], v[84:87]
	v_mfma_f32_16x16x32_bf16 v[108:111], v[188:191], v[156:159], v[88:91]
	v_mfma_f32_16x16x32_bf16 v[56:59], v[184:187], v[168:171], v[56:59]
	v_mfma_f32_16x16x32_bf16 v[60:63], v[188:191], v[168:171], v[60:63]
	v_mfma_f32_16x16x32_bf16 v[0:3], v[184:187], v[172:175], v[0:3]
	v_mfma_f32_16x16x32_bf16 v[4:7], v[188:191], v[172:175], v[4:7]
	s_barrier
	ds_read_b128 v[88:91], v240
	ds_read_b128 v[92:95], v240 offset:2048
	ds_read_b128 v[136:139], v241
	ds_read_b128 v[140:143], v241 offset:2048
	s_mov_b32 m0, s63
	ds_read_b128 v[144:147], v236 offset:32768
	ds_read_b128 v[148:151], v236 offset:34816
	ds_read_b128 v[152:155], v237 offset:32768
	ds_read_b128 v[156:159], v237 offset:34816
	ds_read_b128 v[160:163], v236 offset:36864
	ds_read_b128 v[164:167], v236 offset:38912
	ds_read_b128 v[168:171], v237 offset:36864
	ds_read_b128 v[172:175], v237 offset:38912
	s_add_u32 s80, s6, 0x80900
	s_addc_u32 s81, s7, 0x0
	s_nop 0
	global_load_lds_dwordx4 v222, s[80:81]
	s_mov_b32 m0, s64
	s_nop 0
	s_add_u32 s80, s6, 0xc0900
	s_addc_u32 s81, s7, 0x0
	s_nop 0
	global_load_lds_dwordx4 v222, s[80:81]
	s_waitcnt lgkmcnt(8)
	s_barrier
	s_waitcnt lgkmcnt(0)
	v_mfma_f32_16x16x32_bf16 v[28:31], v[88:91], v[144:147], v[28:31]
	v_mfma_f32_16x16x32_bf16 v[24:27], v[92:95], v[144:147], v[24:27]
	v_mfma_f32_16x16x32_bf16 v[44:47], v[88:91], v[148:151], v[44:47]
	v_mfma_f32_16x16x32_bf16 v[40:43], v[92:95], v[148:151], v[40:43]
	v_mfma_f32_16x16x32_bf16 v[68:71], v[88:91], v[160:163], v[68:71]
	v_mfma_f32_16x16x32_bf16 v[64:67], v[92:95], v[160:163], v[64:67]
	v_mfma_f32_16x16x32_bf16 v[116:119], v[88:91], v[164:167], v[116:119]
	v_mfma_f32_16x16x32_bf16 v[112:115], v[92:95], v[164:167], v[112:115]
	v_mfma_f32_16x16x32_bf16 v[28:31], v[136:139], v[152:155], v[28:31]
	v_mfma_f32_16x16x32_bf16 v[24:27], v[140:143], v[152:155], v[24:27]
	v_mfma_f32_16x16x32_bf16 v[44:47], v[136:139], v[156:159], v[44:47]
	v_mfma_f32_16x16x32_bf16 v[40:43], v[140:143], v[156:159], v[40:43]
	v_mfma_f32_16x16x32_bf16 v[68:71], v[136:139], v[168:171], v[68:71]
	v_mfma_f32_16x16x32_bf16 v[64:67], v[140:143], v[168:171], v[64:67]
	v_mfma_f32_16x16x32_bf16 v[116:119], v[136:139], v[172:175], v[116:119]
	v_mfma_f32_16x16x32_bf16 v[112:115], v[140:143], v[172:175], v[112:115]
	s_barrier
	s_mov_b32 m0, s65
	ds_read_b128 v[176:179], v242
	ds_read_b128 v[180:183], v242 offset:2048
	ds_read_b128 v[184:187], v243
	ds_read_b128 v[188:191], v243 offset:2048
	s_add_u32 s80, s60, s50
	s_addc_u32 s81, s61, s51
	s_nop 0
	global_load_lds_dwordx4 v222, s[80:81]
	s_mov_b32 m0, s68
	s_nop 0
	s_add_u32 s80, s60, s58
	s_addc_u32 s81, s61, s59
	s_nop 0
	global_load_lds_dwordx4 v222, s[80:81]
	s_waitcnt lgkmcnt(0)
	s_barrier
	v_mfma_f32_16x16x32_bf16 v[20:23], v[176:179], v[144:147], v[20:23]
	v_mfma_f32_16x16x32_bf16 v[16:19], v[180:183], v[144:147], v[16:19]
	v_mfma_f32_16x16x32_bf16 v[36:39], v[176:179], v[148:151], v[36:39]
	v_mfma_f32_16x16x32_bf16 v[32:35], v[180:183], v[148:151], v[32:35]
	v_mfma_f32_16x16x32_bf16 v[52:55], v[176:179], v[160:163], v[52:55]
	v_mfma_f32_16x16x32_bf16 v[48:51], v[180:183], v[160:163], v[48:51]
	v_mfma_f32_16x16x32_bf16 v[76:79], v[176:179], v[164:167], v[76:79]
	v_mfma_f32_16x16x32_bf16 v[72:75], v[180:183], v[164:167], v[72:75]
	v_mfma_f32_16x16x32_bf16 v[20:23], v[184:187], v[152:155], v[20:23]
	v_mfma_f32_16x16x32_bf16 v[16:19], v[188:191], v[152:155], v[16:19]
	v_mfma_f32_16x16x32_bf16 v[36:39], v[184:187], v[156:159], v[36:39]
	v_mfma_f32_16x16x32_bf16 v[32:35], v[188:191], v[156:159], v[32:35]
	v_mfma_f32_16x16x32_bf16 v[52:55], v[184:187], v[168:171], v[52:55]
	v_mfma_f32_16x16x32_bf16 v[48:51], v[188:191], v[168:171], v[48:51]
	v_mfma_f32_16x16x32_bf16 v[76:79], v[184:187], v[172:175], v[76:79]
	v_mfma_f32_16x16x32_bf16 v[72:75], v[188:191], v[172:175], v[72:75]
	s_barrier
	s_mov_b32 m0, s69
	ds_read_b128 v[144:147], v236 offset:49152
	ds_read_b128 v[148:151], v236 offset:51200
	ds_read_b128 v[152:155], v237 offset:49152
	ds_read_b128 v[156:159], v237 offset:51200
	ds_read_b128 v[160:163], v236 offset:53248
	ds_read_b128 v[164:167], v236 offset:55296
	ds_read_b128 v[168:171], v237 offset:53248
	ds_read_b128 v[172:175], v237 offset:55296
	s_add_u32 s80, s6, s50
	s_addc_u32 s81, s7, s51
	s_nop 0
	global_load_lds_dwordx4 v222, s[80:81]
	s_mov_b32 m0, s70
	s_nop 0
	s_add_u32 s80, s6, s58
	s_addc_u32 s81, s7, s59
	s_nop 0
	global_load_lds_dwordx4 v222, s[80:81]
	s_barrier
	s_waitcnt lgkmcnt(0)
	v_mfma_f32_16x16x32_bf16 v[8:11], v[88:91], v[164:167], v[8:11]
	v_mfma_f32_16x16x32_bf16 v[100:103], v[88:91], v[144:147], v[100:103]
	v_mfma_f32_16x16x32_bf16 v[96:99], v[92:95], v[144:147], v[96:99]
	v_mfma_f32_16x16x32_bf16 v[132:135], v[88:91], v[148:151], v[132:135]
	v_mfma_f32_16x16x32_bf16 v[128:131], v[92:95], v[148:151], v[128:131]
	v_mfma_f32_16x16x32_bf16 v[124:127], v[88:91], v[160:163], v[124:127]
	v_mfma_f32_16x16x32_bf16 v[120:123], v[92:95], v[160:163], v[120:123]
	v_mfma_f32_16x16x32_bf16 v[88:91], v[136:139], v[172:175], v[8:11]
	v_mfma_f32_16x16x32_bf16 v[8:11], v[92:95], v[164:167], v[12:15]
	v_mfma_f32_16x16x32_bf16 v[100:103], v[136:139], v[152:155], v[100:103]
	v_mfma_f32_16x16x32_bf16 v[96:99], v[140:143], v[152:155], v[96:99]
	v_mfma_f32_16x16x32_bf16 v[132:135], v[136:139], v[156:159], v[132:135]
	v_mfma_f32_16x16x32_bf16 v[128:131], v[140:143], v[156:159], v[128:131]
	v_mfma_f32_16x16x32_bf16 v[124:127], v[136:139], v[168:171], v[124:127]
	v_mfma_f32_16x16x32_bf16 v[120:123], v[140:143], v[168:171], v[120:123]
	v_mfma_f32_16x16x32_bf16 v[92:95], v[140:143], v[172:175], v[8:11]
	s_barrier
	s_mov_b32 m0, s71
	s_add_u32 s80, s4, s50
	s_addc_u32 s81, s5, s51
	s_nop 0
	global_load_lds_dwordx4 v222, s[80:81]
	s_mov_b32 m0, s72
	s_nop 0
	s_add_u32 s80, s4, s58
	s_addc_u32 s81, s5, s59
	s_nop 0
	global_load_lds_dwordx4 v222, s[80:81]
	s_waitcnt vmcnt(6)
	s_barrier
	v_mfma_f32_16x16x32_bf16 v[8:11], v[176:179], v[144:147], v[80:83]
	v_mfma_f32_16x16x32_bf16 v[80:83], v[184:187], v[152:155], v[8:11]
	v_mfma_f32_16x16x32_bf16 v[8:11], v[180:183], v[144:147], v[84:87]
	v_mfma_f32_16x16x32_bf16 v[84:87], v[188:191], v[152:155], v[8:11]
	v_mfma_f32_16x16x32_bf16 v[8:11], v[176:179], v[148:151], v[104:107]
	v_mfma_f32_16x16x32_bf16 v[104:107], v[184:187], v[156:159], v[8:11]
	v_mfma_f32_16x16x32_bf16 v[8:11], v[180:183], v[148:151], v[108:111]
	v_mfma_f32_16x16x32_bf16 v[108:111], v[188:191], v[156:159], v[8:11]
	v_mfma_f32_16x16x32_bf16 v[8:11], v[176:179], v[160:163], v[56:59]
	v_mfma_f32_16x16x32_bf16 v[56:59], v[184:187], v[168:171], v[8:11]
	v_mfma_f32_16x16x32_bf16 v[8:11], v[180:183], v[160:163], v[60:63]
	v_mfma_f32_16x16x32_bf16 v[0:3], v[176:179], v[164:167], v[0:3]
	v_mfma_f32_16x16x32_bf16 v[4:7], v[180:183], v[164:167], v[4:7]
	v_mfma_f32_16x16x32_bf16 v[60:63], v[188:191], v[168:171], v[8:11]
	v_mfma_f32_16x16x32_bf16 v[0:3], v[184:187], v[172:175], v[0:3]
	v_mfma_f32_16x16x32_bf16 v[4:7], v[188:191], v[172:175], v[4:7]
	s_barrier
; #define LDA(dst,b,h) _Pragma("unroll") for(int m=0;m<4;++m) _Pragma("unroll") for(int k=0;k<2;++k) \
;     dst[m][k]=*reinterpret_cast<const bf16x8*>(SA(b,h)+(wr*64+m*16)*128+koff[k])
; #define LDB(dst,b,h) _Pragma("unroll") for(int n=0;n<2;++n) _Pragma("unroll") for(int k=0;k<2;++k) \
;     dst[n][k]=*reinterpret_cast<const bf16x8*>(SB(b,h)+(wc*32+n*16)*128+koff[k])
; #define MMA(ai,bj,Af,Bf) do{__builtin_amdgcn_s_setprio(1); \
;     _Pragma("unroll") for(int m=0;m<4;++m) _Pragma("unroll") for(int n=0;n<2;++n) _Pragma("unroll") for(int k=0;k<2;++k) \
;       acc[ai][bj][m][n]=__builtin_amdgcn_mfma_f32_16x16x32_bf16(Bf[n][k],Af[m][k],acc[ai][bj][m][n],0,0,0); \
;     __builtin_amdgcn_s_setprio(0);}while(0)
; #define WAIT_V(n) asm volatile("s_waitcnt vmcnt(" #n ")":::"memory")
; #define WAIT_L(n) asm volatile("s_waitcnt lgkmcnt(" #n ")":::"memory")
; #define BAR __builtin_amdgcn_s_barrier()
; template <int K, int EPI, bool MIX = false>
; __device__ __forceinline__ void gemm_phase(const Params& p, const u16* __restrict__ A, const u16* __restrict__ Bt,
;                            const float* __restrict__ rs_in, float* __restrict__ ssq_out, float alpha, bool rev = false) {
;     ...
;     if constexpr (EPI == EPI_SWIGLU || EPI == EPI_Z || MIX) {
;       const float* rsrc = MIX ? p.ssqb : rs_in;
;       int fr_p = fr;
;       asm volatile("" : "+v"(fr_p));
; #pragma unroll
;       for (int ai = 0; ai < 2; ++ai)
; #pragma unroll
;         for (int m = 0; m < 4; ++m) rsq[ai][m] = rsrc[cpm * 256 + ai * 128 + wr * 64 + m * 16 + fr_p];
;     }
;     ++it;
;     id = item_id(it);
;     const bool more = id < ntiles;
;     if (rev) id = ntiles - 1 - id;
;     {
;       LDB(B0,0,0); SCHED; LDA(At,0,0); STAGE_A(1,1,nt-1);
;       WAIT_L(8); BAR; WAIT_L(0); MMA(0,0,At,B0); BAR; SCHED;
;       if (more) SETUP_TILE();
;       LDB(B1,0,1); if (more) STAGE_B(0,0,0);
;       BAR; WAIT_L(0); MMA(0,1,At,B1); BAR;
;       LDA(At,0,1); if (more) STAGE_A(0,0,0);
;       BAR; WAIT_L(0); MMA(1,0,At,B0); BAR; SCHED;
;       if (more) { STAGE_B(0,1,0); WAIT_V(6); } else { WAIT_V(0); }
;       BAR; MMA(1,1,At,B1); BAR;
;       LDB(B0,1,0); SCHED; LDA(At,1,0); if (more) STAGE_A(0,1,0);
;       WAIT_L(8); BAR; WAIT_L(0); MMA(0,0,At,B0); BAR; SCHED;
;       LDB(B1,1,1); if (more) STAGE_B(1,0,1);
;       BAR; WAIT_L(0); MMA(0,1,At,B1); BAR;
;       LDA(At,1,1); if (more) STAGE_A(1,0,1);
	s_add_i32 s33, s33, 2
	s_add_u32 s60, s60, 0x100
	s_addc_u32 s61, s61, 0
	s_add_u32 s6, s6, 0x100
	s_addc_u32 s7, s7, 0
	s_add_u32 s4, s4, 0x100
	s_addc_u32 s5, s5, 0
	s_cmp_lt_u32 s33, 28
	s_cbranch_scc1 .LBB0_367
	v_mov_b32_e32 v8, v233
	s_add_i32 s77, s77, 1
	v_add_u32_e32 v8, s79, v8
	v_ashrrev_i32_e32 v9, 31, v8
	v_lshl_add_u64 v[8:9], v[8:9], 2, s[88:89]
	global_load_dword v253, v[8:9], off
	global_load_dword v252, v[8:9], off offset:64
	global_load_dword v251, v[8:9], off offset:128
	global_load_dword v250, v[8:9], off offset:192
	global_load_dword v249, v[8:9], off offset:512
	global_load_dword v248, v[8:9], off offset:576
	global_load_dword v247, v[8:9], off offset:640
	global_load_dword v246, v[8:9], off offset:704
	ds_read_b128 v[136:139], v234
	ds_read_b128 v[140:143], v234 offset:2048
	ds_read_b128 v[148:151], v235
	ds_read_b128 v[144:147], v235 offset:2048
	s_mul_i32 s4, s77, s57
	s_add_i32 s4, s4, s56
	v_lshl_add_u64 v[8:9], s[8:9], 0, v[220:221]
	s_mov_b64 s[6:7], 0x80f80
	s_mov_b32 m0, s74
	v_lshl_add_u64 v[10:11], v[8:9], 0, s[6:7]
	s_mov_b64 s[6:7], 0xc0f80
	ds_read_b128 v[176:179], v236
	ds_read_b128 v[164:167], v236 offset:2048
	ds_read_b128 v[180:183], v237
	ds_read_b128 v[168:171], v237 offset:2048
	ds_read_b128 v[152:155], v236 offset:4096
	ds_read_b128 v[156:159], v236 offset:6144
	ds_read_b128 v[172:175], v237 offset:4096
	ds_read_b128 v[160:163], v237 offset:6144
	global_load_lds_dwordx4 v[10:11], off
	v_lshl_add_u64 v[8:9], v[8:9], 0, s[6:7]
	s_mov_b32 m0, s75
	s_nop 0
	global_load_lds_dwordx4 v[8:9], off
	s_waitcnt lgkmcnt(8)
	s_barrier
	s_waitcnt lgkmcnt(0)
	v_mfma_f32_16x16x32_bf16 v[8:11], v[136:139], v[176:179], v[28:31]
	s_cmpk_lt_i32 s4, 0x600
	s_cselect_b64 s[6:7], -1, 0
	s_cmpk_gt_i32 s4, 0x5ff
	v_mfma_f32_16x16x32_bf16 v[12:15], v[140:143], v[176:179], v[24:27]
	v_mfma_f32_16x16x32_bf16 v[24:27], v[136:139], v[164:167], v[44:47]
	v_mfma_f32_16x16x32_bf16 v[28:31], v[140:143], v[164:167], v[40:43]
	v_mfma_f32_16x16x32_bf16 v[40:43], v[136:139], v[152:155], v[68:71]
	v_mfma_f32_16x16x32_bf16 v[44:47], v[140:143], v[152:155], v[64:67]
	v_mfma_f32_16x16x32_bf16 v[64:67], v[136:139], v[156:159], v[116:119]
	v_mfma_f32_16x16x32_bf16 v[68:71], v[140:143], v[156:159], v[112:115]
	v_mfma_f32_16x16x32_bf16 v[8:11], v[148:151], v[180:183], v[8:11]
	v_mfma_f32_16x16x32_bf16 v[12:15], v[144:147], v[180:183], v[12:15]
	v_mfma_f32_16x16x32_bf16 v[24:27], v[148:151], v[168:171], v[24:27]
	v_mfma_f32_16x16x32_bf16 v[28:31], v[144:147], v[168:171], v[28:31]
	v_mfma_f32_16x16x32_bf16 v[40:43], v[148:151], v[172:175], v[40:43]
	v_mfma_f32_16x16x32_bf16 v[44:47], v[144:147], v[172:175], v[44:47]
	v_mfma_f32_16x16x32_bf16 v[64:67], v[148:151], v[160:163], v[64:67]
	v_mfma_f32_16x16x32_bf16 v[68:71], v[144:147], v[160:163], v[68:71]
	s_barrier
	s_mov_b32 s33, s78
	s_cbranch_scc1 .LBB0_370
	s_ashr_i32 s5, s4, 31
	s_lshr_b32 s5, s5, 26
	s_add_i32 s5, s4, s5
	s_ashr_i32 s8, s5, 6
	s_andn2_b32 s5, s5, 63
	s_lshl_b32 s8, s8, 3
	s_sub_i32 s5, s4, s5
	s_and_b32 s4, s4, 7
	s_or_b32 s35, s8, s4
	s_lshl_b32 s4, s35, 8
	s_ashr_i32 s33, s5, 3
	s_ashr_i32 s5, s4, 31
	s_lshl_b64 s[4:5], s[4:5], 12
	s_add_u32 s8, s94, s4
	s_addc_u32 s9, s95, s5
	s_lshl_b32 s4, s33, 8
	s_ashr_i32 s5, s4, 31
	s_lshl_b64 s[4:5], s[4:5], 12
	v_readlane_b32 s80, v254, 32
	v_readlane_b32 s81, v254, 33
	s_add_u32 s12, s80, s4
	v_readlane_b32 s84, v254, 36
	v_readlane_b32 s85, v254, 37
	v_readlane_b32 s86, v254, 38
	v_readlane_b32 s87, v254, 39
	v_readlane_b32 s88, v254, 40
	v_readlane_b32 s89, v254, 41
	v_readlane_b32 s90, v254, 42
	v_readlane_b32 s91, v254, 43
	s_addc_u32 s13, s81, s5
	v_readlane_b32 s84, v254, 0
	s_add_u32 s16, s12, 0x80000
	v_readlane_b32 s90, v254, 6
	v_readlane_b32 s91, v254, 7
	s_addc_u32 s17, s13, 0
	v_readlane_b32 s82, v254, 34
	v_readlane_b32 s83, v254, 35
	v_readlane_b32 s92, v254, 44
	v_readlane_b32 s93, v254, 45
	v_readlane_b32 s94, v254, 46
	v_readlane_b32 s95, v254, 47
	v_readlane_b32 s85, v254, 1
	v_readlane_b32 s86, v254, 2
	v_readlane_b32 s87, v254, 3
	v_readlane_b32 s88, v254, 4
	v_readlane_b32 s89, v254, 5

; template <int K, int EPI, bool MIX = false>
; __device__ __forceinline__ void gemm_phase(const Params& p, const u16* __restrict__ A, const u16* __restrict__ Bt,
;                            const float* __restrict__ rs_in, float* __restrict__ ssq_out, float alpha, bool rev = false) {
;     ...
; #pragma unroll
;       for (int ai = 0; ai < 2; ++ai)
; #pragma unroll
;         for (int m = 0; m < 4; ++m) {
;           int row = brow + ai * 128 + wr * 64 + m * 16 + fr_e;
;           float al = alpha;
;           if constexpr (MIX) al = rsqrtf(rsq[ai][m] * (1.f / 1024.f) + 1e-6f);
;           float ss = 0.f;
; #pragma unroll
;           for (int bj = 0; bj < 2; ++bj) {
;             const f32x4 a0 = acc[ai][bj][m][0], a1 = acc[ai][bj][m][1];
;             float lo[4], hi[4];
; #pragma unroll
;             for (int j = 0; j < 4; ++j) {
;               auto sw = __builtin_amdgcn_permlane32_swap(__float_as_uint(a0[j]), __float_as_uint(a1[j]), false, false);
;               lo[j] = __uint_as_float(sw[0]); hi[j] = __uint_as_float(sw[1]);
;             }
;             u16* ptr = p.Abuf + (size_t)row * DM + bcol + wc * 32 + bj * 128 + wn16;
;             const uint4 r = *(const uint4*)ptr;
;             const float x0 = __uint_as_float(r.x << 16) + al * lo[0], x1 = __uint_as_float(r.x & 0xffff0000u) + al * lo[1];
;             const float x2 = __uint_as_float(r.y << 16) + al * lo[2], x3 = __uint_as_float(r.y & 0xffff0000u) + al * lo[3];
;             const float x4 = __uint_as_float(r.z << 16) + al * hi[0], x5 = __uint_as_float(r.z & 0xffff0000u) + al * hi[1];
;             const float x6 = __uint_as_float(r.w << 16) + al * hi[2], x7 = __uint_as_float(r.w & 0xffff0000u) + al * hi[3];
;             ss += x0 * x0 + x1 * x1 + x2 * x2 + x3 * x3 + x4 * x4 + x5 * x5 + x6 * x6 + x7 * x7;
;             *(uint4*)ptr = uint4{pk2(x0, x1), pk2(x2, x3), pk2(x4, x5), pk2(x6, x7)};
;           }
;           ss += __shfl_xor(ss, 16, 64);
;           ss += __shfl_xor(ss, 32, 64);
;           if (fq_e == 0) atomicAdd(ssq_out + row, ss);
.LBB0_388:
	v_and_b32_e32 v133, 64, v245
	v_xor_b32_e32 v132, 16, v245
	v_add_u32_e32 v133, 64, v133
	v_cmp_lt_i32_e32 vcc, v132, v133
	v_mov_b32_e32 v131, v232
	s_lshl_b32 s60, s78, 8
	v_cndmask_b32_e32 v132, v245, v132, vcc
	v_lshlrev_b32_e32 v136, 2, v132
	v_xor_b32_e32 v132, 32, v245
	v_cmp_lt_i32_e32 vcc, v132, v133
	v_ashrrev_i32_e32 v128, 1, v131
	v_lshrrev_b32_e32 v129, 1, v131
	v_and_or_b32 v130, v131, 15, s79
	v_cndmask_b32_e32 v132, v245, v132, vcc
	v_cmp_gt_u32_e32 vcc, 16, v131
	s_waitcnt vmcnt(6)
	v_fmamk_f32 v131, v253, 0x3a800000, v244
	v_lshlrev_b32_e32 v133, 2, v132
	v_cmp_gt_f32_e64 s[6:7], s76, v131
	v_mul_f32_e32 v132, 0x4b800000, v131
	v_and_b32_e32 v129, 8, v129
	v_cndmask_b32_e64 v131, v131, v132, s[6:7]
	v_rsq_f32_e32 v131, v131
	s_ashr_i32 s61, s60, 31
	v_and_or_b32 v128, v128, -16, v129
	v_ashrrev_i32_e32 v129, 31, v128
	v_mul_f32_e32 v132, 0x45800000, v131
	v_cndmask_b32_e64 v132, v131, v132, s[6:7]
	v_ashrrev_i32_e32 v131, 31, v130
	v_lshlrev_b64 v[134:135], 12, v[130:131]
	v_lshl_add_u64 v[134:135], s[90:91], 0, v[134:135]
	v_lshl_add_u64 v[134:135], s[60:61], 1, v[134:135]
	v_lshl_add_u64 v[134:135], v[134:135], 0, s[28:29]
	v_lshl_add_u64 v[134:135], v[128:129], 1, v[134:135]
	global_load_dwordx4 v[138:141], v[134:135], off
	global_load_dwordx4 v[152:155], v[134:135], off offset:256
	v_mov_b32_e32 v213, 0
	v_mov_b32_e32 v212, 0x10000
	v_lshl_add_u64 v[214:215], v[212:213], 0, v[134:135]
	global_load_dwordx4 v[156:159], v[214:215], off
	global_load_dwordx4 v[160:163], v[214:215], off offset:256
	v_mov_b32_e32 v212, 0x20000
	v_lshl_add_u64 v[214:215], v[212:213], 0, v[134:135]
	global_load_dwordx4 v[164:167], v[214:215], off
	global_load_dwordx4 v[168:171], v[214:215], off offset:256
	v_mov_b32_e32 v212, 0x30000
	v_lshl_add_u64 v[214:215], v[212:213], 0, v[134:135]
	global_load_dwordx4 v[172:175], v[214:215], off
	global_load_dwordx4 v[176:179], v[214:215], off offset:256
	v_mov_b32_e32 v212, 0x80000
	v_lshl_add_u64 v[214:215], v[212:213], 0, v[134:135]
	global_load_dwordx4 v[180:183], v[214:215], off
	global_load_dwordx4 v[184:187], v[214:215], off offset:256
	v_mov_b32_e32 v212, 0x90000
	v_lshl_add_u64 v[214:215], v[212:213], 0, v[134:135]
	global_load_dwordx4 v[188:191], v[214:215], off
	global_load_dwordx4 v[192:195], v[214:215], off offset:256
	v_mov_b32_e32 v212, 0xa0000
	v_lshl_add_u64 v[214:215], v[212:213], 0, v[134:135]
	global_load_dwordx4 v[196:199], v[214:215], off
	global_load_dwordx4 v[200:203], v[214:215], off offset:256
	v_mov_b32_e32 v212, 0xb0000
	v_lshl_add_u64 v[214:215], v[212:213], 0, v[134:135]
	global_load_dwordx4 v[204:207], v[214:215], off
	global_load_dwordx4 v[208:211], v[214:215], off offset:256
	v_permlane32_swap_b32_e32 v124, v120
	v_permlane32_swap_b32_e32 v125, v121
	v_permlane32_swap_b32_e32 v126, v122
	v_permlane32_swap_b32_e32 v127, v123
	v_permlane32_swap_b32_e32 v118, v114
	v_permlane32_swap_b32_e32 v119, v115
	v_permlane32_swap_b32_e32 v116, v112
	v_permlane32_swap_b32_e32 v117, v113
	v_readlane_b32 s80, v254, 32
	v_readlane_b32 s94, v254, 46
	v_readlane_b32 s95, v254, 47
	v_readlane_b32 s81, v254, 33
	v_readlane_b32 s82, v254, 34
	v_readlane_b32 s83, v254, 35
	v_readlane_b32 s84, v254, 36
	v_readlane_b32 s85, v254, 37
	v_readlane_b32 s86, v254, 38
	v_readlane_b32 s87, v254, 39
	v_readlane_b32 s88, v254, 40
	v_readlane_b32 s89, v254, 41
	v_readlane_b32 s90, v254, 42
	v_readlane_b32 s91, v254, 43
	v_readlane_b32 s92, v254, 44
	v_readlane_b32 s93, v254, 45
	s_waitcnt vmcnt(15)
	v_lshlrev_b32_e32 v142, 16, v138
	v_and_b32_e32 v143, 0xffff0000, v138
	v_pk_fma_f32 v[142:143], v[132:133], v[124:125], v[142:143] op_sel_hi:[0,1,1]
	v_lshlrev_b32_e32 v124, 16, v139
	v_and_b32_e32 v125, 0xffff0000, v139
	v_pk_fma_f32 v[144:145], v[132:133], v[126:127], v[124:125] op_sel_hi:[0,1,1]
	v_lshlrev_b32_e32 v124, 16, v140
	v_and_b32_e32 v125, 0xffff0000, v140
	v_pk_fma_f32 v[146:147], v[132:133], v[120:121], v[124:125] op_sel_hi:[0,1,1]
	v_lshlrev_b32_e32 v120, 16, v141
	v_and_b32_e32 v121, 0xffff0000, v141
	v_pk_fma_f32 v[148:149], v[132:133], v[122:123], v[120:121] op_sel_hi:[0,1,1]
	v_cvt_pk_bf16_f32 v138, v142, v143
	v_cvt_pk_bf16_f32 v139, v144, v145
	v_cvt_pk_bf16_f32 v140, v146, v147
	v_cvt_pk_bf16_f32 v141, v148, v149
	global_store_dwordx4 v[134:135], v[138:141], off
	v_pk_mul_f32 v[126:127], v[142:143], v[142:143]
	v_pk_mul_f32 v[124:125], v[144:145], v[144:145]
	v_pk_mul_f32 v[122:123], v[146:147], v[146:147]
	v_pk_mul_f32 v[120:121], v[148:149], v[148:149]
	s_waitcnt vmcnt(15)
	v_lshlrev_b32_e32 v142, 16, v152
	v_and_b32_e32 v143, 0xffff0000, v152
	v_lshlrev_b32_e32 v138, 16, v153
	v_and_b32_e32 v139, 0xffff0000, v153
	v_pk_fma_f32 v[118:119], v[132:133], v[118:119], v[138:139] op_sel_hi:[0,1,1]
	v_lshlrev_b32_e32 v138, 16, v154
	v_and_b32_e32 v139, 0xffff0000, v154
	v_pk_fma_f32 v[116:117], v[132:133], v[116:117], v[142:143] op_sel_hi:[0,1,1]
	v_pk_fma_f32 v[138:139], v[132:133], v[112:113], v[138:139] op_sel_hi:[0,1,1]
	v_lshlrev_b32_e32 v112, 16, v155
	v_and_b32_e32 v113, 0xffff0000, v155
	v_pk_fma_f32 v[140:141], v[132:133], v[114:115], v[112:113] op_sel_hi:[0,1,1]
	v_pk_mul_f32 v[112:113], v[116:117], v[116:117]
	v_pk_mul_f32 v[114:115], v[118:119], v[118:119]
	v_add_f32_e32 v112, v112, v113
	v_add_f32_e32 v113, v126, v127
	v_add_f32_e32 v112, v112, v114
	v_add_f32_e32 v113, v113, v124
	v_pk_mul_f32 v[142:143], v[138:139], v[138:139]
	v_add_f32_e32 v112, v115, v112
	v_add_f32_e32 v113, v125, v113
	v_add_f32_e32 v112, v142, v112
	v_add_f32_e32 v113, v122, v113
	v_pk_mul_f32 v[144:145], v[140:141], v[140:141]
	v_add_f32_e32 v112, v143, v112
	v_add_f32_e32 v113, v123, v113
	v_add_f32_e32 v112, v144, v112
	v_add_f32_e32 v113, v120, v113
	v_add_f32_e32 v112, v145, v112
	v_add_f32_e32 v113, v121, v113
	v_add_f32_e32 v120, v113, v112
	v_cvt_pk_bf16_f32 v112, v116, v117
	v_cvt_pk_bf16_f32 v113, v118, v119
	v_cvt_pk_bf16_f32 v114, v138, v139
	v_cvt_pk_bf16_f32 v115, v140, v141
	global_store_dwordx4 v[134:135], v[112:115], off offset:256
	ds_bpermute_b32 v112, v136, v120
	s_waitcnt lgkmcnt(0)
	v_add_f32_e32 v114, v120, v112
	ds_bpermute_b32 v115, v133, v114
	v_lshl_add_u64 v[112:113], v[130:131], 2, s[94:95]
	s_and_saveexec_b64 s[6:7], vcc
	s_cbranch_execz .LBB0_390
	s_waitcnt lgkmcnt(0)
	v_add_f32_e32 v114, v114, v115
	global_atomic_add_f32 v[112:113], v114, off

.Llate_p6_done:
.LBB0_423:
	ds_read_b128 v[128:131], v224
	ds_read_b128 v[132:135], v224 offset:2048
	ds_read_b128 v[136:139], v225
	ds_read_b128 v[140:143], v225 offset:2048
	s_mov_b32 m0, s72
	ds_read_b128 v[144:147], v226
	ds_read_b128 v[148:151], v226 offset:2048
	ds_read_b128 v[152:155], v227
	ds_read_b128 v[156:159], v227 offset:2048
	ds_read_b128 v[160:163], v226 offset:4096
	ds_read_b128 v[164:167], v226 offset:6144
	ds_read_b128 v[168:171], v227 offset:4096
	ds_read_b128 v[172:175], v227 offset:6144
	s_add_u32 s96, s52, s24
	s_addc_u32 s97, s53, s25
	s_nop 0
	global_load_lds_dwordx4 v216, s[96:97]
	s_mov_b32 m0, s73
	s_nop 0
	s_add_u32 s96, s52, s26
	s_addc_u32 s97, s53, s27
	s_nop 0
	global_load_lds_dwordx4 v216, s[96:97]
	s_waitcnt lgkmcnt(8)
	s_barrier
	s_waitcnt lgkmcnt(0)
	v_mfma_f32_16x16x32_bf16 v[124:127], v[128:131], v[144:147], v[124:127]
	v_mfma_f32_16x16x32_bf16 v[120:123], v[132:135], v[144:147], v[120:123]
	v_mfma_f32_16x16x32_bf16 v[116:119], v[128:131], v[148:151], v[116:119]
	v_mfma_f32_16x16x32_bf16 v[112:115], v[132:135], v[148:151], v[112:115]
	v_mfma_f32_16x16x32_bf16 v[108:111], v[128:131], v[160:163], v[108:111]
	v_mfma_f32_16x16x32_bf16 v[104:107], v[132:135], v[160:163], v[104:107]
	v_mfma_f32_16x16x32_bf16 v[100:103], v[128:131], v[164:167], v[100:103]
	v_mfma_f32_16x16x32_bf16 v[96:99], v[132:135], v[164:167], v[96:99]
	v_mfma_f32_16x16x32_bf16 v[124:127], v[136:139], v[152:155], v[124:127]
	v_mfma_f32_16x16x32_bf16 v[120:123], v[140:143], v[152:155], v[120:123]
	v_mfma_f32_16x16x32_bf16 v[116:119], v[136:139], v[156:159], v[116:119]
	v_mfma_f32_16x16x32_bf16 v[112:115], v[140:143], v[156:159], v[112:115]
	v_mfma_f32_16x16x32_bf16 v[108:111], v[136:139], v[168:171], v[108:111]
	v_mfma_f32_16x16x32_bf16 v[104:107], v[140:143], v[168:171], v[104:107]
	v_mfma_f32_16x16x32_bf16 v[100:103], v[136:139], v[172:175], v[100:103]
	v_mfma_f32_16x16x32_bf16 v[96:99], v[140:143], v[172:175], v[96:99]
	s_barrier
	s_mov_b32 m0, s35
	ds_read_b128 v[176:179], v228
	ds_read_b128 v[180:183], v228 offset:2048
	ds_read_b128 v[184:187], v229
	ds_read_b128 v[188:191], v229 offset:2048
	s_add_u32 s96, s58, s28
	s_addc_u32 s97, s59, s29
	s_nop 0
	global_load_lds_dwordx4 v216, s[96:97]
	s_mov_b32 m0, s42
	s_nop 0
	s_add_u32 s96, s58, s30
	s_addc_u32 s97, s59, s31
	s_nop 0
	global_load_lds_dwordx4 v216, s[96:97]
	s_waitcnt lgkmcnt(0)
	s_barrier
	v_mfma_f32_16x16x32_bf16 v[92:95], v[176:179], v[144:147], v[92:95]
	v_mfma_f32_16x16x32_bf16 v[88:91], v[180:183], v[144:147], v[88:91]
	v_mfma_f32_16x16x32_bf16 v[84:87], v[176:179], v[148:151], v[84:87]
	v_mfma_f32_16x16x32_bf16 v[80:83], v[180:183], v[148:151], v[80:83]
	v_mfma_f32_16x16x32_bf16 v[76:79], v[176:179], v[160:163], v[76:79]
	v_mfma_f32_16x16x32_bf16 v[72:75], v[180:183], v[160:163], v[72:75]
	v_mfma_f32_16x16x32_bf16 v[68:71], v[176:179], v[164:167], v[68:71]
	v_mfma_f32_16x16x32_bf16 v[64:67], v[180:183], v[164:167], v[64:67]
	v_mfma_f32_16x16x32_bf16 v[92:95], v[184:187], v[152:155], v[92:95]
	v_mfma_f32_16x16x32_bf16 v[88:91], v[188:191], v[152:155], v[88:91]
	v_mfma_f32_16x16x32_bf16 v[84:87], v[184:187], v[156:159], v[84:87]
	v_mfma_f32_16x16x32_bf16 v[80:83], v[188:191], v[156:159], v[80:83]
	v_mfma_f32_16x16x32_bf16 v[76:79], v[184:187], v[168:171], v[76:79]
	v_mfma_f32_16x16x32_bf16 v[72:75], v[188:191], v[168:171], v[72:75]
	v_mfma_f32_16x16x32_bf16 v[68:71], v[184:187], v[172:175], v[68:71]
	v_mfma_f32_16x16x32_bf16 v[64:67], v[188:191], v[172:175], v[64:67]
	s_barrier
	s_mov_b32 m0, s33
	ds_read_b128 v[144:147], v226 offset:16384
	ds_read_b128 v[148:151], v226 offset:18432
	ds_read_b128 v[152:155], v227 offset:16384
	ds_read_b128 v[156:159], v227 offset:18432
	ds_read_b128 v[160:163], v226 offset:20480
	ds_read_b128 v[164:167], v226 offset:22528
	ds_read_b128 v[168:171], v227 offset:20480
	ds_read_b128 v[172:175], v227 offset:22528
	s_add_u32 s96, s52, s28
	s_addc_u32 s97, s53, s29
	s_nop 0
	global_load_lds_dwordx4 v216, s[96:97]
	s_mov_b32 m0, s43
	s_nop 0
	s_add_u32 s96, s52, s30
	s_addc_u32 s97, s53, s31
	s_nop 0
	global_load_lds_dwordx4 v216, s[96:97]
	s_barrier
	s_waitcnt lgkmcnt(0)
	v_mfma_f32_16x16x32_bf16 v[28:31], v[128:131], v[144:147], v[28:31]
	v_mfma_f32_16x16x32_bf16 v[24:27], v[132:135], v[144:147], v[24:27]
	v_mfma_f32_16x16x32_bf16 v[20:23], v[128:131], v[148:151], v[20:23]
	v_mfma_f32_16x16x32_bf16 v[16:19], v[132:135], v[148:151], v[16:19]
	v_mfma_f32_16x16x32_bf16 v[12:15], v[128:131], v[160:163], v[12:15]
	v_mfma_f32_16x16x32_bf16 v[8:11], v[132:135], v[160:163], v[8:11]
	v_mfma_f32_16x16x32_bf16 v[4:7], v[128:131], v[164:167], v[4:7]
	v_mfma_f32_16x16x32_bf16 v[0:3], v[132:135], v[164:167], v[0:3]
	v_mfma_f32_16x16x32_bf16 v[28:31], v[136:139], v[152:155], v[28:31]
	v_mfma_f32_16x16x32_bf16 v[24:27], v[140:143], v[152:155], v[24:27]
	v_mfma_f32_16x16x32_bf16 v[20:23], v[136:139], v[156:159], v[20:23]
	v_mfma_f32_16x16x32_bf16 v[16:19], v[140:143], v[156:159], v[16:19]
	v_mfma_f32_16x16x32_bf16 v[12:15], v[136:139], v[168:171], v[12:15]
	v_mfma_f32_16x16x32_bf16 v[8:11], v[140:143], v[168:171], v[8:11]
	v_mfma_f32_16x16x32_bf16 v[4:7], v[136:139], v[172:175], v[4:7]
	v_mfma_f32_16x16x32_bf16 v[0:3], v[140:143], v[172:175], v[0:3]
	s_barrier
	s_mov_b32 m0, s44
	s_add_u32 s96, s4, s28
	s_addc_u32 s97, s5, s29
	s_nop 0
	global_load_lds_dwordx4 v216, s[96:97]
	s_mov_b32 m0, s45
	s_nop 0
	s_add_u32 s96, s4, s30
	s_addc_u32 s97, s5, s31
	s_nop 0
	global_load_lds_dwordx4 v216, s[96:97]
	s_waitcnt vmcnt(6)
	s_barrier
	v_mfma_f32_16x16x32_bf16 v[32:35], v[176:179], v[144:147], v[32:35]
	v_mfma_f32_16x16x32_bf16 v[36:39], v[180:183], v[144:147], v[36:39]
	v_mfma_f32_16x16x32_bf16 v[40:43], v[176:179], v[148:151], v[40:43]
	v_mfma_f32_16x16x32_bf16 v[44:47], v[180:183], v[148:151], v[44:47]
	v_mfma_f32_16x16x32_bf16 v[48:51], v[176:179], v[160:163], v[48:51]
	v_mfma_f32_16x16x32_bf16 v[52:55], v[180:183], v[160:163], v[52:55]
	v_mfma_f32_16x16x32_bf16 v[56:59], v[176:179], v[164:167], v[56:59]
	v_mfma_f32_16x16x32_bf16 v[60:63], v[180:183], v[164:167], v[60:63]
	v_mfma_f32_16x16x32_bf16 v[32:35], v[184:187], v[152:155], v[32:35]
	v_mfma_f32_16x16x32_bf16 v[36:39], v[188:191], v[152:155], v[36:39]
	v_mfma_f32_16x16x32_bf16 v[40:43], v[184:187], v[156:159], v[40:43]
	v_mfma_f32_16x16x32_bf16 v[44:47], v[188:191], v[156:159], v[44:47]
	v_mfma_f32_16x16x32_bf16 v[48:51], v[184:187], v[168:171], v[48:51]
	v_mfma_f32_16x16x32_bf16 v[52:55], v[188:191], v[168:171], v[52:55]
	v_mfma_f32_16x16x32_bf16 v[56:59], v[184:187], v[172:175], v[56:59]
	v_mfma_f32_16x16x32_bf16 v[60:63], v[188:191], v[172:175], v[60:63]
	s_barrier
	ds_read_b128 v[128:131], v232
	ds_read_b128 v[132:135], v232 offset:2048
	ds_read_b128 v[136:139], v233
	ds_read_b128 v[140:143], v233 offset:2048
	s_mov_b32 m0, s60
	ds_read_b128 v[144:147], v226 offset:32768
	ds_read_b128 v[148:151], v226 offset:34816
	ds_read_b128 v[152:155], v227 offset:32768
	ds_read_b128 v[156:159], v227 offset:34816
	ds_read_b128 v[160:163], v226 offset:36864
	ds_read_b128 v[164:167], v226 offset:38912
	ds_read_b128 v[168:171], v227 offset:36864
	ds_read_b128 v[172:175], v227 offset:38912
	s_add_u32 s96, s52, s36
	s_addc_u32 s97, s53, s37
	s_nop 0
	global_load_lds_dwordx4 v216, s[96:97]
	s_mov_b32 m0, s61
	s_nop 0
	s_add_u32 s96, s52, s38
	s_addc_u32 s97, s53, s39
	s_nop 0
	global_load_lds_dwordx4 v216, s[96:97]
	s_waitcnt lgkmcnt(8)
	s_barrier
	s_waitcnt lgkmcnt(0)
	v_mfma_f32_16x16x32_bf16 v[124:127], v[128:131], v[144:147], v[124:127]
	v_mfma_f32_16x16x32_bf16 v[120:123], v[132:135], v[144:147], v[120:123]
	v_mfma_f32_16x16x32_bf16 v[116:119], v[128:131], v[148:151], v[116:119]
	v_mfma_f32_16x16x32_bf16 v[112:115], v[132:135], v[148:151], v[112:115]
	v_mfma_f32_16x16x32_bf16 v[108:111], v[128:131], v[160:163], v[108:111]
	v_mfma_f32_16x16x32_bf16 v[104:107], v[132:135], v[160:163], v[104:107]
	v_mfma_f32_16x16x32_bf16 v[100:103], v[128:131], v[164:167], v[100:103]
	v_mfma_f32_16x16x32_bf16 v[96:99], v[132:135], v[164:167], v[96:99]
	v_mfma_f32_16x16x32_bf16 v[124:127], v[136:139], v[152:155], v[124:127]
	v_mfma_f32_16x16x32_bf16 v[120:123], v[140:143], v[152:155], v[120:123]
	v_mfma_f32_16x16x32_bf16 v[116:119], v[136:139], v[156:159], v[116:119]
	v_mfma_f32_16x16x32_bf16 v[112:115], v[140:143], v[156:159], v[112:115]
	v_mfma_f32_16x16x32_bf16 v[108:111], v[136:139], v[168:171], v[108:111]
	v_mfma_f32_16x16x32_bf16 v[104:107], v[140:143], v[168:171], v[104:107]
	v_mfma_f32_16x16x32_bf16 v[100:103], v[136:139], v[172:175], v[100:103]
	v_mfma_f32_16x16x32_bf16 v[96:99], v[140:143], v[172:175], v[96:99]
	s_barrier
	s_mov_b32 m0, s62
	ds_read_b128 v[176:179], v234
	ds_read_b128 v[180:183], v234 offset:2048
	ds_read_b128 v[184:187], v235
	ds_read_b128 v[188:191], v235 offset:2048
	s_add_u32 s96, s58, s40
	s_addc_u32 s97, s59, s41
	s_nop 0
	global_load_lds_dwordx4 v216, s[96:97]
	s_mov_b32 m0, s63
	s_nop 0
	s_add_u32 s96, s58, s46
	s_addc_u32 s97, s59, s47
	s_nop 0
	global_load_lds_dwordx4 v216, s[96:97]
	s_waitcnt lgkmcnt(0)
	s_barrier
	v_mfma_f32_16x16x32_bf16 v[92:95], v[176:179], v[144:147], v[92:95]
	v_mfma_f32_16x16x32_bf16 v[88:91], v[180:183], v[144:147], v[88:91]
	v_mfma_f32_16x16x32_bf16 v[84:87], v[176:179], v[148:151], v[84:87]
	v_mfma_f32_16x16x32_bf16 v[80:83], v[180:183], v[148:151], v[80:83]
	v_mfma_f32_16x16x32_bf16 v[76:79], v[176:179], v[160:163], v[76:79]
	v_mfma_f32_16x16x32_bf16 v[72:75], v[180:183], v[160:163], v[72:75]
	v_mfma_f32_16x16x32_bf16 v[68:71], v[176:179], v[164:167], v[68:71]
	v_mfma_f32_16x16x32_bf16 v[64:67], v[180:183], v[164:167], v[64:67]
	v_mfma_f32_16x16x32_bf16 v[92:95], v[184:187], v[152:155], v[92:95]
	v_mfma_f32_16x16x32_bf16 v[88:91], v[188:191], v[152:155], v[88:91]
	v_mfma_f32_16x16x32_bf16 v[84:87], v[184:187], v[156:159], v[84:87]
	v_mfma_f32_16x16x32_bf16 v[80:83], v[188:191], v[156:159], v[80:83]
	v_mfma_f32_16x16x32_bf16 v[76:79], v[184:187], v[168:171], v[76:79]
	v_mfma_f32_16x16x32_bf16 v[72:75], v[188:191], v[168:171], v[72:75]
	v_mfma_f32_16x16x32_bf16 v[68:71], v[184:187], v[172:175], v[68:71]
	v_mfma_f32_16x16x32_bf16 v[64:67], v[188:191], v[172:175], v[64:67]
	s_barrier
	s_mov_b32 m0, s64
	ds_read_b128 v[144:147], v226 offset:49152
	ds_read_b128 v[148:151], v226 offset:51200
	ds_read_b128 v[152:155], v227 offset:49152
	ds_read_b128 v[156:159], v227 offset:51200
	ds_read_b128 v[160:163], v226 offset:53248
	ds_read_b128 v[164:167], v226 offset:55296
	ds_read_b128 v[168:171], v227 offset:53248
	ds_read_b128 v[172:175], v227 offset:55296
	s_add_u32 s96, s52, s40
	s_addc_u32 s97, s53, s41
	s_nop 0
	global_load_lds_dwordx4 v216, s[96:97]
	s_mov_b32 m0, s65
	s_nop 0
	s_add_u32 s96, s52, s46
	s_addc_u32 s97, s53, s47
	s_nop 0
	global_load_lds_dwordx4 v216, s[96:97]
	s_barrier
; template <int K, int EPI, bool MIX = false>
; __device__ __forceinline__ void gemm_phase(const Params& p, const u16* __restrict__ A, const u16* __restrict__ Bt,
;                            const float* __restrict__ rs_in, float* __restrict__ ssq_out, float alpha, bool rev = false) {
;     ...
;       for (int t = 0; t < nt - 2; t += 2) KBODY(t);
	s_waitcnt lgkmcnt(0)
	v_mfma_f32_16x16x32_bf16 v[28:31], v[128:131], v[144:147], v[28:31]
	v_mfma_f32_16x16x32_bf16 v[24:27], v[132:135], v[144:147], v[24:27]
	v_mfma_f32_16x16x32_bf16 v[20:23], v[128:131], v[148:151], v[20:23]
	v_mfma_f32_16x16x32_bf16 v[16:19], v[132:135], v[148:151], v[16:19]
	v_mfma_f32_16x16x32_bf16 v[12:15], v[128:131], v[160:163], v[12:15]
	v_mfma_f32_16x16x32_bf16 v[8:11], v[132:135], v[160:163], v[8:11]
	v_mfma_f32_16x16x32_bf16 v[4:7], v[128:131], v[164:167], v[4:7]
	v_mfma_f32_16x16x32_bf16 v[0:3], v[132:135], v[164:167], v[0:3]
	v_mfma_f32_16x16x32_bf16 v[28:31], v[136:139], v[152:155], v[28:31]
	v_mfma_f32_16x16x32_bf16 v[24:27], v[140:143], v[152:155], v[24:27]
	v_mfma_f32_16x16x32_bf16 v[20:23], v[136:139], v[156:159], v[20:23]
	v_mfma_f32_16x16x32_bf16 v[16:19], v[140:143], v[156:159], v[16:19]
	v_mfma_f32_16x16x32_bf16 v[12:15], v[136:139], v[168:171], v[12:15]
	v_mfma_f32_16x16x32_bf16 v[8:11], v[140:143], v[168:171], v[8:11]
	v_mfma_f32_16x16x32_bf16 v[4:7], v[136:139], v[172:175], v[4:7]
	v_mfma_f32_16x16x32_bf16 v[0:3], v[140:143], v[172:175], v[0:3]
	s_barrier
	s_mov_b32 m0, s68
	s_add_u32 s96, s4, s40
	s_addc_u32 s97, s5, s41
	s_nop 0
	global_load_lds_dwordx4 v216, s[96:97]
	s_mov_b32 m0, s69
	s_nop 0
	s_add_u32 s96, s4, s46
	s_addc_u32 s97, s5, s47
	s_nop 0
	global_load_lds_dwordx4 v216, s[96:97]
	s_waitcnt vmcnt(6)
	s_barrier
	v_mfma_f32_16x16x32_bf16 v[32:35], v[176:179], v[144:147], v[32:35]
	v_mfma_f32_16x16x32_bf16 v[36:39], v[180:183], v[144:147], v[36:39]
	v_mfma_f32_16x16x32_bf16 v[40:43], v[176:179], v[148:151], v[40:43]
	v_mfma_f32_16x16x32_bf16 v[44:47], v[180:183], v[148:151], v[44:47]
	v_mfma_f32_16x16x32_bf16 v[48:51], v[176:179], v[160:163], v[48:51]
	v_mfma_f32_16x16x32_bf16 v[52:55], v[180:183], v[160:163], v[52:55]
	v_mfma_f32_16x16x32_bf16 v[56:59], v[176:179], v[164:167], v[56:59]
	v_mfma_f32_16x16x32_bf16 v[60:63], v[180:183], v[164:167], v[60:63]
	v_mfma_f32_16x16x32_bf16 v[32:35], v[184:187], v[152:155], v[32:35]
	v_mfma_f32_16x16x32_bf16 v[36:39], v[188:191], v[152:155], v[36:39]
	v_mfma_f32_16x16x32_bf16 v[40:43], v[184:187], v[156:159], v[40:43]
	v_mfma_f32_16x16x32_bf16 v[44:47], v[188:191], v[156:159], v[44:47]
	v_mfma_f32_16x16x32_bf16 v[48:51], v[184:187], v[168:171], v[48:51]
	v_mfma_f32_16x16x32_bf16 v[52:55], v[188:191], v[168:171], v[52:55]
	v_mfma_f32_16x16x32_bf16 v[56:59], v[184:187], v[172:175], v[56:59]
	v_mfma_f32_16x16x32_bf16 v[60:63], v[188:191], v[172:175], v[60:63]
	s_barrier
	s_add_i32 s77, s77, 2
	s_add_u32 s58, s58, 0x100
	s_addc_u32 s59, s59, 0
	s_add_u32 s52, s52, 0x100
	s_addc_u32 s53, s53, 0
	s_add_u32 s4, s4, 0x100
	s_addc_u32 s5, s5, 0
	s_cmp_lt_u32 s77, 28
	s_cbranch_scc1 .LBB0_423
; #define LDA(dst,b,h) _Pragma("unroll") for(int m=0;m<4;++m) _Pragma("unroll") for(int k=0;k<2;++k) \
;     dst[m][k]=*reinterpret_cast<const bf16x8*>(SA(b,h)+(wr*64+m*16)*128+koff[k])
; #define LDB(dst,b,h) _Pragma("unroll") for(int n=0;n<2;++n) _Pragma("unroll") for(int k=0;k<2;++k) \
;     dst[n][k]=*reinterpret_cast<const bf16x8*>(SB(b,h)+(wc*32+n*16)*128+koff[k])
; #define MMA(ai,bj,Af,Bf) do{__builtin_amdgcn_s_setprio(1); \
;     _Pragma("unroll") for(int m=0;m<4;++m) _Pragma("unroll") for(int n=0;n<2;++n) _Pragma("unroll") for(int k=0;k<2;++k) \
;       acc[ai][bj][m][n]=__builtin_amdgcn_mfma_f32_16x16x32_bf16(Bf[n][k],Af[m][k],acc[ai][bj][m][n],0,0,0); \
;     __builtin_amdgcn_s_setprio(0);}while(0)
; #define WAIT_L(n) asm volatile("s_waitcnt lgkmcnt(" #n ")":::"memory")
; #define BAR __builtin_amdgcn_s_barrier()
; #define SCHED __builtin_amdgcn_sched_barrier(0)
; #define STAGE_A(b,h,kt) do{ unsigned char* _d = SA(b,h) + wbase; \
;     if constexpr (BLK) { const char* _s = baseA + ((size_t)(h)*(K/64) + (kt)) * 16384; GLDS(_s + voa, _d); GLDS(_s + 8192 + voa, _d + 8192); } \
;     else { const char* _s = baseA + ((size_t)(h)*128*K + (kt)*64) * 2; GLDS(_s + voa, _d); GLDS(_s + (size_t)128*K + voa, _d + 8192); } }while(0)
; template <int K, int EPI, bool MIX = false>
; __device__ __forceinline__ void gemm_phase(const Params& p, const u16* __restrict__ A, const u16* __restrict__ Bt,
;                            const float* __restrict__ rs_in, float* __restrict__ ssq_out, float alpha, bool rev = false) {
;     ...
;     if constexpr (EPI == EPI_SWIGLU || EPI == EPI_Z || MIX) {
;       const float* rsrc = MIX ? p.ssqb : rs_in;
;       int fr_p = fr;
;       asm volatile("" : "+v"(fr_p));
; #pragma unroll
;       for (int ai = 0; ai < 2; ++ai)
; #pragma unroll
;         for (int m = 0; m < 4; ++m) rsq[ai][m] = rsrc[cpm * 256 + ai * 128 + wr * 64 + m * 16 + fr_p];
;     }
;     ++it;
;     id = item_id(it);
;     const bool more = id < ntiles;
;     if (rev) id = ntiles - 1 - id;
;     {
;       LDB(B0,0,0); SCHED; LDA(At,0,0); STAGE_A(1,1,nt-1);
;       WAIT_L(8); BAR; WAIT_L(0); MMA(0,0,At,B0); BAR; SCHED;
;       if (more) SETUP_TILE();
;       LDB(B1,0,1); if (more) STAGE_B(0,0,0);
;       BAR; WAIT_L(0); MMA(0,1,At,B1); BAR;
;       LDA(At,0,1); if (more) STAGE_A(0,0,0);
	v_mov_b32_e32 v128, v223
	s_lshl_b32 s59, s34, 8
	s_add_i32 s59, s59, s70
	v_add_u32_e32 v128, s59, v128
	v_readlane_b32 s80, v254, 32
	v_ashrrev_i32_e32 v129, 31, v128
	v_readlane_b32 s94, v254, 46
	v_readlane_b32 s95, v254, 47
	s_add_i32 s75, s75, 1
	s_mul_i32 s4, s75, s57
	v_lshl_add_u64 v[128:129], v[128:129], 2, s[94:95]
	global_load_dword v214, v[128:129], off
	global_load_dword v243, v[128:129], off offset:64
	global_load_dword v242, v[128:129], off offset:128
	global_load_dword v241, v[128:129], off offset:192
	global_load_dword v240, v[128:129], off offset:512
	global_load_dword v239, v[128:129], off offset:576
	global_load_dword v238, v[128:129], off offset:640
	global_load_dword v237, v[128:129], off offset:704
	ds_read_b128 v[136:139], v224
	ds_read_b128 v[140:143], v224 offset:2048
	ds_read_b128 v[148:151], v225
	ds_read_b128 v[144:147], v225 offset:2048
	s_add_i32 s4, s4, s56
	v_readlane_b32 s81, v254, 33
	v_readlane_b32 s82, v254, 34
	v_readlane_b32 s83, v254, 35
	v_readlane_b32 s84, v254, 36
	v_readlane_b32 s85, v254, 37
	v_readlane_b32 s86, v254, 38
	v_readlane_b32 s87, v254, 39
	v_readlane_b32 s88, v254, 40
	v_readlane_b32 s89, v254, 41
	v_readlane_b32 s90, v254, 42
	v_readlane_b32 s91, v254, 43
	v_readlane_b32 s92, v254, 44
	v_readlane_b32 s93, v254, 45
	v_lshl_add_u64 v[128:129], s[0:1], 0, v[212:213]
	s_mov_b32 m0, s72
	v_lshl_add_u64 v[130:131], v[128:129], 0, s[48:49]
	ds_read_b128 v[152:155], v226
	ds_read_b128 v[156:159], v226 offset:2048
	ds_read_b128 v[180:183], v227
	ds_read_b128 v[172:175], v227 offset:2048
	ds_read_b128 v[160:163], v226 offset:4096
	ds_read_b128 v[164:167], v226 offset:6144
	ds_read_b128 v[176:179], v227 offset:4096
	ds_read_b128 v[168:171], v227 offset:6144
	global_load_lds_dwordx4 v[130:131], off
	v_lshl_add_u64 v[128:129], v[128:129], 0, s[50:51]
	s_mov_b32 m0, s73
	s_nop 0
	global_load_lds_dwordx4 v[128:129], off
	s_waitcnt lgkmcnt(8)
	s_barrier
	s_waitcnt lgkmcnt(0)
	v_mfma_f32_16x16x32_bf16 v[124:127], v[136:139], v[152:155], v[124:127]
	s_cmpk_lt_i32 s4, 0x2100
	s_cselect_b64 s[52:53], -1, 0
	s_cmpk_gt_i32 s4, 0x20ff
	v_mfma_f32_16x16x32_bf16 v[120:123], v[140:143], v[152:155], v[120:123]
	v_mfma_f32_16x16x32_bf16 v[116:119], v[136:139], v[156:159], v[116:119]
	v_mfma_f32_16x16x32_bf16 v[112:115], v[140:143], v[156:159], v[112:115]
	v_mfma_f32_16x16x32_bf16 v[108:111], v[136:139], v[160:163], v[108:111]
	v_mfma_f32_16x16x32_bf16 v[104:107], v[140:143], v[160:163], v[104:107]
	v_mfma_f32_16x16x32_bf16 v[100:103], v[136:139], v[164:167], v[100:103]
	v_mfma_f32_16x16x32_bf16 v[96:99], v[140:143], v[164:167], v[96:99]
	v_mfma_f32_16x16x32_bf16 v[124:127], v[148:151], v[180:183], v[124:127]
	v_mfma_f32_16x16x32_bf16 v[120:123], v[144:147], v[180:183], v[120:123]
	v_mfma_f32_16x16x32_bf16 v[116:119], v[148:151], v[172:175], v[116:119]
	v_mfma_f32_16x16x32_bf16 v[112:115], v[144:147], v[172:175], v[112:115]
	v_mfma_f32_16x16x32_bf16 v[108:111], v[148:151], v[176:179], v[108:111]
	v_mfma_f32_16x16x32_bf16 v[104:107], v[144:147], v[176:179], v[104:107]
	v_mfma_f32_16x16x32_bf16 v[128:131], v[148:151], v[168:171], v[100:103]
	v_mfma_f32_16x16x32_bf16 v[132:135], v[144:147], v[168:171], v[96:99]
	s_barrier
	s_mov_b32 s58, s76
	s_cbranch_scc1 .LBB0_426
	s_mul_hi_i32 s0, s4, 0x2e8ba2e9
	s_lshr_b32 s1, s0, 31
	s_ashr_i32 s0, s0, 6
	s_add_i32 s0, s0, s1
	s_lshl_b32 s1, s0, 3
	s_mulk_i32 s0, 0xfea0
	s_add_i32 s0, s0, s4
	s_and_b32 s4, s4, 7
	s_or_b32 s34, s1, s4
	s_ashr_i32 s58, s0, 3
	s_lshl_b32 s0, s34, 8
	v_readlane_b32 s80, v254, 0
	s_ashr_i32 s1, s0, 31
	v_readlane_b32 s86, v254, 6
	v_readlane_b32 s87, v254, 7
	s_lshl_b64 s[0:1], s[0:1], 12
	s_mov_b64 s[10:11], s[86:87]
	v_readlane_b32 s81, v254, 1
	v_readlane_b32 s82, v254, 2
	v_readlane_b32 s83, v254, 3
	v_readlane_b32 s84, v254, 4
	v_readlane_b32 s85, v254, 5
	s_add_u32 s0, s10, s0
	s_addc_u32 s1, s11, s1
	s_lshl_b32 s4, s58, 7
	v_readlane_b32 s80, v254, 32
	s_ashr_i32 s5, s4, 31
	v_readlane_b32 s82, v254, 34
	v_readlane_b32 s83, v254, 35
	s_lshl_b64 s[4:5], s[4:5], 12
	s_mov_b64 s[78:79], s[82:83]
	s_add_u32 s8, s78, s4
	s_addc_u32 s9, s79, s5
	s_add_u32 s10, s8, 0x1600000
	s_addc_u32 s11, s9, 0
	v_readlane_b32 s81, v254, 33
	v_readlane_b32 s84, v254, 36
	v_readlane_b32 s85, v254, 37
	v_readlane_b32 s86, v254, 38
	v_readlane_b32 s87, v254, 39
	v_readlane_b32 s88, v254, 40
	v_readlane_b32 s89, v254, 41
	v_readlane_b32 s90, v254, 42
	v_readlane_b32 s91, v254, 43
	v_readlane_b32 s92, v254, 44
	v_readlane_b32 s93, v254, 45
	v_readlane_b32 s94, v254, 46
	v_readlane_b32 s95, v254, 47

.Llate_p7_done:
.LBB0_463:
	ds_read_b128 v[128:131], v225
	ds_read_b128 v[132:135], v225 offset:2048
	ds_read_b128 v[136:139], v226
	ds_read_b128 v[140:143], v226 offset:2048
	s_mov_b32 m0, s64
	ds_read_b128 v[144:147], v227
	ds_read_b128 v[148:151], v227 offset:2048
	ds_read_b128 v[152:155], v228
	ds_read_b128 v[156:159], v228 offset:2048
	ds_read_b128 v[160:163], v227 offset:4096
	ds_read_b128 v[164:167], v227 offset:6144
	ds_read_b128 v[168:171], v228 offset:4096
	ds_read_b128 v[172:175], v228 offset:6144
	s_add_u32 s96, s50, s18
	s_addc_u32 s97, s51, s19
	s_nop 0
	global_load_lds_dwordx4 v218, s[96:97]
	s_mov_b32 m0, s65
	s_nop 0
	s_add_u32 s96, s50, s20
	s_addc_u32 s97, s51, s21
	s_nop 0
	global_load_lds_dwordx4 v218, s[96:97]
	s_waitcnt lgkmcnt(8)
	s_barrier
	s_waitcnt lgkmcnt(0)
	v_mfma_f32_16x16x32_bf16 v[124:127], v[128:131], v[144:147], v[124:127]
	v_mfma_f32_16x16x32_bf16 v[120:123], v[132:135], v[144:147], v[120:123]
	v_mfma_f32_16x16x32_bf16 v[116:119], v[128:131], v[148:151], v[116:119]
	v_mfma_f32_16x16x32_bf16 v[112:115], v[132:135], v[148:151], v[112:115]
	v_mfma_f32_16x16x32_bf16 v[108:111], v[128:131], v[160:163], v[108:111]
	v_mfma_f32_16x16x32_bf16 v[104:107], v[132:135], v[160:163], v[104:107]
	v_mfma_f32_16x16x32_bf16 v[100:103], v[128:131], v[164:167], v[100:103]
	v_mfma_f32_16x16x32_bf16 v[96:99], v[132:135], v[164:167], v[96:99]
	v_mfma_f32_16x16x32_bf16 v[124:127], v[136:139], v[152:155], v[124:127]
	v_mfma_f32_16x16x32_bf16 v[120:123], v[140:143], v[152:155], v[120:123]
	v_mfma_f32_16x16x32_bf16 v[116:119], v[136:139], v[156:159], v[116:119]
	v_mfma_f32_16x16x32_bf16 v[112:115], v[140:143], v[156:159], v[112:115]
	v_mfma_f32_16x16x32_bf16 v[108:111], v[136:139], v[168:171], v[108:111]
	v_mfma_f32_16x16x32_bf16 v[104:107], v[140:143], v[168:171], v[104:107]
	v_mfma_f32_16x16x32_bf16 v[100:103], v[136:139], v[172:175], v[100:103]
	v_mfma_f32_16x16x32_bf16 v[96:99], v[140:143], v[172:175], v[96:99]
	s_barrier
	s_mov_b32 m0, s34
	ds_read_b128 v[176:179], v229
	ds_read_b128 v[180:183], v229 offset:2048
	ds_read_b128 v[184:187], v232
	ds_read_b128 v[188:191], v232 offset:2048
	s_add_u32 s96, s52, s26
	s_addc_u32 s97, s53, s27
	s_nop 0
	global_load_lds_dwordx4 v218, s[96:97]
	s_mov_b32 m0, s35
	s_nop 0
	s_add_u32 s96, s52, s28
	s_addc_u32 s97, s53, s29
	s_nop 0
	global_load_lds_dwordx4 v218, s[96:97]
	s_waitcnt lgkmcnt(0)
	s_barrier
	v_mfma_f32_16x16x32_bf16 v[92:95], v[176:179], v[144:147], v[92:95]
	v_mfma_f32_16x16x32_bf16 v[88:91], v[180:183], v[144:147], v[88:91]
	v_mfma_f32_16x16x32_bf16 v[84:87], v[176:179], v[148:151], v[84:87]
	v_mfma_f32_16x16x32_bf16 v[80:83], v[180:183], v[148:151], v[80:83]
	v_mfma_f32_16x16x32_bf16 v[76:79], v[176:179], v[160:163], v[76:79]
	v_mfma_f32_16x16x32_bf16 v[72:75], v[180:183], v[160:163], v[72:75]
	v_mfma_f32_16x16x32_bf16 v[68:71], v[176:179], v[164:167], v[68:71]
	v_mfma_f32_16x16x32_bf16 v[64:67], v[180:183], v[164:167], v[64:67]
	v_mfma_f32_16x16x32_bf16 v[92:95], v[184:187], v[152:155], v[92:95]
	v_mfma_f32_16x16x32_bf16 v[88:91], v[188:191], v[152:155], v[88:91]
	v_mfma_f32_16x16x32_bf16 v[84:87], v[184:187], v[156:159], v[84:87]
	v_mfma_f32_16x16x32_bf16 v[80:83], v[188:191], v[156:159], v[80:83]
	v_mfma_f32_16x16x32_bf16 v[76:79], v[184:187], v[168:171], v[76:79]
	v_mfma_f32_16x16x32_bf16 v[72:75], v[188:191], v[168:171], v[72:75]
	v_mfma_f32_16x16x32_bf16 v[68:71], v[184:187], v[172:175], v[68:71]
	v_mfma_f32_16x16x32_bf16 v[64:67], v[188:191], v[172:175], v[64:67]
	s_barrier
	s_mov_b32 m0, s33
	ds_read_b128 v[144:147], v227 offset:16384
	ds_read_b128 v[148:151], v227 offset:18432
	ds_read_b128 v[152:155], v228 offset:16384
	ds_read_b128 v[156:159], v228 offset:18432
	ds_read_b128 v[160:163], v227 offset:20480
	ds_read_b128 v[164:167], v227 offset:22528
	ds_read_b128 v[168:171], v228 offset:20480
	ds_read_b128 v[172:175], v228 offset:22528
	s_add_u32 s96, s50, s26
	s_addc_u32 s97, s51, s27
	s_nop 0
	global_load_lds_dwordx4 v218, s[96:97]
	s_mov_b32 m0, s42
	s_nop 0
	s_add_u32 s96, s50, s28
	s_addc_u32 s97, s51, s29
	s_nop 0
	global_load_lds_dwordx4 v218, s[96:97]
	s_barrier
	s_waitcnt lgkmcnt(0)
	v_mfma_f32_16x16x32_bf16 v[60:63], v[128:131], v[144:147], v[60:63]
	v_mfma_f32_16x16x32_bf16 v[56:59], v[132:135], v[144:147], v[56:59]
	v_mfma_f32_16x16x32_bf16 v[52:55], v[128:131], v[148:151], v[52:55]
	v_mfma_f32_16x16x32_bf16 v[48:51], v[132:135], v[148:151], v[48:51]
	v_mfma_f32_16x16x32_bf16 v[44:47], v[128:131], v[160:163], v[44:47]
	v_mfma_f32_16x16x32_bf16 v[40:43], v[132:135], v[160:163], v[40:43]
	v_mfma_f32_16x16x32_bf16 v[36:39], v[128:131], v[164:167], v[36:39]
	v_mfma_f32_16x16x32_bf16 v[32:35], v[132:135], v[164:167], v[32:35]
	v_mfma_f32_16x16x32_bf16 v[60:63], v[136:139], v[152:155], v[60:63]
	v_mfma_f32_16x16x32_bf16 v[56:59], v[140:143], v[152:155], v[56:59]
	v_mfma_f32_16x16x32_bf16 v[52:55], v[136:139], v[156:159], v[52:55]
	v_mfma_f32_16x16x32_bf16 v[48:51], v[140:143], v[156:159], v[48:51]
	v_mfma_f32_16x16x32_bf16 v[44:47], v[136:139], v[168:171], v[44:47]
	v_mfma_f32_16x16x32_bf16 v[40:43], v[140:143], v[168:171], v[40:43]
	v_mfma_f32_16x16x32_bf16 v[36:39], v[136:139], v[172:175], v[36:39]
	v_mfma_f32_16x16x32_bf16 v[32:35], v[140:143], v[172:175], v[32:35]
	s_barrier
	s_mov_b32 m0, s43
	s_add_u32 s96, s2, s26
	s_addc_u32 s97, s3, s27
	s_nop 0
	global_load_lds_dwordx4 v218, s[96:97]
	s_mov_b32 m0, s44
	s_nop 0
	s_add_u32 s96, s2, s28
	s_addc_u32 s97, s3, s29
	s_nop 0
	global_load_lds_dwordx4 v218, s[96:97]
	s_waitcnt vmcnt(6)
	s_barrier
	v_mfma_f32_16x16x32_bf16 v[28:31], v[176:179], v[144:147], v[28:31]
	v_mfma_f32_16x16x32_bf16 v[24:27], v[180:183], v[144:147], v[24:27]
	v_mfma_f32_16x16x32_bf16 v[20:23], v[176:179], v[148:151], v[20:23]
	v_mfma_f32_16x16x32_bf16 v[16:19], v[180:183], v[148:151], v[16:19]
	v_mfma_f32_16x16x32_bf16 v[12:15], v[176:179], v[160:163], v[12:15]
	v_mfma_f32_16x16x32_bf16 v[8:11], v[180:183], v[160:163], v[8:11]
	v_mfma_f32_16x16x32_bf16 v[4:7], v[176:179], v[164:167], v[4:7]
	v_mfma_f32_16x16x32_bf16 v[0:3], v[180:183], v[164:167], v[0:3]
	v_mfma_f32_16x16x32_bf16 v[28:31], v[184:187], v[152:155], v[28:31]
	v_mfma_f32_16x16x32_bf16 v[24:27], v[188:191], v[152:155], v[24:27]
	v_mfma_f32_16x16x32_bf16 v[20:23], v[184:187], v[156:159], v[20:23]
	v_mfma_f32_16x16x32_bf16 v[16:19], v[188:191], v[156:159], v[16:19]
	v_mfma_f32_16x16x32_bf16 v[12:15], v[184:187], v[168:171], v[12:15]
	v_mfma_f32_16x16x32_bf16 v[8:11], v[188:191], v[168:171], v[8:11]
	v_mfma_f32_16x16x32_bf16 v[4:7], v[184:187], v[172:175], v[4:7]
	v_mfma_f32_16x16x32_bf16 v[0:3], v[188:191], v[172:175], v[0:3]
	s_barrier
	ds_read_b128 v[128:131], v233
	ds_read_b128 v[132:135], v233 offset:2048
	ds_read_b128 v[136:139], v234
	ds_read_b128 v[140:143], v234 offset:2048
	s_mov_b32 m0, s45
	ds_read_b128 v[144:147], v227 offset:32768
	ds_read_b128 v[148:151], v227 offset:34816
	ds_read_b128 v[152:155], v228 offset:32768
	ds_read_b128 v[156:159], v228 offset:34816
	ds_read_b128 v[160:163], v227 offset:36864
	ds_read_b128 v[164:167], v227 offset:38912
	ds_read_b128 v[168:171], v228 offset:36864
	ds_read_b128 v[172:175], v228 offset:38912
	s_add_u32 s96, s50, s30
	s_addc_u32 s97, s51, s31
	s_nop 0
	global_load_lds_dwordx4 v218, s[96:97]
	s_mov_b32 m0, s54
	s_nop 0
	s_add_u32 s96, s50, s36
	s_addc_u32 s97, s51, s37
	s_nop 0
	global_load_lds_dwordx4 v218, s[96:97]
	s_waitcnt lgkmcnt(8)
	s_barrier
	s_waitcnt lgkmcnt(0)
	v_mfma_f32_16x16x32_bf16 v[124:127], v[128:131], v[144:147], v[124:127]
	v_mfma_f32_16x16x32_bf16 v[120:123], v[132:135], v[144:147], v[120:123]
	v_mfma_f32_16x16x32_bf16 v[116:119], v[128:131], v[148:151], v[116:119]
	v_mfma_f32_16x16x32_bf16 v[112:115], v[132:135], v[148:151], v[112:115]
	v_mfma_f32_16x16x32_bf16 v[108:111], v[128:131], v[160:163], v[108:111]
	v_mfma_f32_16x16x32_bf16 v[104:107], v[132:135], v[160:163], v[104:107]
	v_mfma_f32_16x16x32_bf16 v[100:103], v[128:131], v[164:167], v[100:103]
	v_mfma_f32_16x16x32_bf16 v[96:99], v[132:135], v[164:167], v[96:99]
	v_mfma_f32_16x16x32_bf16 v[124:127], v[136:139], v[152:155], v[124:127]
	v_mfma_f32_16x16x32_bf16 v[120:123], v[140:143], v[152:155], v[120:123]
	v_mfma_f32_16x16x32_bf16 v[116:119], v[136:139], v[156:159], v[116:119]
	v_mfma_f32_16x16x32_bf16 v[112:115], v[140:143], v[156:159], v[112:115]
	v_mfma_f32_16x16x32_bf16 v[108:111], v[136:139], v[168:171], v[108:111]
	v_mfma_f32_16x16x32_bf16 v[104:107], v[140:143], v[168:171], v[104:107]
	v_mfma_f32_16x16x32_bf16 v[100:103], v[136:139], v[172:175], v[100:103]
	v_mfma_f32_16x16x32_bf16 v[96:99], v[140:143], v[172:175], v[96:99]
	s_barrier
	s_mov_b32 m0, s55
	ds_read_b128 v[176:179], v235
	ds_read_b128 v[180:183], v235 offset:2048
	ds_read_b128 v[184:187], v236
	ds_read_b128 v[188:191], v236 offset:2048
	s_add_u32 s96, s52, s38
	s_addc_u32 s97, s53, s39
	s_nop 0
	global_load_lds_dwordx4 v218, s[96:97]
	s_mov_b32 m0, s58
	s_nop 0
	s_add_u32 s96, s52, s40
	s_addc_u32 s97, s53, s41
	s_nop 0
	global_load_lds_dwordx4 v218, s[96:97]
	s_waitcnt lgkmcnt(0)
	s_barrier
	v_mfma_f32_16x16x32_bf16 v[92:95], v[176:179], v[144:147], v[92:95]
	v_mfma_f32_16x16x32_bf16 v[88:91], v[180:183], v[144:147], v[88:91]
	v_mfma_f32_16x16x32_bf16 v[84:87], v[176:179], v[148:151], v[84:87]
	v_mfma_f32_16x16x32_bf16 v[80:83], v[180:183], v[148:151], v[80:83]
	v_mfma_f32_16x16x32_bf16 v[76:79], v[176:179], v[160:163], v[76:79]
	v_mfma_f32_16x16x32_bf16 v[72:75], v[180:183], v[160:163], v[72:75]
	v_mfma_f32_16x16x32_bf16 v[68:71], v[176:179], v[164:167], v[68:71]
	v_mfma_f32_16x16x32_bf16 v[64:67], v[180:183], v[164:167], v[64:67]
	v_mfma_f32_16x16x32_bf16 v[92:95], v[184:187], v[152:155], v[92:95]
	v_mfma_f32_16x16x32_bf16 v[88:91], v[188:191], v[152:155], v[88:91]
	v_mfma_f32_16x16x32_bf16 v[84:87], v[184:187], v[156:159], v[84:87]
	v_mfma_f32_16x16x32_bf16 v[80:83], v[188:191], v[156:159], v[80:83]
	v_mfma_f32_16x16x32_bf16 v[76:79], v[184:187], v[168:171], v[76:79]
	v_mfma_f32_16x16x32_bf16 v[72:75], v[188:191], v[168:171], v[72:75]
	v_mfma_f32_16x16x32_bf16 v[68:71], v[184:187], v[172:175], v[68:71]
	v_mfma_f32_16x16x32_bf16 v[64:67], v[188:191], v[172:175], v[64:67]
	s_barrier
	s_mov_b32 m0, s59
	ds_read_b128 v[144:147], v227 offset:49152
	ds_read_b128 v[148:151], v227 offset:51200
	ds_read_b128 v[152:155], v228 offset:49152
	ds_read_b128 v[156:159], v228 offset:51200
	ds_read_b128 v[160:163], v227 offset:53248
	ds_read_b128 v[164:167], v227 offset:55296
	ds_read_b128 v[168:171], v228 offset:53248
	ds_read_b128 v[172:175], v228 offset:55296
	s_add_u32 s96, s50, s38
	s_addc_u32 s97, s51, s39
	s_nop 0
	global_load_lds_dwordx4 v218, s[96:97]
	s_mov_b32 m0, s60
	s_nop 0
	s_add_u32 s96, s50, s40
	s_addc_u32 s97, s51, s41
	s_nop 0
	global_load_lds_dwordx4 v218, s[96:97]
	s_barrier
; #define LDA(dst,b,h) _Pragma("unroll") for(int m=0;m<4;++m) _Pragma("unroll") for(int k=0;k<2;++k) \
;     dst[m][k]=*reinterpret_cast<const bf16x8*>(SA(b,h)+(wr*64+m*16)*128+koff[k])
; #define LDB(dst,b,h) _Pragma("unroll") for(int n=0;n<2;++n) _Pragma("unroll") for(int k=0;k<2;++k) \
;     dst[n][k]=*reinterpret_cast<const bf16x8*>(SB(b,h)+(wc*32+n*16)*128+koff[k])
; template <int K, int EPI, bool MIX = false>
; __device__ __forceinline__ void gemm_phase(const Params& p, const u16* __restrict__ A, const u16* __restrict__ Bt,
;                            const float* __restrict__ rs_in, float* __restrict__ ssq_out, float alpha, bool rev = false) {
;     ...
;     if constexpr (MIX) {
;       for (int t = 0; t < nt / 2; t += 2) KBODY(t);
;       {
;           int fr_m = fr;
;           asm volatile("" : "+v"(fr_m));
; #pragma unroll
;           for (int ai = 0; ai < 2; ++ai)
; #pragma unroll
;             for (int m = 0; m < 4; ++m) {
;               const int row = pm * 256 + ai * 128 + wr * 64 + m * 16 + fr_m;
;               const float ra = rsqrtf(p.ssqa[row] * (1.f / 1024.f) + 1e-6f);
;               const float rb = rsqrtf(p.ssqb[row] * (1.f / 1024.f) + 1e-6f);
;               const float f = ra * __builtin_amdgcn_rcpf(rb);
; #pragma unroll
;               for (int bj = 0; bj < 2; ++bj)
; #pragma unroll
;                 for (int n = 0; n < 2; ++n) acc[ai][bj][m][n] *= f;
;             }
;       }
;       for (int t = nt / 2; t < nt - 2; t += 2) KBODY(t);
;     } else {
;       for (int t = 0; t < nt - 2; t += 2) KBODY(t);
;     }
;     ...
;     const int cpm = pm, cpn = pn;
;     float rsq[2][4];
;     if constexpr (EPI == EPI_SWIGLU || EPI == EPI_Z || MIX) {
;       const float* rsrc = MIX ? p.ssqb : rs_in;
;       int fr_p = fr;
;       asm volatile("" : "+v"(fr_p));
; #pragma unroll
;       for (int ai = 0; ai < 2; ++ai)
; #pragma unroll
;         for (int m = 0; m < 4; ++m) rsq[ai][m] = rsrc[cpm * 256 + ai * 128 + wr * 64 + m * 16 + fr_p];
;     }
;     ++it;
;     id = item_id(it);
;     const bool more = id < ntiles;
;     if (rev) id = ntiles - 1 - id;
;     {
;       LDB(B0,0,0); SCHED; LDA(At,0,0); STAGE_A(1,1,nt-1);
;       WAIT_L(8); BAR; WAIT_L(0); MMA(0,0,At,B0); BAR; SCHED;
;       if (more) SETUP_TILE();
;       LDB(B1,0,1); if (more) STAGE_B(0,0,0);
;       BAR; WAIT_L(0); MMA(0,1,At,B1); BAR;
;       LDA(At,0,1); if (more) STAGE_A(0,0,0);
	s_waitcnt lgkmcnt(0)
	v_mfma_f32_16x16x32_bf16 v[60:63], v[128:131], v[144:147], v[60:63]
	v_mfma_f32_16x16x32_bf16 v[56:59], v[132:135], v[144:147], v[56:59]
	v_mfma_f32_16x16x32_bf16 v[52:55], v[128:131], v[148:151], v[52:55]
	v_mfma_f32_16x16x32_bf16 v[48:51], v[132:135], v[148:151], v[48:51]
	v_mfma_f32_16x16x32_bf16 v[44:47], v[128:131], v[160:163], v[44:47]
	v_mfma_f32_16x16x32_bf16 v[40:43], v[132:135], v[160:163], v[40:43]
	v_mfma_f32_16x16x32_bf16 v[36:39], v[128:131], v[164:167], v[36:39]
	v_mfma_f32_16x16x32_bf16 v[32:35], v[132:135], v[164:167], v[32:35]
	v_mfma_f32_16x16x32_bf16 v[60:63], v[136:139], v[152:155], v[60:63]
	v_mfma_f32_16x16x32_bf16 v[56:59], v[140:143], v[152:155], v[56:59]
	v_mfma_f32_16x16x32_bf16 v[52:55], v[136:139], v[156:159], v[52:55]
	v_mfma_f32_16x16x32_bf16 v[48:51], v[140:143], v[156:159], v[48:51]
	v_mfma_f32_16x16x32_bf16 v[44:47], v[136:139], v[168:171], v[44:47]
	v_mfma_f32_16x16x32_bf16 v[40:43], v[140:143], v[168:171], v[40:43]
	v_mfma_f32_16x16x32_bf16 v[36:39], v[136:139], v[172:175], v[36:39]
	v_mfma_f32_16x16x32_bf16 v[32:35], v[140:143], v[172:175], v[32:35]
	s_barrier
	s_mov_b32 m0, s61
	s_add_u32 s96, s2, s38
	s_addc_u32 s97, s3, s39
	s_nop 0
	global_load_lds_dwordx4 v218, s[96:97]
	s_mov_b32 m0, s62
	s_nop 0
	s_add_u32 s96, s2, s40
	s_addc_u32 s97, s3, s41
	s_nop 0
	global_load_lds_dwordx4 v218, s[96:97]
	s_waitcnt vmcnt(6)
	s_barrier
	v_mfma_f32_16x16x32_bf16 v[28:31], v[176:179], v[144:147], v[28:31]
	v_mfma_f32_16x16x32_bf16 v[24:27], v[180:183], v[144:147], v[24:27]
	v_mfma_f32_16x16x32_bf16 v[20:23], v[176:179], v[148:151], v[20:23]
	v_mfma_f32_16x16x32_bf16 v[16:19], v[180:183], v[148:151], v[16:19]
	v_mfma_f32_16x16x32_bf16 v[12:15], v[176:179], v[160:163], v[12:15]
	v_mfma_f32_16x16x32_bf16 v[8:11], v[180:183], v[160:163], v[8:11]
	v_mfma_f32_16x16x32_bf16 v[4:7], v[176:179], v[164:167], v[4:7]
	v_mfma_f32_16x16x32_bf16 v[0:3], v[180:183], v[164:167], v[0:3]
	v_mfma_f32_16x16x32_bf16 v[28:31], v[184:187], v[152:155], v[28:31]
	v_mfma_f32_16x16x32_bf16 v[24:27], v[188:191], v[152:155], v[24:27]
	v_mfma_f32_16x16x32_bf16 v[20:23], v[184:187], v[156:159], v[20:23]
	v_mfma_f32_16x16x32_bf16 v[16:19], v[188:191], v[156:159], v[16:19]
	v_mfma_f32_16x16x32_bf16 v[12:15], v[184:187], v[168:171], v[12:15]
	v_mfma_f32_16x16x32_bf16 v[8:11], v[188:191], v[168:171], v[8:11]
	v_mfma_f32_16x16x32_bf16 v[4:7], v[184:187], v[172:175], v[4:7]
	v_mfma_f32_16x16x32_bf16 v[0:3], v[188:191], v[172:175], v[0:3]
	s_barrier
	s_add_i32 s67, s67, 2
	s_add_u32 s52, s52, 0x8000
	s_addc_u32 s53, s53, 0
	s_add_u32 s50, s50, 0x8000
	s_addc_u32 s51, s51, 0
	s_add_u32 s2, s2, 0x8000
	s_addc_u32 s3, s3, 0
	s_cmpk_lt_u32 s67, 0x54
	s_cbranch_scc1 .LBB0_463
	ds_read_b128 v[144:147], v225
	ds_read_b128 v[148:151], v225 offset:2048
	ds_read_b128 v[156:159], v226
	ds_read_b128 v[152:155], v226 offset:2048
	s_add_i32 s66, s66, 1
	s_mul_i32 s2, s66, s76
	s_add_i32 s2, s2, s77
	s_cmpk_lt_i32 s2, 0x600
	s_cselect_b64 s[50:51], -1, 0
	s_cmpk_gt_i32 s2, 0x5ff
	v_lshl_add_u64 v[128:129], s[4:5], 0, v[216:217]
	s_mov_b32 m0, s64
	v_lshl_add_u64 v[130:131], v[128:129], 0, s[46:47]
	ds_read_b128 v[160:163], v227
	ds_read_b128 v[164:167], v227 offset:2048
	ds_read_b128 v[188:191], v228
	ds_read_b128 v[180:183], v228 offset:2048
	ds_read_b128 v[168:171], v227 offset:4096
	ds_read_b128 v[172:175], v227 offset:6144
	ds_read_b128 v[184:187], v228 offset:4096
	ds_read_b128 v[176:179], v228 offset:6144
	global_load_lds_dwordx4 v[130:131], off
	v_lshl_add_u64 v[128:129], v[128:129], 0, s[48:49]
	s_mov_b32 m0, s65
	s_nop 0
	global_load_lds_dwordx4 v[128:129], off
	s_waitcnt lgkmcnt(8)
	s_barrier
	s_waitcnt lgkmcnt(0)
	v_mfma_f32_16x16x32_bf16 v[124:127], v[144:147], v[160:163], v[124:127]
	v_mfma_f32_16x16x32_bf16 v[120:123], v[148:151], v[160:163], v[120:123]
	v_mfma_f32_16x16x32_bf16 v[116:119], v[144:147], v[164:167], v[116:119]
	v_mfma_f32_16x16x32_bf16 v[112:115], v[148:151], v[164:167], v[112:115]
	v_mfma_f32_16x16x32_bf16 v[108:111], v[144:147], v[168:171], v[108:111]
	v_mfma_f32_16x16x32_bf16 v[104:107], v[148:151], v[168:171], v[104:107]
	v_mfma_f32_16x16x32_bf16 v[100:103], v[144:147], v[172:175], v[100:103]
	v_mfma_f32_16x16x32_bf16 v[96:99], v[148:151], v[172:175], v[96:99]
	v_mfma_f32_16x16x32_bf16 v[124:127], v[156:159], v[188:191], v[124:127]
	v_mfma_f32_16x16x32_bf16 v[120:123], v[152:155], v[188:191], v[120:123]
	v_mfma_f32_16x16x32_bf16 v[128:131], v[156:159], v[180:183], v[116:119]
	v_mfma_f32_16x16x32_bf16 v[132:135], v[152:155], v[180:183], v[112:115]
	v_mfma_f32_16x16x32_bf16 v[108:111], v[156:159], v[184:187], v[108:111]
	v_mfma_f32_16x16x32_bf16 v[104:107], v[152:155], v[184:187], v[104:107]
	v_mfma_f32_16x16x32_bf16 v[136:139], v[156:159], v[176:179], v[100:103]
	v_mfma_f32_16x16x32_bf16 v[140:143], v[152:155], v[176:179], v[96:99]
	s_barrier
	s_mov_b32 s67, s69
	s_mov_b32 s68, s70
	s_cbranch_scc1 .LBB0_466
	s_sub_i32 s2, 0x5ff, s2
	s_lshr_b32 s3, s2, 3
	s_and_b32 s3, s3, 0x1ffffff8
	s_lshl_b32 s4, s3, 3
	s_sub_i32 s4, s2, s4
	s_and_b32 s2, s2, 7
	s_or_b32 s68, s3, s2
	s_ashr_i32 s67, s4, 3
	s_lshl_b32 s2, s68, 1
	s_mul_i32 s3, s68, 0x2c0000
	v_readlane_b32 s76, v254, 32
	s_mul_hi_u32 s2, s2, 0x160000
	s_add_u32 s4, s92, s3
	v_readlane_b32 s80, v254, 36
	v_readlane_b32 s81, v254, 37
	s_addc_u32 s5, s93, s2
	s_lshl_b32 s2, s67, 1
	s_mul_i32 s3, s67, 0x2c0000
	s_mov_b64 s[8:9], s[80:81]
	s_mul_hi_i32 s2, s2, 0x160000
	s_add_u32 s8, s8, s3
	v_readlane_b32 s84, v254, 40
	v_readlane_b32 s85, v254, 41
	v_readlane_b32 s86, v254, 42
	v_readlane_b32 s87, v254, 43
	v_readlane_b32 s88, v254, 44
	v_readlane_b32 s89, v254, 45
	v_readlane_b32 s90, v254, 46
	v_readlane_b32 s91, v254, 47
	s_addc_u32 s9, s9, s2
	v_readlane_b32 s77, v254, 33
	v_readlane_b32 s84, v254, 0
	s_add_u32 s10, s8, 0x160000
	s_mov_b32 s76, s57
	s_mov_b32 s77, s56
	v_readlane_b32 s85, v254, 1
	v_readlane_b32 s90, v254, 6
	v_readlane_b32 s91, v254, 7
	s_addc_u32 s11, s9, 0
	v_readlane_b32 s78, v254, 34
	v_readlane_b32 s79, v254, 35
	v_readlane_b32 s82, v254, 38
	v_readlane_b32 s83, v254, 39
	v_readlane_b32 s86, v254, 2
	v_readlane_b32 s87, v254, 3
	v_readlane_b32 s88, v254, 4
	v_readlane_b32 s89, v254, 5
